# GEMM main loops: one static s_setprio 1 for waves 4-7 in front of each loop, hipcc's per-cluster priority flips removed (timing-only)
# speedup vs baseline: 1.0060x; 1.0060x over previous
; __device__ __forceinline__ int otid_full() { int t = threadIdx.x; asm volatile("" : "+v"(t)); return t; }
; #define G8_STAGE(bufoff, gbase, voff) do { _Pragma("unroll") for (int _i = 0; _i < 2; ++_i) \
;     __builtin_amdgcn_global_load_lds((const unsigned*)((const char*)(gbase) + (voff)[_i]), (G8_LAS unsigned*)(lds + (bufoff) + ldsw + _i * 8192), 16, 0, 0); } while (0)
; #define G8_WAIT_V(n) asm volatile("s_waitcnt vmcnt(" #n ")" ::: "memory")
; #define G8_BAR __builtin_amdgcn_s_barrier()
; __device__ __forceinline__ void gemm256(const bf* __restrict__ A, int lda, const bf* __restrict__ Bt, int ldb, int K,
;                                         int brow, int bcol, f32x4 (&acc)[2][2][4][2]) {
;     ...
;   const int tid = otid_full(), wid = __builtin_amdgcn_readfirstlane(tid >> 6), lane = tid & 63, wr = wid >> 2, wc = wid & 3, fr = lane & 15, fq = lane >> 4;
;   unsigned voffA[2], voffB[2];
; #pragma unroll
;   for (int i = 0; i < 2; ++i) { int R, C; g8_stage_rc(tid * 16 + i * 8192, R, C); voffA[i] = (unsigned)(R * lda + C) * 2u; voffB[i] = (unsigned)(R * ldb + C) * 2u; }
;   const size_t kstep = 128;
;   const size_t hstepA = (size_t)128 * lda * 2, hstepB = (size_t)128 * ldb * 2;
;   const unsigned ldsw = (unsigned)wid * 1024u;
;   const int aoff = g8_lds_byte(wr * 64 + fr, fq * 8), boff = g8_lds_byte(wc * 32 + fr, fq * 8);
;   const char* cA = (const char*)A + (size_t)brow * lda * 2; const char* cB = (const char*)Bt + (size_t)bcol * ldb * 2;
;   bf16x8 At[4][2], B0[2][2], B1[2][2];
;   const int nt = K / 64;
;   __syncthreads();
;   G8_STAGE(G8_OSB(0, 0), cB, voffB); G8_STAGE(G8_OSA(0, 0), cA, voffA); G8_STAGE(G8_OSB(0, 1), cB + hstepB, voffB); G8_STAGE(G8_OSA(0, 1), cA + hstepA, voffA);
;   if (wr == 1) G8_BAR;
;   G8_WAIT_V(4); G8_BAR;
;   G8_STAGE(G8_OSB(1, 0), cB + kstep, voffB); G8_STAGE(G8_OSA(1, 0), cA + kstep, voffA); G8_STAGE(G8_OSB(1, 1), cB + hstepB + kstep, voffB);
;   G8_WAIT_V(6); G8_BAR;
.LBB0_204:
	v_and_b32_e32 v16, 15, v15
	v_and_b32_e32 v17, 48, v15
	v_lshlrev_b32_e32 v15, 2, v15
	v_lshlrev_b32_e32 v16, 6, v16
	v_and_b32_e32 v15, 32, v15
	s_lshl_b32 s18, s18, 12
	v_or_b32_e32 v18, v16, v17
	v_bitop3_b32 v16, v16, v15, v17 bitop3:0x36
	s_lshl_b32 s17, s17, 13
	s_and_b32 s18, s18, 0x3000
	v_or_b32_e32 v139, s18, v16
	v_bitop3_b32 v15, v18, s17, v15 bitop3:0xde
	s_lshr_b32 s18, s37, 2
	s_mov_b32 s19, s69
	s_lshl_b32 s17, s36, 12
	s_add_i32 m0, s8, 0x18000
	v_lshl_add_u64 v[8:9], v[8:9], 0, s[50:51]
	s_and_b32 s22, s38, 0x100000
	s_lshl_b64 s[20:21], s[18:19], 21
	s_and_b32 s19, s17, 0x100000
	s_waitcnt vmcnt(4)
	s_barrier
	global_load_lds_dwordx4 v[8:9], off
	v_lshl_add_u64 v[6:7], v[6:7], 0, s[50:51]
	s_add_i32 m0, s8, 0x1a000
	s_add_i32 s17, s8, 0x8000
	s_add_i32 s18, s8, 0xa000
	global_load_lds_dwordx4 v[6:7], off
	v_lshl_add_u64 v[4:5], v[4:5], 0, s[50:51]
	s_mov_b32 m0, s17
	s_add_u32 s2, s2, 0x80080
	global_load_lds_dwordx4 v[4:5], off
	v_lshl_add_u64 v[2:3], v[2:3], 0, s[50:51]
	s_mov_b32 m0, s18
	s_addc_u32 s3, s3, 0
	global_load_lds_dwordx4 v[2:3], off
	s_add_i32 m0, s8, 0x1c000
	v_lshl_add_u64 v[2:3], s[2:3], 0, v[144:145]
	global_load_lds_dwordx4 v[2:3], off
	v_lshl_add_u64 v[2:3], s[2:3], 0, v[154:155]
	s_add_i32 m0, s8, 0x1e000
	v_lshlrev_b32_e32 v4, 15, v1
	global_load_lds_dwordx4 v[2:3], off
	v_lshlrev_b32_e32 v2, 15, v10
	v_and_b32_e32 v2, 0xffff0000, v2
	v_readlane_b32 s52, v253, 3
	v_and_b32_e32 v4, 0xffff0000, v4
	v_lshl_add_u32 v2, v13, 12, v2
	v_and_b32_e32 v3, 1, v10
	v_readlane_b32 s58, v253, 9
	v_lshl_add_u32 v4, v11, 12, v4
	v_and_b32_e32 v1, 1, v1
	v_lshl_or_b32 v2, v3, 6, v2
	v_readlane_b32 s59, v253, 10
	s_add_u32 s2, s58, s22
	v_lshl_or_b32 v1, v1, 6, v4
	v_lshl_add_u32 v2, v14, 1, v2
	v_mov_b32_e32 v3, v145
	s_addc_u32 s3, s59, 0
	v_lshl_add_u32 v4, v12, 1, v1
	v_mov_b32_e32 v5, v145
	v_readlane_b32 s56, v253, 7
	v_lshl_add_u64 v[156:157], s[2:3], 0, v[2:3]
	v_lshl_add_u64 v[158:159], s[2:3], 0, v[4:5]
	s_or_b32 s2, s20, s19
	s_waitcnt vmcnt(6)
	v_readlane_b32 s57, v253, 8
	s_add_u32 s2, s56, s2
	s_addc_u32 s3, s57, s21
	v_lshl_add_u64 v[160:161], s[2:3], 0, v[2:3]
	v_lshl_add_u64 v[162:163], s[2:3], 0, v[4:5]
	s_mov_b32 s19, -2
	s_mov_b64 s[2:3], 0
	v_add_u32_e32 v1, 0, v15
	v_mov_b32_e32 v2, v0
	v_mov_b32_e32 v3, v0
	v_mov_b32_e32 v4, v0
	v_mov_b32_e32 v5, v0
	v_mov_b32_e32 v6, v0
	v_mov_b32_e32 v7, v0
	v_mov_b32_e32 v8, v0
	v_mov_b32_e32 v9, v0
	v_mov_b32_e32 v10, v0
	v_mov_b32_e32 v11, v0
	v_mov_b32_e32 v12, v0
	v_mov_b32_e32 v13, v0
	v_mov_b32_e32 v14, v0
	v_mov_b32_e32 v15, v0
	v_mov_b32_e32 v16, v0
	v_mov_b32_e32 v17, v0
	v_mov_b32_e32 v18, v0
	v_mov_b32_e32 v19, v0
	v_mov_b32_e32 v20, v0
	v_mov_b32_e32 v21, v0
	v_mov_b32_e32 v22, v0
	v_mov_b32_e32 v23, v0
	v_mov_b32_e32 v24, v0
	v_mov_b32_e32 v25, v0
	v_mov_b32_e32 v26, v0
	v_mov_b32_e32 v27, v0
	v_mov_b32_e32 v28, v0
	v_mov_b32_e32 v29, v0
	v_mov_b32_e32 v30, v0
	v_mov_b32_e32 v31, v0
	v_mov_b32_e32 v32, v0
	v_mov_b32_e32 v33, v0
	v_mov_b32_e32 v34, v0
	v_mov_b32_e32 v35, v0
	v_mov_b32_e32 v36, v0
	v_mov_b32_e32 v37, v0
	v_mov_b32_e32 v38, v0
	v_mov_b32_e32 v39, v0
	v_mov_b32_e32 v40, v0
	v_mov_b32_e32 v41, v0
	v_mov_b32_e32 v42, v0
	v_mov_b32_e32 v43, v0
	v_mov_b32_e32 v44, v0
	v_mov_b32_e32 v45, v0
	v_mov_b32_e32 v46, v0
	v_mov_b32_e32 v47, v0
	v_mov_b32_e32 v48, v0
	v_mov_b32_e32 v49, v0
	v_mov_b32_e32 v50, v0
	v_mov_b32_e32 v51, v0
	v_mov_b32_e32 v52, v0
	v_mov_b32_e32 v53, v0
	v_mov_b32_e32 v54, v0
	v_mov_b32_e32 v55, v0
	v_mov_b32_e32 v56, v0
	v_mov_b32_e32 v57, v0
	v_mov_b32_e32 v58, v0
	v_mov_b32_e32 v59, v0
	v_mov_b32_e32 v60, v0
	v_mov_b32_e32 v61, v0
	v_mov_b32_e32 v62, v0
	v_mov_b32_e32 v63, v0
	v_mov_b32_e32 v64, v0
	v_mov_b32_e32 v65, v0
	v_mov_b32_e32 v66, v0
	v_mov_b32_e32 v67, v0
	v_mov_b32_e32 v68, v0
	v_mov_b32_e32 v69, v0
	v_mov_b32_e32 v70, v0
	v_mov_b32_e32 v71, v0
	v_mov_b32_e32 v72, v0
	v_mov_b32_e32 v73, v0
	v_mov_b32_e32 v74, v0
	v_mov_b32_e32 v75, v0
	v_mov_b32_e32 v76, v0
	v_mov_b32_e32 v77, v0
	v_mov_b32_e32 v78, v0
	v_mov_b32_e32 v79, v0
	v_mov_b32_e32 v80, v0
	v_mov_b32_e32 v81, v0
	v_mov_b32_e32 v82, v0
	v_mov_b32_e32 v83, v0
	v_mov_b32_e32 v84, v0
	v_mov_b32_e32 v85, v0
	v_mov_b32_e32 v86, v0
	v_mov_b32_e32 v87, v0
	v_mov_b32_e32 v88, v0
	v_mov_b32_e32 v89, v0
	v_mov_b32_e32 v90, v0
	v_mov_b32_e32 v91, v0
	v_mov_b32_e32 v92, v0
	v_mov_b32_e32 v93, v0
	v_mov_b32_e32 v94, v0
	v_mov_b32_e32 v95, v0
	v_mov_b32_e32 v96, v0
	v_mov_b32_e32 v97, v0
	v_mov_b32_e32 v98, v0
	v_mov_b32_e32 v99, v0
	v_mov_b32_e32 v100, v0
	v_mov_b32_e32 v101, v0
	v_mov_b32_e32 v102, v0
	v_mov_b32_e32 v103, v0
	v_mov_b32_e32 v104, v0
	v_mov_b32_e32 v105, v0
	v_mov_b32_e32 v106, v0
	v_mov_b32_e32 v107, v0
	v_mov_b32_e32 v108, v0
	v_mov_b32_e32 v109, v0
	v_mov_b32_e32 v110, v0
	v_mov_b32_e32 v111, v0
	v_mov_b32_e32 v112, v0
	v_mov_b32_e32 v113, v0
	v_mov_b32_e32 v114, v0
	v_mov_b32_e32 v115, v0
	v_mov_b32_e32 v116, v0
	v_mov_b32_e32 v117, v0
	v_mov_b32_e32 v118, v0
	v_mov_b32_e32 v119, v0
	v_mov_b32_e32 v120, v0
	v_mov_b32_e32 v121, v0
	v_mov_b32_e32 v122, v0
	v_mov_b32_e32 v123, v0
	v_mov_b32_e32 v124, v0
	v_mov_b32_e32 v125, v0
	v_mov_b32_e32 v126, v0
	v_mov_b32_e32 v127, v0
	v_mov_b32_e32 v128, v0
	v_mov_b32_e32 v129, v0
	s_barrier
	v_readlane_b32 s53, v253, 4
	v_readlane_b32 s54, v253, 5
	v_readlane_b32 s55, v253, 6
	v_readlane_b32 s60, v253, 11
	v_readlane_b32 s61, v253, 12
	v_readlane_b32 s62, v253, 13
	v_readlane_b32 s63, v253, 14
	v_readlane_b32 s64, v253, 15
	v_readlane_b32 s65, v253, 16
	v_readlane_b32 s66, v253, 17
	v_readlane_b32 s67, v253, 18
	s_setprio 0
	s_bitcmp1_b32 s6, 8
	s_cbranch_scc0 .Lprio_3
	s_setprio 1
; #define G8_STAGE(bufoff, gbase, voff) do { _Pragma("unroll") for (int _i = 0; _i < 2; ++_i) \
;     __builtin_amdgcn_global_load_lds((const unsigned*)((const char*)(gbase) + (voff)[_i]), (G8_LAS unsigned*)(lds + (bufoff) + ldsw + _i * 8192), 16, 0, 0); } while (0)
; #define G8_LDA(dst, b, h) do { _Pragma("unroll") for (int m = 0; m < 4; ++m) _Pragma("unroll") for (int k = 0; k < 2; ++k) dst[m][k] = *(const G8_LAS bf16x8*)(lds + G8_OSA(b, h) + aoff + m * 2048 + k * 1024); } while (0)
; #define G8_LDB(dst, b, h) do { _Pragma("unroll") for (int n = 0; n < 2; ++n) _Pragma("unroll") for (int k = 0; k < 2; ++k) dst[n][k] = *(const G8_LAS bf16x8*)(lds + G8_OSB(b, h) + boff + n * 2048 + k * 1024); } while (0)
; #define G8_WAIT_L(n) asm volatile("s_waitcnt lgkmcnt(" #n ")" ::: "memory")
; #define G8_BAR __builtin_amdgcn_s_barrier()
; #define G8_SCHED __builtin_amdgcn_sched_barrier(0)
; __device__ __forceinline__ void gemm256(const bf* __restrict__ A, int lda, const bf* __restrict__ Bt, int ldb, int K,
;                                         int brow, int bcol, f32x4 (&acc)[2][2][4][2]) {
;     ...
;     G8_LDB(B0, 0, 0); G8_SCHED; G8_LDA(At, 0, 0); G8_STAGE(G8_OSA(1, 1), a1 + hstepA, voffA);
;     G8_WAIT_L(8); G8_BAR; G8_WAIT_L(0); G8_MMA(0, 0, At, B0); G8_BAR; G8_SCHED;
;     G8_LDB(B1, 0, 1); G8_STAGE(G8_OSB(0, 0), b2, voffB);
;     G8_BAR; G8_WAIT_L(0); G8_MMA(0, 1, At, B1); G8_BAR;
;     G8_LDA(At, 0, 1); G8_STAGE(G8_OSA(0, 0), a2, voffA);
;     G8_BAR; G8_WAIT_L(0); G8_MMA(1, 0, At, B0); G8_BAR; G8_SCHED;
.Lprio_3:
.LBB0_205:
	s_add_i32 s22, 0, 0x10000
	v_add_u32_e32 v141, s22, v139
	ds_read_b128 v[164:167], v141
	ds_read_b128 v[168:171], v141 offset:1024
	ds_read_b128 v[172:175], v141 offset:2048
	ds_read_b128 v[176:179], v141 offset:3072
	v_lshl_add_u64 v[196:197], v[156:157], 0, s[2:3]
	s_add_i32 s21, s8, 0xc000
	v_lshl_add_u64 v[226:227], v[196:197], 0, s[74:75]
	s_mov_b32 m0, s21
	v_lshl_add_u64 v[242:243], v[158:159], 0, s[2:3]
	s_add_i32 s20, s8, 0xe000
	ds_read_b128 v[180:183], v1
	ds_read_b128 v[184:187], v1 offset:1024
	ds_read_b128 v[188:191], v1 offset:2048
	ds_read_b128 v[192:195], v1 offset:3072
	ds_read_b128 v[210:213], v1 offset:4096
	ds_read_b128 v[214:217], v1 offset:5120
	ds_read_b128 v[218:221], v1 offset:6144
	ds_read_b128 v[222:225], v1 offset:7168
	global_load_lds_dwordx4 v[226:227], off
	v_lshl_add_u64 v[226:227], v[242:243], 0, s[74:75]
	s_mov_b32 m0, s20
	s_nop 0
	global_load_lds_dwordx4 v[226:227], off
	s_waitcnt lgkmcnt(8)
	s_barrier
	s_waitcnt lgkmcnt(0)
	s_waitcnt lgkmcnt(0)
	v_mfma_f32_16x16x32_bf16 v[126:129], v[164:167], v[180:183], v[126:129]
	v_mfma_f32_16x16x32_bf16 v[122:125], v[172:175], v[180:183], v[122:125]
	v_mfma_f32_16x16x32_bf16 v[118:121], v[164:167], v[188:191], v[118:121]
	v_mfma_f32_16x16x32_bf16 v[114:117], v[172:175], v[188:191], v[114:117]
	v_mfma_f32_16x16x32_bf16 v[110:113], v[164:167], v[210:213], v[110:113]
	v_mfma_f32_16x16x32_bf16 v[106:109], v[172:175], v[210:213], v[106:109]
	v_mfma_f32_16x16x32_bf16 v[102:105], v[164:167], v[218:221], v[102:105]
	v_mfma_f32_16x16x32_bf16 v[98:101], v[172:175], v[218:221], v[98:101]
	v_mfma_f32_16x16x32_bf16 v[126:129], v[168:171], v[184:187], v[126:129]
	v_mfma_f32_16x16x32_bf16 v[122:125], v[176:179], v[184:187], v[122:125]
	v_mfma_f32_16x16x32_bf16 v[118:121], v[168:171], v[192:195], v[118:121]
	v_mfma_f32_16x16x32_bf16 v[114:117], v[176:179], v[192:195], v[114:117]
	v_mfma_f32_16x16x32_bf16 v[110:113], v[168:171], v[214:217], v[110:113]
	v_mfma_f32_16x16x32_bf16 v[106:109], v[176:179], v[214:217], v[106:109]
	v_mfma_f32_16x16x32_bf16 v[102:105], v[168:171], v[222:225], v[102:105]
	v_mfma_f32_16x16x32_bf16 v[98:101], v[176:179], v[222:225], v[98:101]
	s_barrier
	s_add_i32 s23, 0, 0x14000
	v_lshl_add_u64 v[244:245], v[160:161], 0, s[2:3]
	s_add_i32 s22, s22, s7
	v_add_u32_e32 v141, s23, v139
	v_lshl_add_u64 v[246:247], v[244:245], 0, s[70:71]
	s_mov_b32 m0, s22
	ds_read_b128 v[226:229], v141
	ds_read_b128 v[230:233], v141 offset:1024
	ds_read_b128 v[234:237], v141 offset:2048
	ds_read_b128 v[238:241], v141 offset:3072
	global_load_lds_dwordx4 v[246:247], off
	v_lshl_add_u64 v[246:247], v[162:163], 0, s[2:3]
	v_lshl_add_u64 v[248:249], v[246:247], 0, s[70:71]
	s_add_i32 m0, s22, 0x2000
	s_nop 0
	global_load_lds_dwordx4 v[248:249], off
	s_barrier
	s_waitcnt lgkmcnt(0)
	s_waitcnt lgkmcnt(0)
	v_mfma_f32_16x16x32_bf16 v[94:97], v[226:229], v[180:183], v[94:97]
	v_mfma_f32_16x16x32_bf16 v[90:93], v[234:237], v[180:183], v[90:93]
	v_mfma_f32_16x16x32_bf16 v[86:89], v[226:229], v[188:191], v[86:89]
	v_mfma_f32_16x16x32_bf16 v[82:85], v[234:237], v[188:191], v[82:85]
	v_mfma_f32_16x16x32_bf16 v[78:81], v[226:229], v[210:213], v[78:81]
	v_mfma_f32_16x16x32_bf16 v[74:77], v[234:237], v[210:213], v[74:77]
	v_mfma_f32_16x16x32_bf16 v[70:73], v[226:229], v[218:221], v[70:73]
	v_mfma_f32_16x16x32_bf16 v[66:69], v[234:237], v[218:221], v[66:69]
	v_mfma_f32_16x16x32_bf16 v[94:97], v[230:233], v[184:187], v[94:97]
	v_mfma_f32_16x16x32_bf16 v[90:93], v[238:241], v[184:187], v[90:93]
	v_mfma_f32_16x16x32_bf16 v[86:89], v[230:233], v[192:195], v[86:89]
	v_mfma_f32_16x16x32_bf16 v[82:85], v[238:241], v[192:195], v[82:85]
	v_mfma_f32_16x16x32_bf16 v[78:81], v[230:233], v[214:217], v[78:81]
	v_mfma_f32_16x16x32_bf16 v[74:77], v[238:241], v[214:217], v[74:77]
	v_mfma_f32_16x16x32_bf16 v[70:73], v[230:233], v[222:225], v[70:73]
	v_mfma_f32_16x16x32_bf16 v[66:69], v[238:241], v[222:225], v[66:69]
	s_mov_b32 m0, s8
	v_lshl_add_u64 v[248:249], v[196:197], 0, s[70:71]
	s_barrier
	ds_read_b128 v[180:183], v1 offset:16384
	ds_read_b128 v[184:187], v1 offset:17408
	ds_read_b128 v[188:191], v1 offset:18432
	ds_read_b128 v[192:195], v1 offset:19456
	ds_read_b128 v[210:213], v1 offset:20480
	ds_read_b128 v[214:217], v1 offset:21504
	ds_read_b128 v[218:221], v1 offset:22528
	ds_read_b128 v[222:225], v1 offset:23552
	global_load_lds_dwordx4 v[248:249], off
	v_lshl_add_u64 v[248:249], v[242:243], 0, s[70:71]
	s_mov_b32 m0, s9
	s_nop 0
	global_load_lds_dwordx4 v[248:249], off
	s_barrier
	s_waitcnt lgkmcnt(0)
	s_waitcnt lgkmcnt(0)
	v_mfma_f32_16x16x32_bf16 v[62:65], v[164:167], v[180:183], v[62:65]
	v_mfma_f32_16x16x32_bf16 v[58:61], v[172:175], v[180:183], v[58:61]
	v_mfma_f32_16x16x32_bf16 v[54:57], v[164:167], v[188:191], v[54:57]
	v_mfma_f32_16x16x32_bf16 v[50:53], v[172:175], v[188:191], v[50:53]
	v_mfma_f32_16x16x32_bf16 v[46:49], v[164:167], v[210:213], v[46:49]
	v_mfma_f32_16x16x32_bf16 v[42:45], v[172:175], v[210:213], v[42:45]
	v_mfma_f32_16x16x32_bf16 v[38:41], v[164:167], v[218:221], v[38:41]
	v_mfma_f32_16x16x32_bf16 v[34:37], v[172:175], v[218:221], v[34:37]
	v_mfma_f32_16x16x32_bf16 v[62:65], v[168:171], v[184:187], v[62:65]
	v_mfma_f32_16x16x32_bf16 v[58:61], v[176:179], v[184:187], v[58:61]
	v_mfma_f32_16x16x32_bf16 v[54:57], v[168:171], v[192:195], v[54:57]
	v_mfma_f32_16x16x32_bf16 v[50:53], v[176:179], v[192:195], v[50:53]
	v_mfma_f32_16x16x32_bf16 v[46:49], v[168:171], v[214:217], v[46:49]
	v_mfma_f32_16x16x32_bf16 v[42:45], v[176:179], v[214:217], v[42:45]
	v_mfma_f32_16x16x32_bf16 v[38:41], v[168:171], v[222:225], v[38:41]
	v_mfma_f32_16x16x32_bf16 v[34:37], v[176:179], v[222:225], v[34:37]
	s_barrier
; #define G8_STAGE(bufoff, gbase, voff) do { _Pragma("unroll") for (int _i = 0; _i < 2; ++_i) \
;     __builtin_amdgcn_global_load_lds((const unsigned*)((const char*)(gbase) + (voff)[_i]), (G8_LAS unsigned*)(lds + (bufoff) + ldsw + _i * 8192), 16, 0, 0); } while (0)
; #define G8_LDA(dst, b, h) do { _Pragma("unroll") for (int m = 0; m < 4; ++m) _Pragma("unroll") for (int k = 0; k < 2; ++k) dst[m][k] = *(const G8_LAS bf16x8*)(lds + G8_OSA(b, h) + aoff + m * 2048 + k * 1024); } while (0)
; #define G8_LDB(dst, b, h) do { _Pragma("unroll") for (int n = 0; n < 2; ++n) _Pragma("unroll") for (int k = 0; k < 2; ++k) dst[n][k] = *(const G8_LAS bf16x8*)(lds + G8_OSB(b, h) + boff + n * 2048 + k * 1024); } while (0)
; #define G8_WAIT_V(n) asm volatile("s_waitcnt vmcnt(" #n ")" ::: "memory")
; #define G8_WAIT_L(n) asm volatile("s_waitcnt lgkmcnt(" #n ")" ::: "memory")
; #define G8_BAR __builtin_amdgcn_s_barrier()
; #define G8_SCHED __builtin_amdgcn_sched_barrier(0)
; __device__ __forceinline__ void gemm256(const bf* __restrict__ A, int lda, const bf* __restrict__ Bt, int ldb, int K,
;                                         int brow, int bcol, f32x4 (&acc)[2][2][4][2]) {
;     ...
;     G8_STAGE(G8_OSB(0, 1), b2 + hstepB, voffB);
;     G8_WAIT_V(6); G8_BAR; G8_MMA(1, 1, At, B1); G8_BAR;
;     G8_LDB(B0, 1, 0); G8_SCHED; G8_LDA(At, 1, 0); G8_STAGE(G8_OSA(0, 1), a2 + hstepA, voffA);
;     G8_WAIT_L(8); G8_BAR; G8_WAIT_L(0); G8_MMA(0, 0, At, B0); G8_BAR; G8_SCHED;
;     G8_LDB(B1, 1, 1); G8_STAGE(G8_OSB(1, 0), b3, voffB);
;     G8_BAR; G8_WAIT_L(0); G8_MMA(0, 1, At, B1); G8_BAR;
;     G8_LDA(At, 1, 1); G8_STAGE(G8_OSA(1, 0), a3, voffA);
	s_add_i32 s22, s23, s7
	v_lshl_add_u64 v[164:165], v[244:245], 0, s[76:77]
	s_mov_b32 m0, s22
	s_nop 0
	global_load_lds_dwordx4 v[164:165], off
	v_lshl_add_u64 v[164:165], v[246:247], 0, s[76:77]
	s_add_i32 m0, s22, 0x2000
	s_nop 0
	global_load_lds_dwordx4 v[164:165], off
	s_waitcnt vmcnt(6)
	s_barrier
	v_mfma_f32_16x16x32_bf16 v[30:33], v[226:229], v[180:183], v[30:33]
	v_mfma_f32_16x16x32_bf16 v[26:29], v[234:237], v[180:183], v[26:29]
	v_mfma_f32_16x16x32_bf16 v[22:25], v[226:229], v[188:191], v[22:25]
	v_mfma_f32_16x16x32_bf16 v[18:21], v[234:237], v[188:191], v[18:21]
	v_mfma_f32_16x16x32_bf16 v[14:17], v[226:229], v[210:213], v[14:17]
	v_mfma_f32_16x16x32_bf16 v[10:13], v[234:237], v[210:213], v[10:13]
	v_mfma_f32_16x16x32_bf16 v[6:9], v[226:229], v[218:221], v[6:9]
	v_mfma_f32_16x16x32_bf16 v[2:5], v[234:237], v[218:221], v[2:5]
	v_mfma_f32_16x16x32_bf16 v[30:33], v[230:233], v[184:187], v[30:33]
	v_mfma_f32_16x16x32_bf16 v[26:29], v[238:241], v[184:187], v[26:29]
	v_mfma_f32_16x16x32_bf16 v[22:25], v[230:233], v[192:195], v[22:25]
	v_mfma_f32_16x16x32_bf16 v[18:21], v[238:241], v[192:195], v[18:21]
	v_mfma_f32_16x16x32_bf16 v[14:17], v[230:233], v[214:217], v[14:17]
	v_mfma_f32_16x16x32_bf16 v[10:13], v[238:241], v[214:217], v[10:13]
	v_mfma_f32_16x16x32_bf16 v[6:9], v[230:233], v[222:225], v[6:9]
	v_mfma_f32_16x16x32_bf16 v[2:5], v[238:241], v[222:225], v[2:5]
	s_add_i32 s22, 0, 0x18000
	v_add_u32_e32 v141, s22, v139
	s_barrier
	ds_read_b128 v[164:167], v141
	ds_read_b128 v[168:171], v141 offset:1024
	ds_read_b128 v[172:175], v141 offset:2048
	ds_read_b128 v[176:179], v141 offset:3072
	s_mov_b32 m0, s11
	v_lshl_add_u64 v[226:227], v[196:197], 0, s[76:77]
	ds_read_b128 v[180:183], v1 offset:32768
	ds_read_b128 v[184:187], v1 offset:33792
	ds_read_b128 v[188:191], v1 offset:34816
	ds_read_b128 v[192:195], v1 offset:35840
	ds_read_b128 v[210:213], v1 offset:36864
	ds_read_b128 v[214:217], v1 offset:37888
	ds_read_b128 v[218:221], v1 offset:38912
	ds_read_b128 v[222:225], v1 offset:39936
	global_load_lds_dwordx4 v[226:227], off
	v_lshl_add_u64 v[226:227], v[242:243], 0, s[76:77]
	s_mov_b32 m0, s16
	s_nop 0
	global_load_lds_dwordx4 v[226:227], off
	s_waitcnt lgkmcnt(8)
	s_barrier
	s_waitcnt lgkmcnt(0)
	s_waitcnt lgkmcnt(0)
	v_mfma_f32_16x16x32_bf16 v[126:129], v[164:167], v[180:183], v[126:129]
	v_mfma_f32_16x16x32_bf16 v[122:125], v[172:175], v[180:183], v[122:125]
	v_mfma_f32_16x16x32_bf16 v[118:121], v[164:167], v[188:191], v[118:121]
	v_mfma_f32_16x16x32_bf16 v[114:117], v[172:175], v[188:191], v[114:117]
	v_mfma_f32_16x16x32_bf16 v[110:113], v[164:167], v[210:213], v[110:113]
	v_mfma_f32_16x16x32_bf16 v[106:109], v[172:175], v[210:213], v[106:109]
	v_mfma_f32_16x16x32_bf16 v[102:105], v[164:167], v[218:221], v[102:105]
	v_mfma_f32_16x16x32_bf16 v[98:101], v[172:175], v[218:221], v[98:101]
	v_mfma_f32_16x16x32_bf16 v[126:129], v[168:171], v[184:187], v[126:129]
	v_mfma_f32_16x16x32_bf16 v[122:125], v[176:179], v[184:187], v[122:125]
	v_mfma_f32_16x16x32_bf16 v[118:121], v[168:171], v[192:195], v[118:121]
	v_mfma_f32_16x16x32_bf16 v[114:117], v[176:179], v[192:195], v[114:117]
	v_mfma_f32_16x16x32_bf16 v[110:113], v[168:171], v[214:217], v[110:113]
	v_mfma_f32_16x16x32_bf16 v[106:109], v[176:179], v[214:217], v[106:109]
	v_mfma_f32_16x16x32_bf16 v[102:105], v[168:171], v[222:225], v[102:105]
	v_mfma_f32_16x16x32_bf16 v[98:101], v[176:179], v[222:225], v[98:101]
	s_barrier
	s_add_i32 s23, 0, 0x1c000
	s_add_i32 s22, s22, s7
	v_add_u32_e32 v141, s23, v139
	v_lshl_add_u64 v[248:249], v[244:245], 0, s[72:73]
	s_mov_b32 m0, s22
	ds_read_b128 v[226:229], v141
	ds_read_b128 v[230:233], v141 offset:1024
	ds_read_b128 v[234:237], v141 offset:2048
	ds_read_b128 v[238:241], v141 offset:3072
	global_load_lds_dwordx4 v[248:249], off
	v_lshl_add_u64 v[248:249], v[246:247], 0, s[72:73]
	s_add_i32 m0, s22, 0x2000
	s_nop 0
	global_load_lds_dwordx4 v[248:249], off
	s_barrier
	s_waitcnt lgkmcnt(0)
	s_waitcnt lgkmcnt(0)
	v_mfma_f32_16x16x32_bf16 v[94:97], v[226:229], v[180:183], v[94:97]
	v_mfma_f32_16x16x32_bf16 v[90:93], v[234:237], v[180:183], v[90:93]
	v_mfma_f32_16x16x32_bf16 v[86:89], v[226:229], v[188:191], v[86:89]
	v_mfma_f32_16x16x32_bf16 v[82:85], v[234:237], v[188:191], v[82:85]
	v_mfma_f32_16x16x32_bf16 v[78:81], v[226:229], v[210:213], v[78:81]
	v_mfma_f32_16x16x32_bf16 v[74:77], v[234:237], v[210:213], v[74:77]
	v_mfma_f32_16x16x32_bf16 v[70:73], v[226:229], v[218:221], v[70:73]
	v_mfma_f32_16x16x32_bf16 v[66:69], v[234:237], v[218:221], v[66:69]
	v_mfma_f32_16x16x32_bf16 v[94:97], v[230:233], v[184:187], v[94:97]
	v_mfma_f32_16x16x32_bf16 v[90:93], v[238:241], v[184:187], v[90:93]
	v_mfma_f32_16x16x32_bf16 v[86:89], v[230:233], v[192:195], v[86:89]
	v_mfma_f32_16x16x32_bf16 v[82:85], v[238:241], v[192:195], v[82:85]
	v_mfma_f32_16x16x32_bf16 v[78:81], v[230:233], v[214:217], v[78:81]
	v_mfma_f32_16x16x32_bf16 v[74:77], v[238:241], v[214:217], v[74:77]
	v_mfma_f32_16x16x32_bf16 v[70:73], v[230:233], v[222:225], v[70:73]
	v_mfma_f32_16x16x32_bf16 v[66:69], v[238:241], v[222:225], v[66:69]
	s_mov_b32 m0, s17
	v_lshl_add_u64 v[196:197], v[196:197], 0, s[72:73]
	s_barrier
	ds_read_b128 v[180:183], v1 offset:49152
	ds_read_b128 v[184:187], v1 offset:50176
	ds_read_b128 v[188:191], v1 offset:51200
	ds_read_b128 v[192:195], v1 offset:52224
	ds_read_b128 v[210:213], v1 offset:53248
	ds_read_b128 v[214:217], v1 offset:54272
	ds_read_b128 v[218:221], v1 offset:55296
	ds_read_b128 v[222:225], v1 offset:56320
	global_load_lds_dwordx4 v[196:197], off
	v_lshl_add_u64 v[196:197], v[242:243], 0, s[72:73]
	s_mov_b32 m0, s18
	s_nop 0
	global_load_lds_dwordx4 v[196:197], off
	s_barrier
; #define G8_STAGE(bufoff, gbase, voff) do { _Pragma("unroll") for (int _i = 0; _i < 2; ++_i) \
;     __builtin_amdgcn_global_load_lds((const unsigned*)((const char*)(gbase) + (voff)[_i]), (G8_LAS unsigned*)(lds + (bufoff) + ldsw + _i * 8192), 16, 0, 0); } while (0)
; #define G8_LDA(dst, b, h) do { _Pragma("unroll") for (int m = 0; m < 4; ++m) _Pragma("unroll") for (int k = 0; k < 2; ++k) dst[m][k] = *(const G8_LAS bf16x8*)(lds + G8_OSA(b, h) + aoff + m * 2048 + k * 1024); } while (0)
; #define G8_LDB(dst, b, h) do { _Pragma("unroll") for (int n = 0; n < 2; ++n) _Pragma("unroll") for (int k = 0; k < 2; ++k) dst[n][k] = *(const G8_LAS bf16x8*)(lds + G8_OSB(b, h) + boff + n * 2048 + k * 1024); } while (0)
; #define G8_WAIT_V(n) asm volatile("s_waitcnt vmcnt(" #n ")" ::: "memory")
; #define G8_WAIT_L(n) asm volatile("s_waitcnt lgkmcnt(" #n ")" ::: "memory")
; #define G8_BAR __builtin_amdgcn_s_barrier()
; #define G8_SCHED __builtin_amdgcn_sched_barrier(0)
; __device__ __forceinline__ void gemm256(const bf* __restrict__ A, int lda, const bf* __restrict__ Bt, int ldb, int K,
;                                         int brow, int bcol, f32x4 (&acc)[2][2][4][2]) {
;     ...
;     G8_BAR; G8_WAIT_L(0); G8_MMA(1, 0, At, B0); G8_BAR; G8_SCHED;
;     G8_STAGE(G8_OSB(1, 1), b3 + hstepB, voffB);
;     G8_WAIT_V(6); G8_BAR; G8_MMA(1, 1, At, B1); G8_BAR;
;   }
;   { const char* a1 = cA + (size_t)(nt - 1) * kstep;
;     G8_LDB(B0, 0, 0); G8_LDA(At, 0, 0); G8_STAGE(G8_OSA(1, 1), a1 + hstepA, voffA);
;     G8_BAR; G8_WAIT_L(0); G8_MMA(0, 0, At, B0); G8_BAR;
;     G8_LDB(B1, 0, 1); G8_BAR; G8_WAIT_L(0); G8_MMA(0, 1, At, B1); G8_BAR;
;     G8_LDA(At, 0, 1); G8_WAIT_V(4); G8_BAR; G8_WAIT_L(0); G8_MMA(1, 0, At, B0); G8_MMA(1, 1, At, B1); G8_BAR; }
	s_waitcnt lgkmcnt(0)
	s_waitcnt lgkmcnt(0)
	v_mfma_f32_16x16x32_bf16 v[62:65], v[164:167], v[180:183], v[62:65]
	v_mfma_f32_16x16x32_bf16 v[58:61], v[172:175], v[180:183], v[58:61]
	v_mfma_f32_16x16x32_bf16 v[54:57], v[164:167], v[188:191], v[54:57]
	v_mfma_f32_16x16x32_bf16 v[50:53], v[172:175], v[188:191], v[50:53]
	v_mfma_f32_16x16x32_bf16 v[46:49], v[164:167], v[210:213], v[46:49]
	v_mfma_f32_16x16x32_bf16 v[42:45], v[172:175], v[210:213], v[42:45]
	v_mfma_f32_16x16x32_bf16 v[38:41], v[164:167], v[218:221], v[38:41]
	v_mfma_f32_16x16x32_bf16 v[34:37], v[172:175], v[218:221], v[34:37]
	v_mfma_f32_16x16x32_bf16 v[62:65], v[168:171], v[184:187], v[62:65]
	v_mfma_f32_16x16x32_bf16 v[58:61], v[176:179], v[184:187], v[58:61]
	v_mfma_f32_16x16x32_bf16 v[54:57], v[168:171], v[192:195], v[54:57]
	v_mfma_f32_16x16x32_bf16 v[50:53], v[176:179], v[192:195], v[50:53]
	v_mfma_f32_16x16x32_bf16 v[46:49], v[168:171], v[214:217], v[46:49]
	v_mfma_f32_16x16x32_bf16 v[42:45], v[176:179], v[214:217], v[42:45]
	v_mfma_f32_16x16x32_bf16 v[38:41], v[168:171], v[222:225], v[38:41]
	v_mfma_f32_16x16x32_bf16 v[34:37], v[176:179], v[222:225], v[34:37]
	s_barrier
	s_add_i32 s22, s23, s7
	v_lshl_add_u64 v[164:165], v[244:245], 0, s[84:85]
	s_mov_b32 m0, s22
	s_nop 0
	global_load_lds_dwordx4 v[164:165], off
	v_lshl_add_u64 v[164:165], v[246:247], 0, s[84:85]
	s_add_i32 m0, s22, 0x2000
	s_nop 0
	global_load_lds_dwordx4 v[164:165], off
	s_waitcnt vmcnt(6)
	s_barrier
	v_mfma_f32_16x16x32_bf16 v[30:33], v[226:229], v[180:183], v[30:33]
	v_mfma_f32_16x16x32_bf16 v[26:29], v[234:237], v[180:183], v[26:29]
	v_mfma_f32_16x16x32_bf16 v[22:25], v[226:229], v[188:191], v[22:25]
	v_mfma_f32_16x16x32_bf16 v[18:21], v[234:237], v[188:191], v[18:21]
	v_mfma_f32_16x16x32_bf16 v[14:17], v[226:229], v[210:213], v[14:17]
	v_mfma_f32_16x16x32_bf16 v[10:13], v[234:237], v[210:213], v[10:13]
	v_mfma_f32_16x16x32_bf16 v[6:9], v[226:229], v[218:221], v[6:9]
	v_mfma_f32_16x16x32_bf16 v[2:5], v[234:237], v[218:221], v[2:5]
	v_mfma_f32_16x16x32_bf16 v[30:33], v[230:233], v[184:187], v[30:33]
	v_mfma_f32_16x16x32_bf16 v[26:29], v[238:241], v[184:187], v[26:29]
	v_mfma_f32_16x16x32_bf16 v[22:25], v[230:233], v[192:195], v[22:25]
	v_mfma_f32_16x16x32_bf16 v[18:21], v[238:241], v[192:195], v[18:21]
	v_mfma_f32_16x16x32_bf16 v[14:17], v[230:233], v[214:217], v[14:17]
	v_mfma_f32_16x16x32_bf16 v[10:13], v[238:241], v[214:217], v[10:13]
	v_mfma_f32_16x16x32_bf16 v[6:9], v[230:233], v[222:225], v[6:9]
	v_mfma_f32_16x16x32_bf16 v[2:5], v[238:241], v[222:225], v[2:5]
	s_add_i32 s19, s19, 2
	s_add_u32 s2, s2, 0x100
	s_addc_u32 s3, s3, 0
	s_cmp_gt_u32 s19, 27
	s_barrier
	s_cbranch_scc0 .LBB0_205
	s_add_u32 s0, s0, 0x80f80
	v_add_u32_e32 v139, 0, v139
	s_addc_u32 s1, s1, 0
	s_mov_b32 m0, s21
	v_add_u32_e32 v141, 0x10000, v139
	v_lshl_add_u64 v[196:197], s[0:1], 0, v[144:145]
	ds_read_b128 v[156:159], v141
	ds_read_b128 v[160:163], v141 offset:1024
	ds_read_b128 v[164:167], v141 offset:2048
	ds_read_b128 v[168:171], v141 offset:3072
	ds_read_b128 v[172:175], v1
	ds_read_b128 v[176:179], v1 offset:1024
	ds_read_b128 v[180:183], v1 offset:2048
	ds_read_b128 v[184:187], v1 offset:3072
	ds_read_b128 v[188:191], v1 offset:4096
	ds_read_b128 v[192:195], v1 offset:5120
	ds_read_b128 v[214:217], v1 offset:6144
	ds_read_b128 v[218:221], v1 offset:7168
	global_load_lds_dwordx4 v[196:197], off
	v_lshl_add_u64 v[154:155], s[0:1], 0, v[154:155]
	s_mov_b32 m0, s20
	s_nop 0
	global_load_lds_dwordx4 v[154:155], off
	s_barrier
	s_waitcnt lgkmcnt(0)
	s_waitcnt lgkmcnt(0)
	v_mfma_f32_16x16x32_bf16 v[126:129], v[156:159], v[172:175], v[126:129]
	v_mfma_f32_16x16x32_bf16 v[122:125], v[164:167], v[172:175], v[122:125]
	v_mfma_f32_16x16x32_bf16 v[118:121], v[156:159], v[180:183], v[118:121]
	v_mfma_f32_16x16x32_bf16 v[114:117], v[164:167], v[180:183], v[114:117]
	v_mfma_f32_16x16x32_bf16 v[102:105], v[156:159], v[214:217], v[102:105]
	v_mfma_f32_16x16x32_bf16 v[98:101], v[164:167], v[214:217], v[98:101]
	v_mfma_f32_16x16x32_bf16 v[126:129], v[160:163], v[176:179], v[126:129]
	v_mfma_f32_16x16x32_bf16 v[122:125], v[168:171], v[176:179], v[122:125]
	v_mfma_f32_16x16x32_bf16 v[118:121], v[160:163], v[184:187], v[118:121]
	v_mfma_f32_16x16x32_bf16 v[114:117], v[168:171], v[184:187], v[114:117]
	v_mfma_f32_16x16x32_bf16 v[110:113], v[156:159], v[188:191], v[110:113]
	v_mfma_f32_16x16x32_bf16 v[106:109], v[164:167], v[188:191], v[106:109]
	v_mfma_f32_16x16x32_bf16 v[102:105], v[160:163], v[218:221], v[102:105]
	v_mfma_f32_16x16x32_bf16 v[98:101], v[168:171], v[218:221], v[98:101]
	v_mfma_f32_16x16x32_bf16 v[222:225], v[160:163], v[192:195], v[110:113]
	v_mfma_f32_16x16x32_bf16 v[226:229], v[168:171], v[192:195], v[106:109]
	v_add_u32_e32 v141, 0x14000, v139
	s_barrier
	s_nop 0
	ds_read_b128 v[106:109], v141
	ds_read_b128 v[110:113], v141 offset:1024
	ds_read_b128 v[230:233], v141 offset:2048
	ds_read_b128 v[234:237], v141 offset:3072
	s_barrier
	s_waitcnt lgkmcnt(0)
	s_waitcnt lgkmcnt(0)
	v_mfma_f32_16x16x32_bf16 v[86:89], v[106:109], v[180:183], v[86:89]
	v_mfma_f32_16x16x32_bf16 v[82:85], v[230:233], v[180:183], v[82:85]
	v_mfma_f32_16x16x32_bf16 v[70:73], v[106:109], v[214:217], v[70:73]
	v_mfma_f32_16x16x32_bf16 v[66:69], v[230:233], v[214:217], v[66:69]
	v_mfma_f32_16x16x32_bf16 v[94:97], v[106:109], v[172:175], v[94:97]
	v_mfma_f32_16x16x32_bf16 v[90:93], v[230:233], v[172:175], v[90:93]
	v_mfma_f32_16x16x32_bf16 v[86:89], v[110:113], v[184:187], v[86:89]
	v_mfma_f32_16x16x32_bf16 v[82:85], v[234:237], v[184:187], v[82:85]
	v_mfma_f32_16x16x32_bf16 v[78:81], v[106:109], v[188:191], v[78:81]
	v_mfma_f32_16x16x32_bf16 v[74:77], v[230:233], v[188:191], v[74:77]
	v_mfma_f32_16x16x32_bf16 v[70:73], v[110:113], v[218:221], v[70:73]
	v_mfma_f32_16x16x32_bf16 v[66:69], v[234:237], v[218:221], v[66:69]
	v_mfma_f32_16x16x32_bf16 v[238:241], v[110:113], v[176:179], v[94:97]
	v_mfma_f32_16x16x32_bf16 v[172:175], v[234:237], v[176:179], v[90:93]
	v_mfma_f32_16x16x32_bf16 v[176:179], v[110:113], v[192:195], v[78:81]
	v_mfma_f32_16x16x32_bf16 v[180:183], v[234:237], v[192:195], v[74:77]
	s_barrier
; #define G8_LDA(dst, b, h) do { _Pragma("unroll") for (int m = 0; m < 4; ++m) _Pragma("unroll") for (int k = 0; k < 2; ++k) dst[m][k] = *(const G8_LAS bf16x8*)(lds + G8_OSA(b, h) + aoff + m * 2048 + k * 1024); } while (0)
; #define G8_LDB(dst, b, h) do { _Pragma("unroll") for (int n = 0; n < 2; ++n) _Pragma("unroll") for (int k = 0; k < 2; ++k) dst[n][k] = *(const G8_LAS bf16x8*)(lds + G8_OSB(b, h) + boff + n * 2048 + k * 1024); } while (0)
; #define G8_WAIT_V(n) asm volatile("s_waitcnt vmcnt(" #n ")" ::: "memory")
; #define G8_WAIT_L(n) asm volatile("s_waitcnt lgkmcnt(" #n ")" ::: "memory")
; #define G8_BAR __builtin_amdgcn_s_barrier()
; __device__ __forceinline__ void gemm256(const bf* __restrict__ A, int lda, const bf* __restrict__ Bt, int ldb, int K,
;                                         int brow, int bcol, f32x4 (&acc)[2][2][4][2]) {
;     ...
;     G8_LDA(At, 0, 1); G8_WAIT_V(4); G8_BAR; G8_WAIT_L(0); G8_MMA(1, 0, At, B0); G8_MMA(1, 1, At, B1); G8_BAR; }
;   { G8_LDB(B0, 1, 0); G8_LDA(At, 1, 0); G8_WAIT_V(2); G8_BAR; G8_WAIT_L(0); G8_MMA(0, 0, At, B0); G8_BAR;
;     G8_LDB(B1, 1, 1); G8_WAIT_V(0); G8_BAR; G8_WAIT_L(0); G8_MMA(0, 1, At, B1); G8_BAR;
	s_nop 0
	ds_read_b128 v[74:77], v1 offset:16384
	ds_read_b128 v[78:81], v1 offset:17408
	ds_read_b128 v[90:93], v1 offset:18432
	ds_read_b128 v[94:97], v1 offset:19456
	ds_read_b128 v[184:187], v1 offset:20480
	ds_read_b128 v[188:191], v1 offset:21504
	ds_read_b128 v[192:195], v1 offset:22528
	ds_read_b128 v[214:217], v1 offset:23552
	s_waitcnt vmcnt(4)
	s_barrier
	s_waitcnt lgkmcnt(0)
	s_waitcnt lgkmcnt(0)
	v_mfma_f32_16x16x32_bf16 v[62:65], v[156:159], v[74:77], v[62:65]
	v_mfma_f32_16x16x32_bf16 v[58:61], v[164:167], v[74:77], v[58:61]
	v_mfma_f32_16x16x32_bf16 v[54:57], v[156:159], v[90:93], v[54:57]
	v_mfma_f32_16x16x32_bf16 v[50:53], v[164:167], v[90:93], v[50:53]
	v_mfma_f32_16x16x32_bf16 v[38:41], v[156:159], v[192:195], v[38:41]
	v_mfma_f32_16x16x32_bf16 v[34:37], v[164:167], v[192:195], v[34:37]
	v_mfma_f32_16x16x32_bf16 v[62:65], v[160:163], v[78:81], v[62:65]
	v_mfma_f32_16x16x32_bf16 v[58:61], v[168:171], v[78:81], v[58:61]
	v_mfma_f32_16x16x32_bf16 v[54:57], v[160:163], v[94:97], v[54:57]
	v_mfma_f32_16x16x32_bf16 v[50:53], v[168:171], v[94:97], v[50:53]
	v_mfma_f32_16x16x32_bf16 v[46:49], v[156:159], v[184:187], v[46:49]
	v_mfma_f32_16x16x32_bf16 v[42:45], v[164:167], v[184:187], v[42:45]
	v_mfma_f32_16x16x32_bf16 v[38:41], v[160:163], v[214:217], v[38:41]
	v_mfma_f32_16x16x32_bf16 v[34:37], v[168:171], v[214:217], v[34:37]
	v_mfma_f32_16x16x32_bf16 v[218:221], v[160:163], v[188:191], v[46:49]
	v_mfma_f32_16x16x32_bf16 v[242:245], v[168:171], v[188:191], v[42:45]
	v_mfma_f32_16x16x32_bf16 v[22:25], v[106:109], v[90:93], v[22:25]
	v_mfma_f32_16x16x32_bf16 v[18:21], v[230:233], v[90:93], v[18:21]
	v_mfma_f32_16x16x32_bf16 v[6:9], v[106:109], v[192:195], v[6:9]
	v_mfma_f32_16x16x32_bf16 v[2:5], v[230:233], v[192:195], v[2:5]
	v_mfma_f32_16x16x32_bf16 v[30:33], v[106:109], v[74:77], v[30:33]
	v_mfma_f32_16x16x32_bf16 v[26:29], v[230:233], v[74:77], v[26:29]
	v_mfma_f32_16x16x32_bf16 v[22:25], v[110:113], v[94:97], v[22:25]
	v_mfma_f32_16x16x32_bf16 v[18:21], v[234:237], v[94:97], v[18:21]
	v_mfma_f32_16x16x32_bf16 v[14:17], v[106:109], v[184:187], v[14:17]
	v_mfma_f32_16x16x32_bf16 v[10:13], v[230:233], v[184:187], v[10:13]
	v_mfma_f32_16x16x32_bf16 v[6:9], v[110:113], v[214:217], v[6:9]
	v_mfma_f32_16x16x32_bf16 v[2:5], v[234:237], v[214:217], v[2:5]
	v_mfma_f32_16x16x32_bf16 v[154:157], v[110:113], v[78:81], v[30:33]
	v_mfma_f32_16x16x32_bf16 v[158:161], v[234:237], v[78:81], v[26:29]
	v_mfma_f32_16x16x32_bf16 v[162:165], v[110:113], v[188:191], v[14:17]
	v_mfma_f32_16x16x32_bf16 v[166:169], v[234:237], v[188:191], v[10:13]
	v_add_u32_e32 v26, 0x18000, v139
	s_barrier
	ds_read_b128 v[10:13], v26
	ds_read_b128 v[14:17], v26 offset:1024
	ds_read_b128 v[184:187], v26 offset:2048
	ds_read_b128 v[188:191], v26 offset:3072
	ds_read_b128 v[26:29], v1 offset:32768
	ds_read_b128 v[30:33], v1 offset:33792
	ds_read_b128 v[42:45], v1 offset:34816
	ds_read_b128 v[46:49], v1 offset:35840
	ds_read_b128 v[192:195], v1 offset:36864
	ds_read_b128 v[214:217], v1 offset:37888
	ds_read_b128 v[230:233], v1 offset:38912
	ds_read_b128 v[234:237], v1 offset:39936
	s_waitcnt vmcnt(2)
	s_barrier
	s_waitcnt lgkmcnt(0)
	s_waitcnt lgkmcnt(0)
	v_mfma_f32_16x16x32_bf16 v[74:77], v[10:13], v[26:29], v[126:129]
	v_mfma_f32_16x16x32_bf16 v[126:129], v[14:17], v[30:33], v[74:77]
	v_mfma_f32_16x16x32_bf16 v[74:77], v[184:187], v[26:29], v[122:125]
	v_mfma_f32_16x16x32_bf16 v[122:125], v[188:191], v[30:33], v[74:77]
	v_mfma_f32_16x16x32_bf16 v[74:77], v[10:13], v[42:45], v[118:121]
	v_mfma_f32_16x16x32_bf16 v[110:113], v[14:17], v[46:49], v[74:77]
	v_mfma_f32_16x16x32_bf16 v[74:77], v[184:187], v[42:45], v[114:117]
	v_mfma_f32_16x16x32_bf16 v[106:109], v[188:191], v[46:49], v[74:77]
	v_mfma_f32_16x16x32_bf16 v[74:77], v[10:13], v[192:195], v[222:225]
	v_mfma_f32_16x16x32_bf16 v[94:97], v[14:17], v[214:217], v[74:77]
	v_mfma_f32_16x16x32_bf16 v[74:77], v[184:187], v[192:195], v[226:229]
	v_mfma_f32_16x16x32_bf16 v[90:93], v[188:191], v[214:217], v[74:77]
	v_mfma_f32_16x16x32_bf16 v[74:77], v[10:13], v[230:233], v[102:105]
	v_mfma_f32_16x16x32_bf16 v[78:81], v[14:17], v[234:237], v[74:77]
	v_mfma_f32_16x16x32_bf16 v[74:77], v[184:187], v[230:233], v[98:101]
	v_mfma_f32_16x16x32_bf16 v[74:77], v[188:191], v[234:237], v[74:77]
	s_nop 0
	v_add_u32_e32 v98, 0x1c000, v139
	s_barrier
; #define G8_LDA(dst, b, h) do { _Pragma("unroll") for (int m = 0; m < 4; ++m) _Pragma("unroll") for (int k = 0; k < 2; ++k) dst[m][k] = *(const G8_LAS bf16x8*)(lds + G8_OSA(b, h) + aoff + m * 2048 + k * 1024); } while (0)
; #define G8_LDB(dst, b, h) do { _Pragma("unroll") for (int n = 0; n < 2; ++n) _Pragma("unroll") for (int k = 0; k < 2; ++k) dst[n][k] = *(const G8_LAS bf16x8*)(lds + G8_OSB(b, h) + boff + n * 2048 + k * 1024); } while (0)
; #define G8_WAIT_V(n) asm volatile("s_waitcnt vmcnt(" #n ")" ::: "memory")
; #define G8_WAIT_L(n) asm volatile("s_waitcnt lgkmcnt(" #n ")" ::: "memory")
; #define G8_BAR __builtin_amdgcn_s_barrier()
; __device__ __forceinline__ void gemm256(const bf* __restrict__ A, int lda, const bf* __restrict__ Bt, int ldb, int K,
;                                         int brow, int bcol, f32x4 (&acc)[2][2][4][2]) {
;     ...
;   { G8_LDB(B0, 1, 0); G8_LDA(At, 1, 0); G8_WAIT_V(2); G8_BAR; G8_WAIT_L(0); G8_MMA(0, 0, At, B0); G8_BAR;
;     G8_LDB(B1, 1, 1); G8_WAIT_V(0); G8_BAR; G8_WAIT_L(0); G8_MMA(0, 1, At, B1); G8_BAR;
;     G8_LDA(At, 1, 1); G8_BAR; G8_WAIT_L(0); G8_MMA(1, 0, At, B0); G8_MMA(1, 1, At, B1); G8_BAR; }
;   if (wr == 0) G8_BAR;
	ds_read_b128 v[222:225], v98
	ds_read_b128 v[226:229], v98 offset:1024
	ds_read_b128 v[246:249], v98 offset:2048
	ds_read_b128 v[210:213], v98 offset:3072
	s_waitcnt vmcnt(0)
	s_barrier
	s_waitcnt lgkmcnt(0)
	s_waitcnt lgkmcnt(0)
	v_mfma_f32_16x16x32_bf16 v[98:101], v[222:225], v[26:29], v[238:241]
	v_mfma_f32_16x16x32_bf16 v[26:29], v[246:249], v[26:29], v[172:175]
	v_mfma_f32_16x16x32_bf16 v[114:117], v[210:213], v[30:33], v[26:29]
	v_mfma_f32_16x16x32_bf16 v[26:29], v[222:225], v[42:45], v[86:89]
	v_mfma_f32_16x16x32_bf16 v[102:105], v[226:229], v[46:49], v[26:29]
	v_mfma_f32_16x16x32_bf16 v[26:29], v[246:249], v[42:45], v[82:85]
	v_mfma_f32_16x16x32_bf16 v[118:121], v[226:229], v[30:33], v[98:101]
	v_mfma_f32_16x16x32_bf16 v[98:101], v[210:213], v[46:49], v[26:29]
	v_mfma_f32_16x16x32_bf16 v[26:29], v[222:225], v[192:195], v[176:179]
	v_mfma_f32_16x16x32_bf16 v[86:89], v[226:229], v[214:217], v[26:29]
	v_mfma_f32_16x16x32_bf16 v[26:29], v[246:249], v[192:195], v[180:183]
	v_mfma_f32_16x16x32_bf16 v[82:85], v[210:213], v[214:217], v[26:29]
	v_mfma_f32_16x16x32_bf16 v[26:29], v[222:225], v[230:233], v[70:73]
	v_mfma_f32_16x16x32_bf16 v[70:73], v[226:229], v[234:237], v[26:29]
	v_mfma_f32_16x16x32_bf16 v[26:29], v[246:249], v[230:233], v[66:69]
	v_mfma_f32_16x16x32_bf16 v[66:69], v[210:213], v[234:237], v[26:29]
	s_barrier
	ds_read_b128 v[170:173], v1 offset:49152
	ds_read_b128 v[174:177], v1 offset:50176
	ds_read_b128 v[178:181], v1 offset:51200
	ds_read_b128 v[192:195], v1 offset:52224
	ds_read_b128 v[214:217], v1 offset:53248
	ds_read_b128 v[230:233], v1 offset:54272
	ds_read_b128 v[234:237], v1 offset:55296
	ds_read_b128 v[238:241], v1 offset:56320
	s_barrier
	s_waitcnt lgkmcnt(0)
	s_waitcnt lgkmcnt(0)
	v_mfma_f32_16x16x32_bf16 v[26:29], v[10:13], v[170:173], v[62:65]
	v_mfma_f32_16x16x32_bf16 v[62:65], v[14:17], v[174:177], v[26:29]
	v_mfma_f32_16x16x32_bf16 v[26:29], v[184:187], v[170:173], v[58:61]
	v_mfma_f32_16x16x32_bf16 v[58:61], v[188:191], v[174:177], v[26:29]
	v_mfma_f32_16x16x32_bf16 v[26:29], v[10:13], v[178:181], v[54:57]
	v_mfma_f32_16x16x32_bf16 v[46:49], v[14:17], v[192:195], v[26:29]
	v_mfma_f32_16x16x32_bf16 v[26:29], v[184:187], v[178:181], v[50:53]
	v_mfma_f32_16x16x32_bf16 v[42:45], v[188:191], v[192:195], v[26:29]
	v_mfma_f32_16x16x32_bf16 v[26:29], v[10:13], v[214:217], v[218:221]
	v_mfma_f32_16x16x32_bf16 v[10:13], v[10:13], v[234:237], v[38:41]
	v_mfma_f32_16x16x32_bf16 v[30:33], v[14:17], v[230:233], v[26:29]
	v_mfma_f32_16x16x32_bf16 v[26:29], v[184:187], v[214:217], v[242:245]
	v_mfma_f32_16x16x32_bf16 v[14:17], v[14:17], v[238:241], v[10:13]
	v_mfma_f32_16x16x32_bf16 v[10:13], v[184:187], v[234:237], v[34:37]
	v_mfma_f32_16x16x32_bf16 v[26:29], v[188:191], v[230:233], v[26:29]
	v_mfma_f32_16x16x32_bf16 v[10:13], v[188:191], v[238:241], v[10:13]
	v_mfma_f32_16x16x32_bf16 v[34:37], v[222:225], v[170:173], v[154:157]
	v_mfma_f32_16x16x32_bf16 v[54:57], v[226:229], v[174:177], v[34:37]
	v_mfma_f32_16x16x32_bf16 v[34:37], v[246:249], v[170:173], v[158:161]
	v_mfma_f32_16x16x32_bf16 v[18:21], v[246:249], v[178:181], v[18:21]
	v_mfma_f32_16x16x32_bf16 v[50:53], v[210:213], v[174:177], v[34:37]
	v_mfma_f32_16x16x32_bf16 v[22:25], v[222:225], v[178:181], v[22:25]
	v_mfma_f32_16x16x32_bf16 v[34:37], v[210:213], v[192:195], v[18:21]
	v_mfma_f32_16x16x32_bf16 v[18:21], v[222:225], v[214:217], v[162:165]
	v_mfma_f32_16x16x32_bf16 v[38:41], v[226:229], v[192:195], v[22:25]
	v_mfma_f32_16x16x32_bf16 v[22:25], v[226:229], v[230:233], v[18:21]
	v_mfma_f32_16x16x32_bf16 v[18:21], v[246:249], v[214:217], v[166:169]
	v_mfma_f32_16x16x32_bf16 v[6:9], v[222:225], v[234:237], v[6:9]
	v_mfma_f32_16x16x32_bf16 v[2:5], v[246:249], v[234:237], v[2:5]
	v_mfma_f32_16x16x32_bf16 v[18:21], v[210:213], v[230:233], v[18:21]
	v_mfma_f32_16x16x32_bf16 v[6:9], v[226:229], v[238:241], v[6:9]
	v_mfma_f32_16x16x32_bf16 v[2:5], v[210:213], v[238:241], v[2:5]
	s_setprio 0
	s_cmpk_lt_u32 s6, 0x100
	s_barrier
	s_cbranch_scc0 .LBB0_208
	s_barrier

; __device__ __forceinline__ int otid_full() { int t = threadIdx.x; asm volatile("" : "+v"(t)); return t; }
; #define G8_STAGE(bufoff, gbase, voff) do { _Pragma("unroll") for (int _i = 0; _i < 2; ++_i) \
;     __builtin_amdgcn_global_load_lds((const unsigned*)((const char*)(gbase) + (voff)[_i]), (G8_LAS unsigned*)(lds + (bufoff) + ldsw + _i * 8192), 16, 0, 0); } while (0)
; #define G8_WAIT_V(n) asm volatile("s_waitcnt vmcnt(" #n ")" ::: "memory")
; #define G8_BAR __builtin_amdgcn_s_barrier()
; __device__ __forceinline__ void gemm256(const bf* __restrict__ A, int lda, const bf* __restrict__ Bt, int ldb, int K,
;                                         int brow, int bcol, f32x4 (&acc)[2][2][4][2]) {
;     ...
;   const int tid = otid_full(), wid = __builtin_amdgcn_readfirstlane(tid >> 6), lane = tid & 63, wr = wid >> 2, wc = wid & 3, fr = lane & 15, fq = lane >> 4;
;   unsigned voffA[2], voffB[2];
; #pragma unroll
;   for (int i = 0; i < 2; ++i) { int R, C; g8_stage_rc(tid * 16 + i * 8192, R, C); voffA[i] = (unsigned)(R * lda + C) * 2u; voffB[i] = (unsigned)(R * ldb + C) * 2u; }
;   const size_t kstep = 128;
;   const size_t hstepA = (size_t)128 * lda * 2, hstepB = (size_t)128 * ldb * 2;
;   const unsigned ldsw = (unsigned)wid * 1024u;
;   const int aoff = g8_lds_byte(wr * 64 + fr, fq * 8), boff = g8_lds_byte(wc * 32 + fr, fq * 8);
;   const char* cA = (const char*)A + (size_t)brow * lda * 2; const char* cB = (const char*)Bt + (size_t)bcol * ldb * 2;
;   bf16x8 At[4][2], B0[2][2], B1[2][2];
;   const int nt = K / 64;
;   __syncthreads();
;   G8_STAGE(G8_OSB(0, 0), cB, voffB); G8_STAGE(G8_OSA(0, 0), cA, voffA); G8_STAGE(G8_OSB(0, 1), cB + hstepB, voffB); G8_STAGE(G8_OSA(0, 1), cA + hstepA, voffA);
;   if (wr == 1) G8_BAR;
;   G8_WAIT_V(4); G8_BAR;
;   G8_STAGE(G8_OSB(1, 0), cB + kstep, voffB); G8_STAGE(G8_OSA(1, 0), cA + kstep, voffA); G8_STAGE(G8_OSB(1, 1), cB + hstepB + kstep, voffB);
;   G8_WAIT_V(6); G8_BAR;
.LBB0_276:
	v_and_b32_e32 v16, 15, v15
	v_and_b32_e32 v17, 48, v15
	v_lshlrev_b32_e32 v15, 2, v15
	v_lshlrev_b32_e32 v16, 6, v16
	v_and_b32_e32 v15, 32, v15
	s_lshl_b32 s22, s22, 12
	v_or_b32_e32 v18, v16, v17
	v_bitop3_b32 v16, v16, v15, v17 bitop3:0x36
	s_lshl_b32 s21, s21, 13
	s_and_b32 s22, s22, 0x3000
	s_add_i32 m0, s1, 0x18000
	v_lshl_add_u64 v[8:9], v[8:9], 0, s[50:51]
	v_or_b32_e32 v141, s22, v16
	v_bitop3_b32 v15, v18, s21, v15 bitop3:0xde
	s_waitcnt vmcnt(4)
	s_barrier
	global_load_lds_dwordx4 v[8:9], off
	v_lshl_add_u64 v[6:7], v[6:7], 0, s[50:51]
	s_add_i32 m0, s1, 0x1a000
	s_add_i32 s21, s1, 0x8000
	s_add_i32 s22, s1, 0xa000
	global_load_lds_dwordx4 v[6:7], off
	v_lshl_add_u64 v[4:5], v[4:5], 0, s[50:51]
	s_mov_b32 m0, s21
	s_add_u32 s8, s8, 0x80080
	global_load_lds_dwordx4 v[4:5], off
	v_lshl_add_u64 v[2:3], v[2:3], 0, s[50:51]
	s_mov_b32 m0, s22
	s_addc_u32 s9, s9, 0
	global_load_lds_dwordx4 v[2:3], off
	s_add_i32 m0, s1, 0x1c000
	v_lshl_add_u64 v[2:3], s[8:9], 0, v[144:145]
	global_load_lds_dwordx4 v[2:3], off
	v_lshl_add_u64 v[2:3], s[8:9], 0, v[128:129]
	s_add_i32 m0, s1, 0x1e000
	s_sub_i32 s9, s23, s42
	global_load_lds_dwordx4 v[2:3], off
	s_sub_i32 s9, s9, s41
	s_sext_i32_i16 s9, s9
	s_lshl_b32 s8, s40, 11
	s_lshl_b32 s9, s9, 8
	s_add_i32 s8, s8, s9
	s_ashr_i32 s9, s8, 31
	v_readlane_b32 s52, v253, 3
	s_lshl_b64 s[8:9], s[8:9], 12
	v_lshlrev_b32_e32 v2, 15, v10
	v_readlane_b32 s60, v253, 11
	v_lshlrev_b32_e32 v4, 15, v1
	v_and_b32_e32 v2, 0xffff0000, v2
	v_readlane_b32 s61, v253, 12
	s_add_u32 s8, s60, s8
	v_and_b32_e32 v4, 0xffff0000, v4
	v_lshl_add_u32 v2, v13, 12, v2
	v_and_b32_e32 v3, 1, v10
	s_addc_u32 s9, s61, s9
	v_lshl_add_u32 v4, v11, 12, v4
	v_and_b32_e32 v1, 1, v1
	s_waitcnt vmcnt(6)
	v_lshl_or_b32 v2, v3, 6, v2
	v_lshl_or_b32 v1, v1, 6, v4
	s_add_u32 s6, s29, s6
	v_lshl_add_u32 v2, v14, 1, v2
	v_mov_b32_e32 v3, v145
	v_lshl_add_u32 v4, v12, 1, v1
	v_mov_b32_e32 v5, v145
	s_addc_u32 s7, s30, s7
	v_lshl_add_u64 v[154:155], s[8:9], 0, v[2:3]
	v_lshl_add_u64 v[156:157], s[8:9], 0, v[4:5]
	v_lshl_add_u64 v[158:159], s[6:7], 0, v[2:3]
	v_lshl_add_u64 v[160:161], s[6:7], 0, v[4:5]
	s_mov_b32 s8, -2
	s_mov_b64 s[6:7], 0
	v_add_u32_e32 v139, 0, v15
	v_mov_b32_e32 v1, v0
	v_mov_b32_e32 v2, v0
	v_mov_b32_e32 v3, v0
	v_mov_b32_e32 v4, v0
	v_mov_b32_e32 v5, v0
	v_mov_b32_e32 v6, v0
	v_mov_b32_e32 v7, v0
	v_mov_b32_e32 v8, v0
	v_mov_b32_e32 v9, v0
	v_mov_b32_e32 v10, v0
	v_mov_b32_e32 v11, v0
	v_mov_b32_e32 v12, v0
	v_mov_b32_e32 v13, v0
	v_mov_b32_e32 v14, v0
	v_mov_b32_e32 v15, v0
	v_mov_b32_e32 v16, v0
	v_mov_b32_e32 v17, v0
	v_mov_b32_e32 v18, v0
	v_mov_b32_e32 v19, v0
	v_mov_b32_e32 v20, v0
	v_mov_b32_e32 v21, v0
	v_mov_b32_e32 v22, v0
	v_mov_b32_e32 v23, v0
	v_mov_b32_e32 v24, v0
	v_mov_b32_e32 v25, v0
	v_mov_b32_e32 v26, v0
	v_mov_b32_e32 v27, v0
	v_mov_b32_e32 v28, v0
	v_mov_b32_e32 v29, v0
	v_mov_b32_e32 v30, v0
	v_mov_b32_e32 v31, v0
	v_mov_b32_e32 v32, v0
	v_mov_b32_e32 v33, v0
	v_mov_b32_e32 v34, v0
	v_mov_b32_e32 v35, v0
	v_mov_b32_e32 v36, v0
	v_mov_b32_e32 v37, v0
	v_mov_b32_e32 v38, v0
	v_mov_b32_e32 v39, v0
	v_mov_b32_e32 v40, v0
	v_mov_b32_e32 v41, v0
	v_mov_b32_e32 v42, v0
	v_mov_b32_e32 v43, v0
	v_mov_b32_e32 v44, v0
	v_mov_b32_e32 v45, v0
	v_mov_b32_e32 v46, v0
	v_mov_b32_e32 v47, v0
	v_mov_b32_e32 v48, v0
	v_mov_b32_e32 v49, v0
	v_mov_b32_e32 v50, v0
	v_mov_b32_e32 v51, v0
	v_mov_b32_e32 v52, v0
	v_mov_b32_e32 v53, v0
	v_mov_b32_e32 v54, v0
	v_mov_b32_e32 v55, v0
	v_mov_b32_e32 v56, v0
	v_mov_b32_e32 v57, v0
	v_mov_b32_e32 v58, v0
	v_mov_b32_e32 v59, v0
	v_mov_b32_e32 v60, v0
	v_mov_b32_e32 v61, v0
	v_mov_b32_e32 v62, v0
	v_mov_b32_e32 v63, v0
	v_mov_b32_e32 v64, v0
	v_mov_b32_e32 v65, v0
	v_mov_b32_e32 v66, v0
	v_mov_b32_e32 v67, v0
	v_mov_b32_e32 v68, v0
	v_mov_b32_e32 v69, v0
	v_mov_b32_e32 v70, v0
	v_mov_b32_e32 v71, v0
	v_mov_b32_e32 v72, v0
	v_mov_b32_e32 v73, v0
	v_mov_b32_e32 v74, v0
	v_mov_b32_e32 v75, v0
	v_mov_b32_e32 v76, v0
	v_mov_b32_e32 v77, v0
	v_mov_b32_e32 v78, v0
	v_mov_b32_e32 v79, v0
	v_mov_b32_e32 v80, v0
	v_mov_b32_e32 v81, v0
	v_mov_b32_e32 v82, v0
	v_mov_b32_e32 v83, v0
	v_mov_b32_e32 v84, v0
	v_mov_b32_e32 v85, v0
	v_mov_b32_e32 v86, v0
	v_mov_b32_e32 v87, v0
	v_mov_b32_e32 v88, v0
	v_mov_b32_e32 v89, v0
	v_mov_b32_e32 v90, v0
	v_mov_b32_e32 v91, v0
	v_mov_b32_e32 v92, v0
	v_mov_b32_e32 v93, v0
	v_mov_b32_e32 v94, v0
	v_mov_b32_e32 v95, v0
	v_mov_b32_e32 v96, v0
	v_mov_b32_e32 v97, v0
	v_mov_b32_e32 v98, v0
	v_mov_b32_e32 v99, v0
	v_mov_b32_e32 v100, v0
	v_mov_b32_e32 v101, v0
	v_mov_b32_e32 v102, v0
	v_mov_b32_e32 v103, v0
	v_mov_b32_e32 v104, v0
	v_mov_b32_e32 v105, v0
	v_mov_b32_e32 v106, v0
	v_mov_b32_e32 v107, v0
	v_mov_b32_e32 v108, v0
	v_mov_b32_e32 v109, v0
	v_mov_b32_e32 v110, v0
	v_mov_b32_e32 v111, v0
	v_mov_b32_e32 v112, v0
	v_mov_b32_e32 v113, v0
	v_mov_b32_e32 v114, v0
	v_mov_b32_e32 v115, v0
	v_mov_b32_e32 v116, v0
	v_mov_b32_e32 v117, v0
	v_mov_b32_e32 v118, v0
	v_mov_b32_e32 v119, v0
	v_mov_b32_e32 v120, v0
	v_mov_b32_e32 v121, v0
	v_mov_b32_e32 v122, v0
	v_mov_b32_e32 v123, v0
	v_mov_b32_e32 v124, v0
	v_mov_b32_e32 v125, v0
	v_mov_b32_e32 v126, v0
	v_mov_b32_e32 v127, v0
	s_barrier
	v_readlane_b32 s53, v253, 4
	v_readlane_b32 s54, v253, 5
	v_readlane_b32 s55, v253, 6
	v_readlane_b32 s56, v253, 7
	v_readlane_b32 s57, v253, 8
	v_readlane_b32 s58, v253, 9
	v_readlane_b32 s59, v253, 10
	v_readlane_b32 s62, v253, 13
	v_readlane_b32 s63, v253, 14
	v_readlane_b32 s64, v253, 15
	v_readlane_b32 s65, v253, 16
	v_readlane_b32 s66, v253, 17
	v_readlane_b32 s67, v253, 18
	s_setprio 0
	s_bitcmp1_b32 s11, 8
	s_cbranch_scc0 .Lprio_2
	s_setprio 1
; #define G8_STAGE(bufoff, gbase, voff) do { _Pragma("unroll") for (int _i = 0; _i < 2; ++_i) \
;     __builtin_amdgcn_global_load_lds((const unsigned*)((const char*)(gbase) + (voff)[_i]), (G8_LAS unsigned*)(lds + (bufoff) + ldsw + _i * 8192), 16, 0, 0); } while (0)
; #define G8_LDA(dst, b, h) do { _Pragma("unroll") for (int m = 0; m < 4; ++m) _Pragma("unroll") for (int k = 0; k < 2; ++k) dst[m][k] = *(const G8_LAS bf16x8*)(lds + G8_OSA(b, h) + aoff + m * 2048 + k * 1024); } while (0)
; #define G8_LDB(dst, b, h) do { _Pragma("unroll") for (int n = 0; n < 2; ++n) _Pragma("unroll") for (int k = 0; k < 2; ++k) dst[n][k] = *(const G8_LAS bf16x8*)(lds + G8_OSB(b, h) + boff + n * 2048 + k * 1024); } while (0)
; #define G8_WAIT_L(n) asm volatile("s_waitcnt lgkmcnt(" #n ")" ::: "memory")
; #define G8_BAR __builtin_amdgcn_s_barrier()
; #define G8_SCHED __builtin_amdgcn_sched_barrier(0)
; __device__ __forceinline__ void gemm256(const bf* __restrict__ A, int lda, const bf* __restrict__ Bt, int ldb, int K,
;                                         int brow, int bcol, f32x4 (&acc)[2][2][4][2]) {
;     ...
;     G8_LDB(B0, 0, 0); G8_SCHED; G8_LDA(At, 0, 0); G8_STAGE(G8_OSA(1, 1), a1 + hstepA, voffA);
;     G8_WAIT_L(8); G8_BAR; G8_WAIT_L(0); G8_MMA(0, 0, At, B0); G8_BAR; G8_SCHED;
;     G8_LDB(B1, 0, 1); G8_STAGE(G8_OSB(0, 0), b2, voffB);
;     G8_BAR; G8_WAIT_L(0); G8_MMA(0, 1, At, B1); G8_BAR;
;     G8_LDA(At, 0, 1); G8_STAGE(G8_OSA(0, 0), a2, voffA);
;     G8_BAR; G8_WAIT_L(0); G8_MMA(1, 0, At, B0); G8_BAR; G8_SCHED;
.Lprio_2:
.LBB0_277:
	s_add_i32 s40, 0, 0x10000
	v_add_u32_e32 v143, s40, v141
	ds_read_b128 v[162:165], v143
	ds_read_b128 v[166:169], v143 offset:1024
	ds_read_b128 v[170:173], v143 offset:2048
	ds_read_b128 v[174:177], v143 offset:3072
	v_lshl_add_u64 v[210:211], v[154:155], 0, s[6:7]
	s_add_i32 s23, s1, 0xc000
	v_lshl_add_u64 v[212:213], v[210:211], 0, s[74:75]
	s_mov_b32 m0, s23
	ds_read_b128 v[178:181], v139
	ds_read_b128 v[182:185], v139 offset:1024
	ds_read_b128 v[186:189], v139 offset:2048
	ds_read_b128 v[190:193], v139 offset:3072
	ds_read_b128 v[194:197], v139 offset:4096
	ds_read_b128 v[214:217], v139 offset:5120
	ds_read_b128 v[218:221], v139 offset:6144
	ds_read_b128 v[222:225], v139 offset:7168
	global_load_lds_dwordx4 v[212:213], off
	v_lshl_add_u64 v[212:213], v[156:157], 0, s[6:7]
	s_add_i32 s9, s1, 0xe000
	v_lshl_add_u64 v[226:227], v[212:213], 0, s[74:75]
	s_mov_b32 m0, s9
	s_nop 0
	global_load_lds_dwordx4 v[226:227], off
	s_waitcnt lgkmcnt(8)
	s_barrier
	s_waitcnt lgkmcnt(0)
	s_waitcnt lgkmcnt(0)
	v_mfma_f32_16x16x32_bf16 v[124:127], v[162:165], v[178:181], v[124:127]
	v_mfma_f32_16x16x32_bf16 v[120:123], v[170:173], v[178:181], v[120:123]
	v_mfma_f32_16x16x32_bf16 v[116:119], v[162:165], v[186:189], v[116:119]
	v_mfma_f32_16x16x32_bf16 v[112:115], v[170:173], v[186:189], v[112:115]
	v_mfma_f32_16x16x32_bf16 v[108:111], v[162:165], v[194:197], v[108:111]
	v_mfma_f32_16x16x32_bf16 v[104:107], v[170:173], v[194:197], v[104:107]
	v_mfma_f32_16x16x32_bf16 v[100:103], v[162:165], v[218:221], v[100:103]
	v_mfma_f32_16x16x32_bf16 v[96:99], v[170:173], v[218:221], v[96:99]
	v_mfma_f32_16x16x32_bf16 v[124:127], v[166:169], v[182:185], v[124:127]
	v_mfma_f32_16x16x32_bf16 v[120:123], v[174:177], v[182:185], v[120:123]
	v_mfma_f32_16x16x32_bf16 v[116:119], v[166:169], v[190:193], v[116:119]
	v_mfma_f32_16x16x32_bf16 v[112:115], v[174:177], v[190:193], v[112:115]
	v_mfma_f32_16x16x32_bf16 v[108:111], v[166:169], v[214:217], v[108:111]
	v_mfma_f32_16x16x32_bf16 v[104:107], v[174:177], v[214:217], v[104:107]
	v_mfma_f32_16x16x32_bf16 v[100:103], v[166:169], v[222:225], v[100:103]
	v_mfma_f32_16x16x32_bf16 v[96:99], v[174:177], v[222:225], v[96:99]
	s_barrier
	s_add_i32 s41, 0, 0x14000
	v_lshl_add_u64 v[242:243], v[158:159], 0, s[6:7]
	s_add_i32 s40, s40, s18
	v_add_u32_e32 v143, s41, v141
	v_lshl_add_u64 v[244:245], v[242:243], 0, s[70:71]
	s_mov_b32 m0, s40
	ds_read_b128 v[226:229], v143
	ds_read_b128 v[230:233], v143 offset:1024
	ds_read_b128 v[234:237], v143 offset:2048
	ds_read_b128 v[238:241], v143 offset:3072
	global_load_lds_dwordx4 v[244:245], off
	v_lshl_add_u64 v[244:245], v[160:161], 0, s[6:7]
	v_lshl_add_u64 v[246:247], v[244:245], 0, s[70:71]
	s_add_i32 m0, s40, 0x2000
	s_nop 0
	global_load_lds_dwordx4 v[246:247], off
	s_barrier
	s_waitcnt lgkmcnt(0)
	s_waitcnt lgkmcnt(0)
	v_mfma_f32_16x16x32_bf16 v[92:95], v[226:229], v[178:181], v[92:95]
	v_mfma_f32_16x16x32_bf16 v[88:91], v[234:237], v[178:181], v[88:91]
	v_mfma_f32_16x16x32_bf16 v[84:87], v[226:229], v[186:189], v[84:87]
	v_mfma_f32_16x16x32_bf16 v[80:83], v[234:237], v[186:189], v[80:83]
	v_mfma_f32_16x16x32_bf16 v[76:79], v[226:229], v[194:197], v[76:79]
	v_mfma_f32_16x16x32_bf16 v[72:75], v[234:237], v[194:197], v[72:75]
	v_mfma_f32_16x16x32_bf16 v[68:71], v[226:229], v[218:221], v[68:71]
	v_mfma_f32_16x16x32_bf16 v[64:67], v[234:237], v[218:221], v[64:67]
	v_mfma_f32_16x16x32_bf16 v[92:95], v[230:233], v[182:185], v[92:95]
	v_mfma_f32_16x16x32_bf16 v[88:91], v[238:241], v[182:185], v[88:91]
	v_mfma_f32_16x16x32_bf16 v[84:87], v[230:233], v[190:193], v[84:87]
	v_mfma_f32_16x16x32_bf16 v[80:83], v[238:241], v[190:193], v[80:83]
	v_mfma_f32_16x16x32_bf16 v[76:79], v[230:233], v[214:217], v[76:79]
	v_mfma_f32_16x16x32_bf16 v[72:75], v[238:241], v[214:217], v[72:75]
	v_mfma_f32_16x16x32_bf16 v[68:71], v[230:233], v[222:225], v[68:71]
	v_mfma_f32_16x16x32_bf16 v[64:67], v[238:241], v[222:225], v[64:67]
	s_mov_b32 m0, s1
	v_lshl_add_u64 v[246:247], v[210:211], 0, s[70:71]
	s_barrier
	ds_read_b128 v[178:181], v139 offset:16384
	ds_read_b128 v[182:185], v139 offset:17408
	ds_read_b128 v[186:189], v139 offset:18432
	ds_read_b128 v[190:193], v139 offset:19456
	ds_read_b128 v[194:197], v139 offset:20480
	ds_read_b128 v[214:217], v139 offset:21504
	ds_read_b128 v[218:221], v139 offset:22528
	ds_read_b128 v[222:225], v139 offset:23552
	global_load_lds_dwordx4 v[246:247], off
	v_lshl_add_u64 v[246:247], v[212:213], 0, s[70:71]
	s_mov_b32 m0, s17
	s_nop 0
	global_load_lds_dwordx4 v[246:247], off
	s_barrier
	s_waitcnt lgkmcnt(0)
	s_waitcnt lgkmcnt(0)
	v_mfma_f32_16x16x32_bf16 v[60:63], v[162:165], v[178:181], v[60:63]
	v_mfma_f32_16x16x32_bf16 v[56:59], v[170:173], v[178:181], v[56:59]
	v_mfma_f32_16x16x32_bf16 v[52:55], v[162:165], v[186:189], v[52:55]
	v_mfma_f32_16x16x32_bf16 v[48:51], v[170:173], v[186:189], v[48:51]
	v_mfma_f32_16x16x32_bf16 v[44:47], v[162:165], v[194:197], v[44:47]
	v_mfma_f32_16x16x32_bf16 v[40:43], v[170:173], v[194:197], v[40:43]
	v_mfma_f32_16x16x32_bf16 v[36:39], v[162:165], v[218:221], v[36:39]
	v_mfma_f32_16x16x32_bf16 v[32:35], v[170:173], v[218:221], v[32:35]
	v_mfma_f32_16x16x32_bf16 v[60:63], v[166:169], v[182:185], v[60:63]
	v_mfma_f32_16x16x32_bf16 v[56:59], v[174:177], v[182:185], v[56:59]
	v_mfma_f32_16x16x32_bf16 v[52:55], v[166:169], v[190:193], v[52:55]
	v_mfma_f32_16x16x32_bf16 v[48:51], v[174:177], v[190:193], v[48:51]
	v_mfma_f32_16x16x32_bf16 v[44:47], v[166:169], v[214:217], v[44:47]
	v_mfma_f32_16x16x32_bf16 v[40:43], v[174:177], v[214:217], v[40:43]
	v_mfma_f32_16x16x32_bf16 v[36:39], v[166:169], v[222:225], v[36:39]
	v_mfma_f32_16x16x32_bf16 v[32:35], v[174:177], v[222:225], v[32:35]
	s_barrier
; #define G8_STAGE(bufoff, gbase, voff) do { _Pragma("unroll") for (int _i = 0; _i < 2; ++_i) \
;     __builtin_amdgcn_global_load_lds((const unsigned*)((const char*)(gbase) + (voff)[_i]), (G8_LAS unsigned*)(lds + (bufoff) + ldsw + _i * 8192), 16, 0, 0); } while (0)
; #define G8_LDA(dst, b, h) do { _Pragma("unroll") for (int m = 0; m < 4; ++m) _Pragma("unroll") for (int k = 0; k < 2; ++k) dst[m][k] = *(const G8_LAS bf16x8*)(lds + G8_OSA(b, h) + aoff + m * 2048 + k * 1024); } while (0)
; #define G8_LDB(dst, b, h) do { _Pragma("unroll") for (int n = 0; n < 2; ++n) _Pragma("unroll") for (int k = 0; k < 2; ++k) dst[n][k] = *(const G8_LAS bf16x8*)(lds + G8_OSB(b, h) + boff + n * 2048 + k * 1024); } while (0)
; #define G8_WAIT_V(n) asm volatile("s_waitcnt vmcnt(" #n ")" ::: "memory")
; #define G8_WAIT_L(n) asm volatile("s_waitcnt lgkmcnt(" #n ")" ::: "memory")
; #define G8_BAR __builtin_amdgcn_s_barrier()
; #define G8_SCHED __builtin_amdgcn_sched_barrier(0)
; __device__ __forceinline__ void gemm256(const bf* __restrict__ A, int lda, const bf* __restrict__ Bt, int ldb, int K,
;                                         int brow, int bcol, f32x4 (&acc)[2][2][4][2]) {
;     ...
;     G8_STAGE(G8_OSB(0, 1), b2 + hstepB, voffB);
;     G8_WAIT_V(6); G8_BAR; G8_MMA(1, 1, At, B1); G8_BAR;
;     G8_LDB(B0, 1, 0); G8_SCHED; G8_LDA(At, 1, 0); G8_STAGE(G8_OSA(0, 1), a2 + hstepA, voffA);
;     G8_WAIT_L(8); G8_BAR; G8_WAIT_L(0); G8_MMA(0, 0, At, B0); G8_BAR; G8_SCHED;
;     G8_LDB(B1, 1, 1); G8_STAGE(G8_OSB(1, 0), b3, voffB);
;     G8_BAR; G8_WAIT_L(0); G8_MMA(0, 1, At, B1); G8_BAR;
;     G8_LDA(At, 1, 1); G8_STAGE(G8_OSA(1, 0), a3, voffA);
	s_add_i32 s40, s41, s18
	v_lshl_add_u64 v[162:163], v[242:243], 0, s[76:77]
	s_mov_b32 m0, s40
	s_nop 0
	global_load_lds_dwordx4 v[162:163], off
	v_lshl_add_u64 v[162:163], v[244:245], 0, s[76:77]
	s_add_i32 m0, s40, 0x2000
	s_nop 0
	global_load_lds_dwordx4 v[162:163], off
	s_waitcnt vmcnt(6)
	s_barrier
	v_mfma_f32_16x16x32_bf16 v[28:31], v[226:229], v[178:181], v[28:31]
	v_mfma_f32_16x16x32_bf16 v[24:27], v[234:237], v[178:181], v[24:27]
	v_mfma_f32_16x16x32_bf16 v[20:23], v[226:229], v[186:189], v[20:23]
	v_mfma_f32_16x16x32_bf16 v[16:19], v[234:237], v[186:189], v[16:19]
	v_mfma_f32_16x16x32_bf16 v[12:15], v[226:229], v[194:197], v[12:15]
	v_mfma_f32_16x16x32_bf16 v[8:11], v[234:237], v[194:197], v[8:11]
	v_mfma_f32_16x16x32_bf16 v[4:7], v[226:229], v[218:221], v[4:7]
	v_mfma_f32_16x16x32_bf16 v[0:3], v[234:237], v[218:221], v[0:3]
	v_mfma_f32_16x16x32_bf16 v[28:31], v[230:233], v[182:185], v[28:31]
	v_mfma_f32_16x16x32_bf16 v[24:27], v[238:241], v[182:185], v[24:27]
	v_mfma_f32_16x16x32_bf16 v[20:23], v[230:233], v[190:193], v[20:23]
	v_mfma_f32_16x16x32_bf16 v[16:19], v[238:241], v[190:193], v[16:19]
	v_mfma_f32_16x16x32_bf16 v[12:15], v[230:233], v[214:217], v[12:15]
	v_mfma_f32_16x16x32_bf16 v[8:11], v[238:241], v[214:217], v[8:11]
	v_mfma_f32_16x16x32_bf16 v[4:7], v[230:233], v[222:225], v[4:7]
	v_mfma_f32_16x16x32_bf16 v[0:3], v[238:241], v[222:225], v[0:3]
	s_add_i32 s40, 0, 0x18000
	v_add_u32_e32 v143, s40, v141
	s_barrier
	ds_read_b128 v[162:165], v143
	ds_read_b128 v[166:169], v143 offset:1024
	ds_read_b128 v[170:173], v143 offset:2048
	ds_read_b128 v[174:177], v143 offset:3072
	s_mov_b32 m0, s19
	v_lshl_add_u64 v[226:227], v[210:211], 0, s[76:77]
	ds_read_b128 v[178:181], v139 offset:32768
	ds_read_b128 v[182:185], v139 offset:33792
	ds_read_b128 v[186:189], v139 offset:34816
	ds_read_b128 v[190:193], v139 offset:35840
	ds_read_b128 v[194:197], v139 offset:36864
	ds_read_b128 v[214:217], v139 offset:37888
	ds_read_b128 v[218:221], v139 offset:38912
	ds_read_b128 v[222:225], v139 offset:39936
	global_load_lds_dwordx4 v[226:227], off
	v_lshl_add_u64 v[226:227], v[212:213], 0, s[76:77]
	s_mov_b32 m0, s20
	s_nop 0
	global_load_lds_dwordx4 v[226:227], off
	s_waitcnt lgkmcnt(8)
	s_barrier
	s_waitcnt lgkmcnt(0)
	s_waitcnt lgkmcnt(0)
	v_mfma_f32_16x16x32_bf16 v[124:127], v[162:165], v[178:181], v[124:127]
	v_mfma_f32_16x16x32_bf16 v[120:123], v[170:173], v[178:181], v[120:123]
	v_mfma_f32_16x16x32_bf16 v[116:119], v[162:165], v[186:189], v[116:119]
	v_mfma_f32_16x16x32_bf16 v[112:115], v[170:173], v[186:189], v[112:115]
	v_mfma_f32_16x16x32_bf16 v[108:111], v[162:165], v[194:197], v[108:111]
	v_mfma_f32_16x16x32_bf16 v[104:107], v[170:173], v[194:197], v[104:107]
	v_mfma_f32_16x16x32_bf16 v[100:103], v[162:165], v[218:221], v[100:103]
	v_mfma_f32_16x16x32_bf16 v[96:99], v[170:173], v[218:221], v[96:99]
	v_mfma_f32_16x16x32_bf16 v[124:127], v[166:169], v[182:185], v[124:127]
	v_mfma_f32_16x16x32_bf16 v[120:123], v[174:177], v[182:185], v[120:123]
	v_mfma_f32_16x16x32_bf16 v[116:119], v[166:169], v[190:193], v[116:119]
	v_mfma_f32_16x16x32_bf16 v[112:115], v[174:177], v[190:193], v[112:115]
	v_mfma_f32_16x16x32_bf16 v[108:111], v[166:169], v[214:217], v[108:111]
	v_mfma_f32_16x16x32_bf16 v[104:107], v[174:177], v[214:217], v[104:107]
	v_mfma_f32_16x16x32_bf16 v[100:103], v[166:169], v[222:225], v[100:103]
	v_mfma_f32_16x16x32_bf16 v[96:99], v[174:177], v[222:225], v[96:99]
	s_barrier
	s_add_i32 s41, 0, 0x1c000
	s_add_i32 s40, s40, s18
	v_add_u32_e32 v143, s41, v141
	v_lshl_add_u64 v[246:247], v[242:243], 0, s[72:73]
	s_mov_b32 m0, s40
	ds_read_b128 v[226:229], v143
	ds_read_b128 v[230:233], v143 offset:1024
	ds_read_b128 v[234:237], v143 offset:2048
	ds_read_b128 v[238:241], v143 offset:3072
	global_load_lds_dwordx4 v[246:247], off
	v_lshl_add_u64 v[246:247], v[244:245], 0, s[72:73]
	s_add_i32 m0, s40, 0x2000
	s_nop 0
	global_load_lds_dwordx4 v[246:247], off
	s_barrier
	s_waitcnt lgkmcnt(0)
	s_waitcnt lgkmcnt(0)
	v_mfma_f32_16x16x32_bf16 v[92:95], v[226:229], v[178:181], v[92:95]
	v_mfma_f32_16x16x32_bf16 v[88:91], v[234:237], v[178:181], v[88:91]
	v_mfma_f32_16x16x32_bf16 v[84:87], v[226:229], v[186:189], v[84:87]
	v_mfma_f32_16x16x32_bf16 v[80:83], v[234:237], v[186:189], v[80:83]
	v_mfma_f32_16x16x32_bf16 v[76:79], v[226:229], v[194:197], v[76:79]
	v_mfma_f32_16x16x32_bf16 v[72:75], v[234:237], v[194:197], v[72:75]
	v_mfma_f32_16x16x32_bf16 v[68:71], v[226:229], v[218:221], v[68:71]
	v_mfma_f32_16x16x32_bf16 v[64:67], v[234:237], v[218:221], v[64:67]
	v_mfma_f32_16x16x32_bf16 v[92:95], v[230:233], v[182:185], v[92:95]
	v_mfma_f32_16x16x32_bf16 v[88:91], v[238:241], v[182:185], v[88:91]
	v_mfma_f32_16x16x32_bf16 v[84:87], v[230:233], v[190:193], v[84:87]
	v_mfma_f32_16x16x32_bf16 v[80:83], v[238:241], v[190:193], v[80:83]
	v_mfma_f32_16x16x32_bf16 v[76:79], v[230:233], v[214:217], v[76:79]
	v_mfma_f32_16x16x32_bf16 v[72:75], v[238:241], v[214:217], v[72:75]
	v_mfma_f32_16x16x32_bf16 v[68:71], v[230:233], v[222:225], v[68:71]
	v_mfma_f32_16x16x32_bf16 v[64:67], v[238:241], v[222:225], v[64:67]
	s_mov_b32 m0, s21
	v_lshl_add_u64 v[210:211], v[210:211], 0, s[72:73]
	s_barrier
	ds_read_b128 v[178:181], v139 offset:49152
	ds_read_b128 v[182:185], v139 offset:50176
	ds_read_b128 v[186:189], v139 offset:51200
	ds_read_b128 v[190:193], v139 offset:52224
	ds_read_b128 v[194:197], v139 offset:53248
	ds_read_b128 v[214:217], v139 offset:54272
	ds_read_b128 v[218:221], v139 offset:55296
	ds_read_b128 v[222:225], v139 offset:56320
	global_load_lds_dwordx4 v[210:211], off
	v_lshl_add_u64 v[210:211], v[212:213], 0, s[72:73]
	s_mov_b32 m0, s22
	s_nop 0
	global_load_lds_dwordx4 v[210:211], off
	s_barrier
; #define G8_STAGE(bufoff, gbase, voff) do { _Pragma("unroll") for (int _i = 0; _i < 2; ++_i) \
;     __builtin_amdgcn_global_load_lds((const unsigned*)((const char*)(gbase) + (voff)[_i]), (G8_LAS unsigned*)(lds + (bufoff) + ldsw + _i * 8192), 16, 0, 0); } while (0)
; #define G8_LDA(dst, b, h) do { _Pragma("unroll") for (int m = 0; m < 4; ++m) _Pragma("unroll") for (int k = 0; k < 2; ++k) dst[m][k] = *(const G8_LAS bf16x8*)(lds + G8_OSA(b, h) + aoff + m * 2048 + k * 1024); } while (0)
; #define G8_LDB(dst, b, h) do { _Pragma("unroll") for (int n = 0; n < 2; ++n) _Pragma("unroll") for (int k = 0; k < 2; ++k) dst[n][k] = *(const G8_LAS bf16x8*)(lds + G8_OSB(b, h) + boff + n * 2048 + k * 1024); } while (0)
; #define G8_WAIT_V(n) asm volatile("s_waitcnt vmcnt(" #n ")" ::: "memory")
; #define G8_WAIT_L(n) asm volatile("s_waitcnt lgkmcnt(" #n ")" ::: "memory")
; #define G8_BAR __builtin_amdgcn_s_barrier()
; #define G8_SCHED __builtin_amdgcn_sched_barrier(0)
; __device__ __forceinline__ void gemm256(const bf* __restrict__ A, int lda, const bf* __restrict__ Bt, int ldb, int K,
;                                         int brow, int bcol, f32x4 (&acc)[2][2][4][2]) {
;     ...
;     G8_BAR; G8_WAIT_L(0); G8_MMA(1, 0, At, B0); G8_BAR; G8_SCHED;
;     G8_STAGE(G8_OSB(1, 1), b3 + hstepB, voffB);
;     G8_WAIT_V(6); G8_BAR; G8_MMA(1, 1, At, B1); G8_BAR;
;   }
;   { const char* a1 = cA + (size_t)(nt - 1) * kstep;
;     G8_LDB(B0, 0, 0); G8_LDA(At, 0, 0); G8_STAGE(G8_OSA(1, 1), a1 + hstepA, voffA);
;     G8_BAR; G8_WAIT_L(0); G8_MMA(0, 0, At, B0); G8_BAR;
;     G8_LDB(B1, 0, 1); G8_BAR; G8_WAIT_L(0); G8_MMA(0, 1, At, B1); G8_BAR;
;     G8_LDA(At, 0, 1); G8_WAIT_V(4); G8_BAR; G8_WAIT_L(0); G8_MMA(1, 0, At, B0); G8_MMA(1, 1, At, B1); G8_BAR; }
	s_waitcnt lgkmcnt(0)
	s_waitcnt lgkmcnt(0)
	v_mfma_f32_16x16x32_bf16 v[60:63], v[162:165], v[178:181], v[60:63]
	v_mfma_f32_16x16x32_bf16 v[56:59], v[170:173], v[178:181], v[56:59]
	v_mfma_f32_16x16x32_bf16 v[52:55], v[162:165], v[186:189], v[52:55]
	v_mfma_f32_16x16x32_bf16 v[48:51], v[170:173], v[186:189], v[48:51]
	v_mfma_f32_16x16x32_bf16 v[44:47], v[162:165], v[194:197], v[44:47]
	v_mfma_f32_16x16x32_bf16 v[40:43], v[170:173], v[194:197], v[40:43]
	v_mfma_f32_16x16x32_bf16 v[36:39], v[162:165], v[218:221], v[36:39]
	v_mfma_f32_16x16x32_bf16 v[32:35], v[170:173], v[218:221], v[32:35]
	v_mfma_f32_16x16x32_bf16 v[60:63], v[166:169], v[182:185], v[60:63]
	v_mfma_f32_16x16x32_bf16 v[56:59], v[174:177], v[182:185], v[56:59]
	v_mfma_f32_16x16x32_bf16 v[52:55], v[166:169], v[190:193], v[52:55]
	v_mfma_f32_16x16x32_bf16 v[48:51], v[174:177], v[190:193], v[48:51]
	v_mfma_f32_16x16x32_bf16 v[44:47], v[166:169], v[214:217], v[44:47]
	v_mfma_f32_16x16x32_bf16 v[40:43], v[174:177], v[214:217], v[40:43]
	v_mfma_f32_16x16x32_bf16 v[36:39], v[166:169], v[222:225], v[36:39]
	v_mfma_f32_16x16x32_bf16 v[32:35], v[174:177], v[222:225], v[32:35]
	s_barrier
	s_add_i32 s40, s41, s18
	v_lshl_add_u64 v[162:163], v[242:243], 0, s[84:85]
	s_mov_b32 m0, s40
	s_nop 0
	global_load_lds_dwordx4 v[162:163], off
	v_lshl_add_u64 v[162:163], v[244:245], 0, s[84:85]
	s_add_i32 m0, s40, 0x2000
	s_nop 0
	global_load_lds_dwordx4 v[162:163], off
	s_waitcnt vmcnt(6)
	s_barrier
	v_mfma_f32_16x16x32_bf16 v[28:31], v[226:229], v[178:181], v[28:31]
	v_mfma_f32_16x16x32_bf16 v[24:27], v[234:237], v[178:181], v[24:27]
	v_mfma_f32_16x16x32_bf16 v[20:23], v[226:229], v[186:189], v[20:23]
	v_mfma_f32_16x16x32_bf16 v[16:19], v[234:237], v[186:189], v[16:19]
	v_mfma_f32_16x16x32_bf16 v[12:15], v[226:229], v[194:197], v[12:15]
	v_mfma_f32_16x16x32_bf16 v[8:11], v[234:237], v[194:197], v[8:11]
	v_mfma_f32_16x16x32_bf16 v[4:7], v[226:229], v[218:221], v[4:7]
	v_mfma_f32_16x16x32_bf16 v[0:3], v[234:237], v[218:221], v[0:3]
	v_mfma_f32_16x16x32_bf16 v[28:31], v[230:233], v[182:185], v[28:31]
	v_mfma_f32_16x16x32_bf16 v[24:27], v[238:241], v[182:185], v[24:27]
	v_mfma_f32_16x16x32_bf16 v[20:23], v[230:233], v[190:193], v[20:23]
	v_mfma_f32_16x16x32_bf16 v[16:19], v[238:241], v[190:193], v[16:19]
	v_mfma_f32_16x16x32_bf16 v[12:15], v[230:233], v[214:217], v[12:15]
	v_mfma_f32_16x16x32_bf16 v[8:11], v[238:241], v[214:217], v[8:11]
	v_mfma_f32_16x16x32_bf16 v[4:7], v[230:233], v[222:225], v[4:7]
	v_mfma_f32_16x16x32_bf16 v[0:3], v[238:241], v[222:225], v[0:3]
	s_add_i32 s8, s8, 2
	s_add_u32 s6, s6, 0x100
	s_addc_u32 s7, s7, 0
	s_cmp_gt_u32 s8, 27
	s_barrier
	s_cbranch_scc0 .LBB0_277
	s_add_u32 s2, s2, 0x80f80
	v_add_u32_e32 v141, 0, v141
	s_addc_u32 s3, s3, 0
	s_mov_b32 m0, s23
	v_add_u32_e32 v143, 0x10000, v141
	v_lshl_add_u64 v[210:211], s[2:3], 0, v[144:145]
	ds_read_b128 v[154:157], v143
	ds_read_b128 v[158:161], v143 offset:1024
	ds_read_b128 v[162:165], v143 offset:2048
	ds_read_b128 v[166:169], v143 offset:3072
	ds_read_b128 v[170:173], v139
	ds_read_b128 v[174:177], v139 offset:1024
	ds_read_b128 v[178:181], v139 offset:2048
	ds_read_b128 v[182:185], v139 offset:3072
	ds_read_b128 v[186:189], v139 offset:4096
	ds_read_b128 v[190:193], v139 offset:5120
	ds_read_b128 v[194:197], v139 offset:6144
	ds_read_b128 v[214:217], v139 offset:7168
	global_load_lds_dwordx4 v[210:211], off
	v_lshl_add_u64 v[128:129], s[2:3], 0, v[128:129]
	s_mov_b32 m0, s9
	s_nop 0
	global_load_lds_dwordx4 v[128:129], off
	s_barrier
	s_waitcnt lgkmcnt(0)
	s_waitcnt lgkmcnt(0)
	v_mfma_f32_16x16x32_bf16 v[124:127], v[154:157], v[170:173], v[124:127]
	v_mfma_f32_16x16x32_bf16 v[120:123], v[162:165], v[170:173], v[120:123]
	v_mfma_f32_16x16x32_bf16 v[116:119], v[154:157], v[178:181], v[116:119]
	v_mfma_f32_16x16x32_bf16 v[112:115], v[162:165], v[178:181], v[112:115]
	v_mfma_f32_16x16x32_bf16 v[100:103], v[154:157], v[194:197], v[100:103]
	v_mfma_f32_16x16x32_bf16 v[96:99], v[162:165], v[194:197], v[96:99]
	v_mfma_f32_16x16x32_bf16 v[124:127], v[158:161], v[174:177], v[124:127]
	v_mfma_f32_16x16x32_bf16 v[120:123], v[166:169], v[174:177], v[120:123]
	v_mfma_f32_16x16x32_bf16 v[116:119], v[158:161], v[182:185], v[116:119]
	v_mfma_f32_16x16x32_bf16 v[112:115], v[166:169], v[182:185], v[112:115]
	v_mfma_f32_16x16x32_bf16 v[108:111], v[154:157], v[186:189], v[108:111]
	v_mfma_f32_16x16x32_bf16 v[104:107], v[162:165], v[186:189], v[104:107]
	v_mfma_f32_16x16x32_bf16 v[100:103], v[158:161], v[214:217], v[100:103]
	v_mfma_f32_16x16x32_bf16 v[96:99], v[166:169], v[214:217], v[96:99]
	v_mfma_f32_16x16x32_bf16 v[218:221], v[158:161], v[190:193], v[108:111]
	v_mfma_f32_16x16x32_bf16 v[222:225], v[166:169], v[190:193], v[104:107]
	v_add_u32_e32 v128, 0x14000, v141
	s_barrier
	s_nop 0
	ds_read_b128 v[104:107], v128
	ds_read_b128 v[108:111], v128 offset:1024
	ds_read_b128 v[226:229], v128 offset:2048
	ds_read_b128 v[230:233], v128 offset:3072
	s_barrier
	s_waitcnt lgkmcnt(0)
	s_waitcnt lgkmcnt(0)
	v_mfma_f32_16x16x32_bf16 v[84:87], v[104:107], v[178:181], v[84:87]
	v_mfma_f32_16x16x32_bf16 v[80:83], v[226:229], v[178:181], v[80:83]
	v_mfma_f32_16x16x32_bf16 v[68:71], v[104:107], v[194:197], v[68:71]
	v_mfma_f32_16x16x32_bf16 v[64:67], v[226:229], v[194:197], v[64:67]
	v_mfma_f32_16x16x32_bf16 v[92:95], v[104:107], v[170:173], v[92:95]
	v_mfma_f32_16x16x32_bf16 v[88:91], v[226:229], v[170:173], v[88:91]
	v_mfma_f32_16x16x32_bf16 v[84:87], v[108:111], v[182:185], v[84:87]
	v_mfma_f32_16x16x32_bf16 v[80:83], v[230:233], v[182:185], v[80:83]
	v_mfma_f32_16x16x32_bf16 v[76:79], v[104:107], v[186:189], v[76:79]
	v_mfma_f32_16x16x32_bf16 v[72:75], v[226:229], v[186:189], v[72:75]
	v_mfma_f32_16x16x32_bf16 v[68:71], v[108:111], v[214:217], v[68:71]
	v_mfma_f32_16x16x32_bf16 v[64:67], v[230:233], v[214:217], v[64:67]
	v_mfma_f32_16x16x32_bf16 v[234:237], v[108:111], v[174:177], v[92:95]
	v_mfma_f32_16x16x32_bf16 v[170:173], v[230:233], v[174:177], v[88:91]
	v_mfma_f32_16x16x32_bf16 v[174:177], v[108:111], v[190:193], v[76:79]
	v_mfma_f32_16x16x32_bf16 v[178:181], v[230:233], v[190:193], v[72:75]
	s_barrier
; #define G8_LDA(dst, b, h) do { _Pragma("unroll") for (int m = 0; m < 4; ++m) _Pragma("unroll") for (int k = 0; k < 2; ++k) dst[m][k] = *(const G8_LAS bf16x8*)(lds + G8_OSA(b, h) + aoff + m * 2048 + k * 1024); } while (0)
; #define G8_LDB(dst, b, h) do { _Pragma("unroll") for (int n = 0; n < 2; ++n) _Pragma("unroll") for (int k = 0; k < 2; ++k) dst[n][k] = *(const G8_LAS bf16x8*)(lds + G8_OSB(b, h) + boff + n * 2048 + k * 1024); } while (0)
; #define G8_WAIT_V(n) asm volatile("s_waitcnt vmcnt(" #n ")" ::: "memory")
; #define G8_WAIT_L(n) asm volatile("s_waitcnt lgkmcnt(" #n ")" ::: "memory")
; #define G8_BAR __builtin_amdgcn_s_barrier()
; __device__ __forceinline__ void gemm256(const bf* __restrict__ A, int lda, const bf* __restrict__ Bt, int ldb, int K,
;                                         int brow, int bcol, f32x4 (&acc)[2][2][4][2]) {
;     ...
;     G8_LDA(At, 0, 1); G8_WAIT_V(4); G8_BAR; G8_WAIT_L(0); G8_MMA(1, 0, At, B0); G8_MMA(1, 1, At, B1); G8_BAR; }
;   { G8_LDB(B0, 1, 0); G8_LDA(At, 1, 0); G8_WAIT_V(2); G8_BAR; G8_WAIT_L(0); G8_MMA(0, 0, At, B0); G8_BAR;
;     G8_LDB(B1, 1, 1); G8_WAIT_V(0); G8_BAR; G8_WAIT_L(0); G8_MMA(0, 1, At, B1); G8_BAR;
	s_nop 0
	ds_read_b128 v[72:75], v139 offset:16384
	ds_read_b128 v[76:79], v139 offset:17408
	ds_read_b128 v[88:91], v139 offset:18432
	ds_read_b128 v[92:95], v139 offset:19456
	ds_read_b128 v[182:185], v139 offset:20480
	ds_read_b128 v[186:189], v139 offset:21504
	ds_read_b128 v[190:193], v139 offset:22528
	ds_read_b128 v[194:197], v139 offset:23552
	s_waitcnt vmcnt(4)
	s_barrier
	s_waitcnt lgkmcnt(0)
	s_waitcnt lgkmcnt(0)
	v_mfma_f32_16x16x32_bf16 v[60:63], v[154:157], v[72:75], v[60:63]
	v_mfma_f32_16x16x32_bf16 v[56:59], v[162:165], v[72:75], v[56:59]
	v_mfma_f32_16x16x32_bf16 v[52:55], v[154:157], v[88:91], v[52:55]
	v_mfma_f32_16x16x32_bf16 v[48:51], v[162:165], v[88:91], v[48:51]
	v_mfma_f32_16x16x32_bf16 v[36:39], v[154:157], v[190:193], v[36:39]
	v_mfma_f32_16x16x32_bf16 v[32:35], v[162:165], v[190:193], v[32:35]
	v_mfma_f32_16x16x32_bf16 v[60:63], v[158:161], v[76:79], v[60:63]
	v_mfma_f32_16x16x32_bf16 v[56:59], v[166:169], v[76:79], v[56:59]
	v_mfma_f32_16x16x32_bf16 v[52:55], v[158:161], v[92:95], v[52:55]
	v_mfma_f32_16x16x32_bf16 v[48:51], v[166:169], v[92:95], v[48:51]
	v_mfma_f32_16x16x32_bf16 v[44:47], v[154:157], v[182:185], v[44:47]
	v_mfma_f32_16x16x32_bf16 v[40:43], v[162:165], v[182:185], v[40:43]
	v_mfma_f32_16x16x32_bf16 v[36:39], v[158:161], v[194:197], v[36:39]
	v_mfma_f32_16x16x32_bf16 v[32:35], v[166:169], v[194:197], v[32:35]
	v_mfma_f32_16x16x32_bf16 v[214:217], v[158:161], v[186:189], v[44:47]
	v_mfma_f32_16x16x32_bf16 v[238:241], v[166:169], v[186:189], v[40:43]
	v_mfma_f32_16x16x32_bf16 v[20:23], v[104:107], v[88:91], v[20:23]
	v_mfma_f32_16x16x32_bf16 v[16:19], v[226:229], v[88:91], v[16:19]
	v_mfma_f32_16x16x32_bf16 v[4:7], v[104:107], v[190:193], v[4:7]
	v_mfma_f32_16x16x32_bf16 v[0:3], v[226:229], v[190:193], v[0:3]
	v_mfma_f32_16x16x32_bf16 v[28:31], v[104:107], v[72:75], v[28:31]
	v_mfma_f32_16x16x32_bf16 v[24:27], v[226:229], v[72:75], v[24:27]
	v_mfma_f32_16x16x32_bf16 v[20:23], v[108:111], v[92:95], v[20:23]
	v_mfma_f32_16x16x32_bf16 v[16:19], v[230:233], v[92:95], v[16:19]
	v_mfma_f32_16x16x32_bf16 v[12:15], v[104:107], v[182:185], v[12:15]
	v_mfma_f32_16x16x32_bf16 v[8:11], v[226:229], v[182:185], v[8:11]
	v_mfma_f32_16x16x32_bf16 v[4:7], v[108:111], v[194:197], v[4:7]
	v_mfma_f32_16x16x32_bf16 v[0:3], v[230:233], v[194:197], v[0:3]
	v_mfma_f32_16x16x32_bf16 v[154:157], v[108:111], v[76:79], v[28:31]
	v_mfma_f32_16x16x32_bf16 v[158:161], v[230:233], v[76:79], v[24:27]
	v_mfma_f32_16x16x32_bf16 v[162:165], v[108:111], v[186:189], v[12:15]
	v_mfma_f32_16x16x32_bf16 v[166:169], v[230:233], v[186:189], v[8:11]
	v_add_u32_e32 v24, 0x18000, v141
	s_barrier
	ds_read_b128 v[8:11], v24
	ds_read_b128 v[12:15], v24 offset:1024
	ds_read_b128 v[182:185], v24 offset:2048
	ds_read_b128 v[186:189], v24 offset:3072
	ds_read_b128 v[24:27], v139 offset:32768
	ds_read_b128 v[28:31], v139 offset:33792
	ds_read_b128 v[40:43], v139 offset:34816
	ds_read_b128 v[44:47], v139 offset:35840
	ds_read_b128 v[190:193], v139 offset:36864
	ds_read_b128 v[194:197], v139 offset:37888
	ds_read_b128 v[226:229], v139 offset:38912
	ds_read_b128 v[230:233], v139 offset:39936
	s_waitcnt vmcnt(2)
	s_barrier
	s_waitcnt lgkmcnt(0)
	s_waitcnt lgkmcnt(0)
	v_mfma_f32_16x16x32_bf16 v[72:75], v[8:11], v[24:27], v[124:127]
	v_mfma_f32_16x16x32_bf16 v[124:127], v[12:15], v[28:31], v[72:75]
	v_mfma_f32_16x16x32_bf16 v[72:75], v[182:185], v[24:27], v[120:123]
	v_mfma_f32_16x16x32_bf16 v[120:123], v[186:189], v[28:31], v[72:75]
	v_mfma_f32_16x16x32_bf16 v[72:75], v[8:11], v[40:43], v[116:119]
	v_mfma_f32_16x16x32_bf16 v[108:111], v[12:15], v[44:47], v[72:75]
	v_mfma_f32_16x16x32_bf16 v[72:75], v[182:185], v[40:43], v[112:115]
	v_mfma_f32_16x16x32_bf16 v[104:107], v[186:189], v[44:47], v[72:75]
	v_mfma_f32_16x16x32_bf16 v[72:75], v[8:11], v[190:193], v[218:221]
	v_mfma_f32_16x16x32_bf16 v[92:95], v[12:15], v[194:197], v[72:75]
	v_mfma_f32_16x16x32_bf16 v[72:75], v[182:185], v[190:193], v[222:225]
	v_mfma_f32_16x16x32_bf16 v[88:91], v[186:189], v[194:197], v[72:75]
	v_mfma_f32_16x16x32_bf16 v[72:75], v[8:11], v[226:229], v[100:103]
	v_mfma_f32_16x16x32_bf16 v[76:79], v[12:15], v[230:233], v[72:75]
	v_mfma_f32_16x16x32_bf16 v[72:75], v[182:185], v[226:229], v[96:99]
	v_mfma_f32_16x16x32_bf16 v[72:75], v[186:189], v[230:233], v[72:75]
	s_nop 0
	v_add_u32_e32 v96, 0x1c000, v141
	s_barrier
; #define G8_LDA(dst, b, h) do { _Pragma("unroll") for (int m = 0; m < 4; ++m) _Pragma("unroll") for (int k = 0; k < 2; ++k) dst[m][k] = *(const G8_LAS bf16x8*)(lds + G8_OSA(b, h) + aoff + m * 2048 + k * 1024); } while (0)
; #define G8_LDB(dst, b, h) do { _Pragma("unroll") for (int n = 0; n < 2; ++n) _Pragma("unroll") for (int k = 0; k < 2; ++k) dst[n][k] = *(const G8_LAS bf16x8*)(lds + G8_OSB(b, h) + boff + n * 2048 + k * 1024); } while (0)
; #define G8_WAIT_V(n) asm volatile("s_waitcnt vmcnt(" #n ")" ::: "memory")
; #define G8_WAIT_L(n) asm volatile("s_waitcnt lgkmcnt(" #n ")" ::: "memory")
; #define G8_BAR __builtin_amdgcn_s_barrier()
; __device__ __forceinline__ void gemm256(const bf* __restrict__ A, int lda, const bf* __restrict__ Bt, int ldb, int K,
;                                         int brow, int bcol, f32x4 (&acc)[2][2][4][2]) {
;     ...
;   { G8_LDB(B0, 1, 0); G8_LDA(At, 1, 0); G8_WAIT_V(2); G8_BAR; G8_WAIT_L(0); G8_MMA(0, 0, At, B0); G8_BAR;
;     G8_LDB(B1, 1, 1); G8_WAIT_V(0); G8_BAR; G8_WAIT_L(0); G8_MMA(0, 1, At, B1); G8_BAR;
;     G8_LDA(At, 1, 1); G8_BAR; G8_WAIT_L(0); G8_MMA(1, 0, At, B0); G8_MMA(1, 1, At, B1); G8_BAR; }
;   if (wr == 0) G8_BAR;
	ds_read_b128 v[218:221], v96
	ds_read_b128 v[222:225], v96 offset:1024
	ds_read_b128 v[242:245], v96 offset:2048
	ds_read_b128 v[246:249], v96 offset:3072
	s_waitcnt vmcnt(0)
	s_barrier
	s_waitcnt lgkmcnt(0)
	s_waitcnt lgkmcnt(0)
	v_mfma_f32_16x16x32_bf16 v[96:99], v[218:221], v[24:27], v[234:237]
	v_mfma_f32_16x16x32_bf16 v[24:27], v[242:245], v[24:27], v[170:173]
	v_mfma_f32_16x16x32_bf16 v[112:115], v[246:249], v[28:31], v[24:27]
	v_mfma_f32_16x16x32_bf16 v[24:27], v[218:221], v[40:43], v[84:87]
	v_mfma_f32_16x16x32_bf16 v[100:103], v[222:225], v[44:47], v[24:27]
	v_mfma_f32_16x16x32_bf16 v[24:27], v[242:245], v[40:43], v[80:83]
	v_mfma_f32_16x16x32_bf16 v[116:119], v[222:225], v[28:31], v[96:99]
	v_mfma_f32_16x16x32_bf16 v[96:99], v[246:249], v[44:47], v[24:27]
	v_mfma_f32_16x16x32_bf16 v[24:27], v[218:221], v[190:193], v[174:177]
	v_mfma_f32_16x16x32_bf16 v[84:87], v[222:225], v[194:197], v[24:27]
	v_mfma_f32_16x16x32_bf16 v[24:27], v[242:245], v[190:193], v[178:181]
	v_mfma_f32_16x16x32_bf16 v[80:83], v[246:249], v[194:197], v[24:27]
	v_mfma_f32_16x16x32_bf16 v[24:27], v[218:221], v[226:229], v[68:71]
	v_mfma_f32_16x16x32_bf16 v[68:71], v[222:225], v[230:233], v[24:27]
	v_mfma_f32_16x16x32_bf16 v[24:27], v[242:245], v[226:229], v[64:67]
	v_mfma_f32_16x16x32_bf16 v[64:67], v[246:249], v[230:233], v[24:27]
	s_barrier
	ds_read_b128 v[170:173], v139 offset:49152
	ds_read_b128 v[174:177], v139 offset:50176
	ds_read_b128 v[178:181], v139 offset:51200
	ds_read_b128 v[190:193], v139 offset:52224
	ds_read_b128 v[194:197], v139 offset:53248
	ds_read_b128 v[226:229], v139 offset:54272
	ds_read_b128 v[230:233], v139 offset:55296
	ds_read_b128 v[234:237], v139 offset:56320
	s_barrier
	s_waitcnt lgkmcnt(0)
	s_waitcnt lgkmcnt(0)
	v_mfma_f32_16x16x32_bf16 v[24:27], v[8:11], v[170:173], v[60:63]
	v_mfma_f32_16x16x32_bf16 v[60:63], v[12:15], v[174:177], v[24:27]
	v_mfma_f32_16x16x32_bf16 v[24:27], v[182:185], v[170:173], v[56:59]
	v_mfma_f32_16x16x32_bf16 v[56:59], v[186:189], v[174:177], v[24:27]
	v_mfma_f32_16x16x32_bf16 v[24:27], v[8:11], v[178:181], v[52:55]
	v_mfma_f32_16x16x32_bf16 v[44:47], v[12:15], v[190:193], v[24:27]
	v_mfma_f32_16x16x32_bf16 v[24:27], v[182:185], v[178:181], v[48:51]
	v_mfma_f32_16x16x32_bf16 v[40:43], v[186:189], v[190:193], v[24:27]
	v_mfma_f32_16x16x32_bf16 v[24:27], v[8:11], v[194:197], v[214:217]
	v_mfma_f32_16x16x32_bf16 v[8:11], v[8:11], v[230:233], v[36:39]
	v_mfma_f32_16x16x32_bf16 v[28:31], v[12:15], v[226:229], v[24:27]
	v_mfma_f32_16x16x32_bf16 v[24:27], v[182:185], v[194:197], v[238:241]
	v_mfma_f32_16x16x32_bf16 v[12:15], v[12:15], v[234:237], v[8:11]
	v_mfma_f32_16x16x32_bf16 v[8:11], v[182:185], v[230:233], v[32:35]
	v_mfma_f32_16x16x32_bf16 v[24:27], v[186:189], v[226:229], v[24:27]
	v_mfma_f32_16x16x32_bf16 v[8:11], v[186:189], v[234:237], v[8:11]
	v_mfma_f32_16x16x32_bf16 v[32:35], v[218:221], v[170:173], v[154:157]
	v_mfma_f32_16x16x32_bf16 v[52:55], v[222:225], v[174:177], v[32:35]
	v_mfma_f32_16x16x32_bf16 v[32:35], v[242:245], v[170:173], v[158:161]
	v_mfma_f32_16x16x32_bf16 v[16:19], v[242:245], v[178:181], v[16:19]
	v_mfma_f32_16x16x32_bf16 v[48:51], v[246:249], v[174:177], v[32:35]
	v_mfma_f32_16x16x32_bf16 v[20:23], v[218:221], v[178:181], v[20:23]
	v_mfma_f32_16x16x32_bf16 v[32:35], v[246:249], v[190:193], v[16:19]
	v_mfma_f32_16x16x32_bf16 v[16:19], v[218:221], v[194:197], v[162:165]
	v_mfma_f32_16x16x32_bf16 v[36:39], v[222:225], v[190:193], v[20:23]
	v_mfma_f32_16x16x32_bf16 v[20:23], v[222:225], v[226:229], v[16:19]
	v_mfma_f32_16x16x32_bf16 v[16:19], v[242:245], v[194:197], v[166:169]
	v_mfma_f32_16x16x32_bf16 v[4:7], v[218:221], v[230:233], v[4:7]
	v_mfma_f32_16x16x32_bf16 v[0:3], v[242:245], v[230:233], v[0:3]
	v_mfma_f32_16x16x32_bf16 v[16:19], v[246:249], v[226:229], v[16:19]
	v_mfma_f32_16x16x32_bf16 v[4:7], v[222:225], v[234:237], v[4:7]
	v_mfma_f32_16x16x32_bf16 v[0:3], v[246:249], v[234:237], v[0:3]
	s_setprio 0
	s_cmpk_lt_u32 s11, 0x100
	s_barrier
	s_cbranch_scc0 .LBB0_280
	s_barrier

; #define G8_STAGE(bufoff, gbase, voff) do { _Pragma("unroll") for (int _i = 0; _i < 2; ++_i) \
;     __builtin_amdgcn_global_load_lds((const unsigned*)((const char*)(gbase) + (voff)[_i]), (G8_LAS unsigned*)(lds + (bufoff) + ldsw + _i * 8192), 16, 0, 0); } while (0)
; #define G8_WAIT_V(n) asm volatile("s_waitcnt vmcnt(" #n ")" ::: "memory")
; #define G8_BAR __builtin_amdgcn_s_barrier()
; #define ZERO_ACC8(a) { float z_ = 0.f; asm volatile("" : "+v"(z_)); _Pragma("unroll") for (int i_ = 0; i_ < 2; i_++) _Pragma("unroll") for (int j_ = 0; j_ < 2; j_++) _Pragma("unroll") for (int m_ = 0; m_ < 4; m_++) _Pragma("unroll") for (int n_ = 0; n_ < 2; n_++) a[i_][j_][m_][n_] = (f32x4){z_, z_, z_, z_}; }
; __device__ __forceinline__ void gemm256(const bf* __restrict__ A, int lda, const bf* __restrict__ Bt, int ldb, int K,
;                                         int brow, int bcol, f32x4 (&acc)[2][2][4][2]) {
;     ...
;   __syncthreads();
;   G8_STAGE(G8_OSB(0, 0), cB, voffB); G8_STAGE(G8_OSA(0, 0), cA, voffA); G8_STAGE(G8_OSB(0, 1), cB + hstepB, voffB); G8_STAGE(G8_OSA(0, 1), cA + hstepA, voffA);
;   if (wr == 1) G8_BAR;
;   G8_WAIT_V(4); G8_BAR;
;   G8_STAGE(G8_OSB(1, 0), cB + kstep, voffB); G8_STAGE(G8_OSA(1, 0), cA + kstep, voffA); G8_STAGE(G8_OSB(1, 1), cB + hstepB + kstep, voffB);
;   G8_WAIT_V(6); G8_BAR;
; __device__ __forceinline__ void phaseE(const Params& p, int layer) {
;     ...
;       const int br = s >> 1; const bool isBr = (s & 1) != 0;
;       const int koff = br == 0 ? 0 : (br == 1 ? 512 : (br == 2 ? 1024 : 2048));
;       const int kb = br == 2 ? 1024 : (br == 3 ? 256 : 512);
;       const bf* A_ = isBr ? p.Y + koff : p.xb; const int lda_ = isBr ? YW : 2048;
;       const bf* B_ = isBr ? Wb + koff : Wl + (size_t)(5716 + br * 2048) * 2048; const int ldb_ = isBr ? YW : 2048;
;       const int K_ = isBr ? kb : 2048;
;       f32x4 acc[2][2][4][2]; ZERO_ACC8(acc);
;       gemm256(A_, lda_, B_, ldb_, K_, brow, bcol, acc);
.LBB0_2317:
	s_cmp_eq_u32 s5, 3
	s_cselect_b32 s78, 4, 8
	s_and_b64 s[16:17], s[16:17], exec
	s_cselect_b32 s78, 16, s78
	s_and_b64 s[16:17], s[18:19], exec
	s_cselect_b32 s18, 32, s78
	s_add_i32 m0, s41, 0x18000
	v_lshl_add_u64 v[2:3], v[2:3], 0, s[50:51]
	s_waitcnt vmcnt(4)
	s_barrier
	global_load_lds_dwordx4 v[2:3], off
	v_lshl_add_u64 v[2:3], v[4:5], 0, s[50:51]
	s_add_i32 m0, s41, 0x1a000
	s_add_i32 s19, s41, 0x8000
	s_lshl_b32 s17, s46, 13
	global_load_lds_dwordx4 v[2:3], off
	v_lshl_add_u64 v[2:3], v[6:7], 0, s[50:51]
	s_mov_b32 m0, s19
	s_add_i32 s46, s41, 0xa000
	global_load_lds_dwordx4 v[2:3], off
	v_lshl_add_u64 v[2:3], v[8:9], 0, s[50:51]
	s_mov_b32 m0, s46
	v_and_b32_e32 v20, 15, v17
	global_load_lds_dwordx4 v[2:3], off
	s_add_i32 m0, s41, 0x1c000
	v_lshl_add_u64 v[2:3], v[10:11], 0, s[50:51]
	global_load_lds_dwordx4 v[2:3], off
	v_lshl_add_u64 v[2:3], v[12:13], 0, s[50:51]
	s_add_i32 m0, s41, 0x1e000
	v_and_b32_e32 v21, 48, v17
	global_load_lds_dwordx4 v[2:3], off
	v_lshlrev_b32_e32 v17, 2, v17
	v_lshlrev_b32_e32 v20, 6, v20
	v_and_b32_e32 v17, 32, v17
	s_lshl_b32 s16, s47, 12
	v_or_b32_e32 v22, v20, v21
	v_bitop3_b32 v20, v20, v17, v21 bitop3:0x36
	s_and_b32 s16, s16, 0x3000
	v_or_b32_e32 v157, s16, v20
	v_bitop3_b32 v17, v22, s17, v17 bitop3:0xde
	s_mul_i32 s16, s9, s49
	s_mul_hi_u32 s17, s8, s49
	s_add_i32 s47, s18, -2
	s_add_i32 s17, s17, s16
	s_mul_i32 s16, s8, s49
	v_add_u32_e32 v1, v15, v1
	v_add_lshl_u32 v2, v1, v14, 1
	s_add_u32 s16, s75, s16
	v_add_u32_e32 v1, v19, v16
	v_mov_b32_e32 v3, v145
	s_addc_u32 s17, s74, s17
	v_add_lshl_u32 v4, v1, v18, 1
	v_mov_b32_e32 v5, v145
	v_lshl_add_u64 v[130:131], s[16:17], 0, v[2:3]
	v_lshl_add_u64 v[132:133], s[16:17], 0, v[4:5]
	s_mul_i32 s16, s38, s49
	s_mul_hi_u32 s17, s37, s49
	s_add_i32 s17, s17, s16
	s_mul_i32 s16, s37, s49
	s_add_u32 s16, s75, s16
	s_addc_u32 s17, s74, s17
	v_lshl_add_u64 v[134:135], s[16:17], 0, v[2:3]
	v_lshl_add_u64 v[136:137], s[16:17], 0, v[4:5]
	s_add_u32 s16, s68, s77
	s_addc_u32 s17, s48, s76
	v_lshl_add_u64 v[138:139], s[16:17], 0, v[2:3]
	v_lshl_add_u64 v[140:141], s[16:17], 0, v[4:5]
	s_mul_i32 s16, s11, s49
	s_mul_hi_u32 s17, s10, s49
	s_add_i32 s17, s17, s16
	s_mul_i32 s16, s10, s49
	s_waitcnt vmcnt(6)
	s_add_u32 s16, s68, s16
	s_addc_u32 s17, s48, s17
	v_lshl_add_u64 v[142:143], s[16:17], 0, v[2:3]
	v_lshl_add_u64 v[154:155], s[16:17], 0, v[4:5]
	s_mov_b32 s48, 0
	s_mov_b64 s[16:17], 0
	v_add_u32_e32 v156, 0, v17
	v_mov_b32_e32 v1, v0
	v_mov_b32_e32 v2, v0
	v_mov_b32_e32 v3, v0
	v_mov_b32_e32 v4, v0
	v_mov_b32_e32 v5, v0
	v_mov_b32_e32 v6, v0
	v_mov_b32_e32 v7, v0
	v_mov_b32_e32 v8, v0
	v_mov_b32_e32 v9, v0
	v_mov_b32_e32 v10, v0
	v_mov_b32_e32 v11, v0
	v_mov_b32_e32 v12, v0
	v_mov_b32_e32 v13, v0
	v_mov_b32_e32 v14, v0
	v_mov_b32_e32 v15, v0
	v_mov_b32_e32 v16, v0
	v_mov_b32_e32 v17, v0
	v_mov_b32_e32 v18, v0
	v_mov_b32_e32 v19, v0
	v_mov_b32_e32 v20, v0
	v_mov_b32_e32 v21, v0
	v_mov_b32_e32 v22, v0
	v_mov_b32_e32 v23, v0
	v_mov_b32_e32 v24, v0
	v_mov_b32_e32 v25, v0
	v_mov_b32_e32 v26, v0
	v_mov_b32_e32 v27, v0
	v_mov_b32_e32 v28, v0
	v_mov_b32_e32 v29, v0
	v_mov_b32_e32 v30, v0
	v_mov_b32_e32 v31, v0
	v_mov_b32_e32 v32, v0
	v_mov_b32_e32 v33, v0
	v_mov_b32_e32 v34, v0
	v_mov_b32_e32 v35, v0
	v_mov_b32_e32 v36, v0
	v_mov_b32_e32 v37, v0
	v_mov_b32_e32 v38, v0
	v_mov_b32_e32 v39, v0
	v_mov_b32_e32 v40, v0
	v_mov_b32_e32 v41, v0
	v_mov_b32_e32 v42, v0
	v_mov_b32_e32 v43, v0
	v_mov_b32_e32 v44, v0
	v_mov_b32_e32 v45, v0
	v_mov_b32_e32 v46, v0
	v_mov_b32_e32 v47, v0
	v_mov_b32_e32 v48, v0
	v_mov_b32_e32 v49, v0
	v_mov_b32_e32 v50, v0
	v_mov_b32_e32 v51, v0
	v_mov_b32_e32 v52, v0
	v_mov_b32_e32 v53, v0
	v_mov_b32_e32 v54, v0
	v_mov_b32_e32 v55, v0
	v_mov_b32_e32 v56, v0
	v_mov_b32_e32 v57, v0
	v_mov_b32_e32 v58, v0
	v_mov_b32_e32 v59, v0
	v_mov_b32_e32 v60, v0
	v_mov_b32_e32 v61, v0
	v_mov_b32_e32 v62, v0
	v_mov_b32_e32 v63, v0
	v_mov_b32_e32 v64, v0
	v_mov_b32_e32 v65, v0
	v_mov_b32_e32 v66, v0
	v_mov_b32_e32 v67, v0
	v_mov_b32_e32 v68, v0
	v_mov_b32_e32 v69, v0
	v_mov_b32_e32 v70, v0
	v_mov_b32_e32 v71, v0
	v_mov_b32_e32 v72, v0
	v_mov_b32_e32 v73, v0
	v_mov_b32_e32 v74, v0
	v_mov_b32_e32 v75, v0
	v_mov_b32_e32 v76, v0
	v_mov_b32_e32 v77, v0
	v_mov_b32_e32 v78, v0
	v_mov_b32_e32 v79, v0
	v_mov_b32_e32 v80, v0
	v_mov_b32_e32 v81, v0
	v_mov_b32_e32 v82, v0
	v_mov_b32_e32 v83, v0
	v_mov_b32_e32 v84, v0
	v_mov_b32_e32 v85, v0
	v_mov_b32_e32 v86, v0
	v_mov_b32_e32 v87, v0
	v_mov_b32_e32 v88, v0
	v_mov_b32_e32 v89, v0
	v_mov_b32_e32 v90, v0
	v_mov_b32_e32 v91, v0
	v_mov_b32_e32 v92, v0
	v_mov_b32_e32 v93, v0
	v_mov_b32_e32 v94, v0
	v_mov_b32_e32 v95, v0
	v_mov_b32_e32 v96, v0
	v_mov_b32_e32 v97, v0
	v_mov_b32_e32 v98, v0
	v_mov_b32_e32 v99, v0
	v_mov_b32_e32 v100, v0
	v_mov_b32_e32 v101, v0
	v_mov_b32_e32 v102, v0
	v_mov_b32_e32 v103, v0
	v_mov_b32_e32 v104, v0
	v_mov_b32_e32 v105, v0
	v_mov_b32_e32 v106, v0
	v_mov_b32_e32 v107, v0
	v_mov_b32_e32 v108, v0
	v_mov_b32_e32 v109, v0
	v_mov_b32_e32 v110, v0
	v_mov_b32_e32 v111, v0
	v_mov_b32_e32 v112, v0
	v_mov_b32_e32 v113, v0
	v_mov_b32_e32 v114, v0
	v_mov_b32_e32 v115, v0
	v_mov_b32_e32 v116, v0
	v_mov_b32_e32 v117, v0
	v_mov_b32_e32 v118, v0
	v_mov_b32_e32 v119, v0
	v_mov_b32_e32 v120, v0
	v_mov_b32_e32 v121, v0
	v_mov_b32_e32 v122, v0
	v_mov_b32_e32 v123, v0
	v_mov_b32_e32 v124, v0
	v_mov_b32_e32 v125, v0
	v_mov_b32_e32 v126, v0
	v_mov_b32_e32 v127, v0
	s_barrier
	s_setprio 0
	s_bitcmp1_b32 s39, 8
	s_cbranch_scc0 .Lprio_1
	s_setprio 1
; #define G8_STAGE(bufoff, gbase, voff) do { _Pragma("unroll") for (int _i = 0; _i < 2; ++_i) \
;     __builtin_amdgcn_global_load_lds((const unsigned*)((const char*)(gbase) + (voff)[_i]), (G8_LAS unsigned*)(lds + (bufoff) + ldsw + _i * 8192), 16, 0, 0); } while (0)
; #define G8_LDA(dst, b, h) do { _Pragma("unroll") for (int m = 0; m < 4; ++m) _Pragma("unroll") for (int k = 0; k < 2; ++k) dst[m][k] = *(const G8_LAS bf16x8*)(lds + G8_OSA(b, h) + aoff + m * 2048 + k * 1024); } while (0)
; #define G8_LDB(dst, b, h) do { _Pragma("unroll") for (int n = 0; n < 2; ++n) _Pragma("unroll") for (int k = 0; k < 2; ++k) dst[n][k] = *(const G8_LAS bf16x8*)(lds + G8_OSB(b, h) + boff + n * 2048 + k * 1024); } while (0)
; #define G8_WAIT_L(n) asm volatile("s_waitcnt lgkmcnt(" #n ")" ::: "memory")
; #define G8_BAR __builtin_amdgcn_s_barrier()
; #define G8_SCHED __builtin_amdgcn_sched_barrier(0)
; __device__ __forceinline__ void gemm256(const bf* __restrict__ A, int lda, const bf* __restrict__ Bt, int ldb, int K,
;                                         int brow, int bcol, f32x4 (&acc)[2][2][4][2]) {
;     ...
;     G8_LDB(B0, 0, 0); G8_SCHED; G8_LDA(At, 0, 0); G8_STAGE(G8_OSA(1, 1), a1 + hstepA, voffA);
;     G8_WAIT_L(8); G8_BAR; G8_WAIT_L(0); G8_MMA(0, 0, At, B0); G8_BAR; G8_SCHED;
;     G8_LDB(B1, 0, 1); G8_STAGE(G8_OSB(0, 0), b2, voffB);
;     G8_BAR; G8_WAIT_L(0); G8_MMA(0, 1, At, B1); G8_BAR;
;     G8_LDA(At, 0, 1); G8_STAGE(G8_OSA(0, 0), a2, voffA);
;     G8_BAR; G8_WAIT_L(0); G8_MMA(1, 0, At, B0); G8_BAR; G8_SCHED;
.Lprio_1:
.LBB0_2318:
	s_add_i32 s74, 0, 0x10000
	v_add_u32_e32 v158, s74, v157
	ds_read_b128 v[164:167], v158
	ds_read_b128 v[168:171], v158 offset:1024
	ds_read_b128 v[172:175], v158 offset:2048
	ds_read_b128 v[176:179], v158 offset:3072
	s_add_i32 s48, s48, 2
	v_lshl_add_u64 v[158:159], v[134:135], 0, s[16:17]
	s_add_i32 s68, s41, 0xc000
	v_lshl_add_u64 v[196:197], v[158:159], 0, s[50:51]
	s_mov_b32 m0, s68
	ds_read_b128 v[180:183], v156
	ds_read_b128 v[184:187], v156 offset:1024
	ds_read_b128 v[188:191], v156 offset:2048
	ds_read_b128 v[192:195], v156 offset:3072
	ds_read_b128 v[210:213], v156 offset:4096
	ds_read_b128 v[214:217], v156 offset:5120
	ds_read_b128 v[218:221], v156 offset:6144
	ds_read_b128 v[222:225], v156 offset:7168
	global_load_lds_dwordx4 v[196:197], off
	v_lshl_add_u64 v[196:197], v[136:137], 0, s[16:17]
	s_add_i32 s49, s41, 0xe000
	v_lshl_add_u64 v[198:199], v[196:197], 0, s[50:51]
	s_mov_b32 m0, s49
	s_nop 0
	global_load_lds_dwordx4 v[198:199], off
	s_waitcnt lgkmcnt(8)
	s_barrier
	s_waitcnt lgkmcnt(0)
	s_waitcnt lgkmcnt(0)
	v_mfma_f32_16x16x32_bf16 v[124:127], v[164:167], v[180:183], v[124:127]
	v_mfma_f32_16x16x32_bf16 v[120:123], v[172:175], v[180:183], v[120:123]
	v_mfma_f32_16x16x32_bf16 v[116:119], v[164:167], v[188:191], v[116:119]
	v_mfma_f32_16x16x32_bf16 v[112:115], v[172:175], v[188:191], v[112:115]
	v_mfma_f32_16x16x32_bf16 v[108:111], v[164:167], v[210:213], v[108:111]
	v_mfma_f32_16x16x32_bf16 v[104:107], v[172:175], v[210:213], v[104:107]
	v_mfma_f32_16x16x32_bf16 v[100:103], v[164:167], v[218:221], v[100:103]
	v_mfma_f32_16x16x32_bf16 v[96:99], v[172:175], v[218:221], v[96:99]
	v_mfma_f32_16x16x32_bf16 v[124:127], v[168:171], v[184:187], v[124:127]
	v_mfma_f32_16x16x32_bf16 v[120:123], v[176:179], v[184:187], v[120:123]
	v_mfma_f32_16x16x32_bf16 v[116:119], v[168:171], v[192:195], v[116:119]
	v_mfma_f32_16x16x32_bf16 v[112:115], v[176:179], v[192:195], v[112:115]
	v_mfma_f32_16x16x32_bf16 v[108:111], v[168:171], v[214:217], v[108:111]
	v_mfma_f32_16x16x32_bf16 v[104:107], v[176:179], v[214:217], v[104:107]
	v_mfma_f32_16x16x32_bf16 v[100:103], v[168:171], v[222:225], v[100:103]
	v_mfma_f32_16x16x32_bf16 v[96:99], v[176:179], v[222:225], v[96:99]
	s_barrier
	s_add_i32 s75, 0, 0x14000
	v_lshl_add_u64 v[198:199], v[138:139], 0, s[16:17]
	s_add_i32 s74, s74, s40
	v_add_u32_e32 v163, s75, v157
	v_lshl_add_u64 v[200:201], v[198:199], 0, s[70:71]
	s_mov_b32 m0, s74
	ds_read_b128 v[226:229], v163
	ds_read_b128 v[230:233], v163 offset:1024
	ds_read_b128 v[234:237], v163 offset:2048
	ds_read_b128 v[238:241], v163 offset:3072
	global_load_lds_dwordx4 v[200:201], off
	v_lshl_add_u64 v[200:201], v[140:141], 0, s[16:17]
	v_lshl_add_u64 v[204:205], v[200:201], 0, s[70:71]
	s_add_i32 m0, s74, 0x2000
	s_nop 0
	global_load_lds_dwordx4 v[204:205], off
	s_barrier
	s_waitcnt lgkmcnt(0)
	s_waitcnt lgkmcnt(0)
	v_mfma_f32_16x16x32_bf16 v[92:95], v[226:229], v[180:183], v[92:95]
	v_mfma_f32_16x16x32_bf16 v[88:91], v[234:237], v[180:183], v[88:91]
	v_mfma_f32_16x16x32_bf16 v[84:87], v[226:229], v[188:191], v[84:87]
	v_mfma_f32_16x16x32_bf16 v[80:83], v[234:237], v[188:191], v[80:83]
	v_mfma_f32_16x16x32_bf16 v[76:79], v[226:229], v[210:213], v[76:79]
	v_mfma_f32_16x16x32_bf16 v[72:75], v[234:237], v[210:213], v[72:75]
	v_mfma_f32_16x16x32_bf16 v[68:71], v[226:229], v[218:221], v[68:71]
	v_mfma_f32_16x16x32_bf16 v[64:67], v[234:237], v[218:221], v[64:67]
	v_mfma_f32_16x16x32_bf16 v[92:95], v[230:233], v[184:187], v[92:95]
	v_mfma_f32_16x16x32_bf16 v[88:91], v[238:241], v[184:187], v[88:91]
	v_mfma_f32_16x16x32_bf16 v[84:87], v[230:233], v[192:195], v[84:87]
	v_mfma_f32_16x16x32_bf16 v[80:83], v[238:241], v[192:195], v[80:83]
	v_mfma_f32_16x16x32_bf16 v[76:79], v[230:233], v[214:217], v[76:79]
	v_mfma_f32_16x16x32_bf16 v[72:75], v[238:241], v[214:217], v[72:75]
	v_mfma_f32_16x16x32_bf16 v[68:71], v[230:233], v[222:225], v[68:71]
	v_mfma_f32_16x16x32_bf16 v[64:67], v[238:241], v[222:225], v[64:67]
	v_lshl_add_u64 v[204:205], v[130:131], 0, s[16:17]
	s_mov_b32 m0, s41
	v_lshl_add_u64 v[242:243], v[204:205], 0, s[70:71]
	s_barrier
	ds_read_b128 v[180:183], v156 offset:16384
	ds_read_b128 v[184:187], v156 offset:17408
	ds_read_b128 v[188:191], v156 offset:18432
	ds_read_b128 v[192:195], v156 offset:19456
	ds_read_b128 v[210:213], v156 offset:20480
	ds_read_b128 v[214:217], v156 offset:21504
	ds_read_b128 v[218:221], v156 offset:22528
	ds_read_b128 v[222:225], v156 offset:23552
	global_load_lds_dwordx4 v[242:243], off
	v_lshl_add_u64 v[242:243], v[132:133], 0, s[16:17]
	v_lshl_add_u64 v[244:245], v[242:243], 0, s[70:71]
	s_mov_b32 m0, s43
	s_nop 0
	global_load_lds_dwordx4 v[244:245], off
	s_barrier
	s_waitcnt lgkmcnt(0)
	s_waitcnt lgkmcnt(0)
	v_mfma_f32_16x16x32_bf16 v[60:63], v[164:167], v[180:183], v[60:63]
	v_mfma_f32_16x16x32_bf16 v[56:59], v[172:175], v[180:183], v[56:59]
	v_mfma_f32_16x16x32_bf16 v[52:55], v[164:167], v[188:191], v[52:55]
	v_mfma_f32_16x16x32_bf16 v[48:51], v[172:175], v[188:191], v[48:51]
	v_mfma_f32_16x16x32_bf16 v[44:47], v[164:167], v[210:213], v[44:47]
	v_mfma_f32_16x16x32_bf16 v[40:43], v[172:175], v[210:213], v[40:43]
	v_mfma_f32_16x16x32_bf16 v[36:39], v[164:167], v[218:221], v[36:39]
	v_mfma_f32_16x16x32_bf16 v[32:35], v[172:175], v[218:221], v[32:35]
	v_mfma_f32_16x16x32_bf16 v[60:63], v[168:171], v[184:187], v[60:63]
	v_mfma_f32_16x16x32_bf16 v[56:59], v[176:179], v[184:187], v[56:59]
	v_mfma_f32_16x16x32_bf16 v[52:55], v[168:171], v[192:195], v[52:55]
	v_mfma_f32_16x16x32_bf16 v[48:51], v[176:179], v[192:195], v[48:51]
	v_mfma_f32_16x16x32_bf16 v[44:47], v[168:171], v[214:217], v[44:47]
	v_mfma_f32_16x16x32_bf16 v[40:43], v[176:179], v[214:217], v[40:43]
	v_mfma_f32_16x16x32_bf16 v[36:39], v[168:171], v[222:225], v[36:39]
	v_mfma_f32_16x16x32_bf16 v[32:35], v[176:179], v[222:225], v[32:35]
	s_barrier
; #define G8_STAGE(bufoff, gbase, voff) do { _Pragma("unroll") for (int _i = 0; _i < 2; ++_i) \
;     __builtin_amdgcn_global_load_lds((const unsigned*)((const char*)(gbase) + (voff)[_i]), (G8_LAS unsigned*)(lds + (bufoff) + ldsw + _i * 8192), 16, 0, 0); } while (0)
; #define G8_LDA(dst, b, h) do { _Pragma("unroll") for (int m = 0; m < 4; ++m) _Pragma("unroll") for (int k = 0; k < 2; ++k) dst[m][k] = *(const G8_LAS bf16x8*)(lds + G8_OSA(b, h) + aoff + m * 2048 + k * 1024); } while (0)
; #define G8_LDB(dst, b, h) do { _Pragma("unroll") for (int n = 0; n < 2; ++n) _Pragma("unroll") for (int k = 0; k < 2; ++k) dst[n][k] = *(const G8_LAS bf16x8*)(lds + G8_OSB(b, h) + boff + n * 2048 + k * 1024); } while (0)
; #define G8_WAIT_V(n) asm volatile("s_waitcnt vmcnt(" #n ")" ::: "memory")
; #define G8_WAIT_L(n) asm volatile("s_waitcnt lgkmcnt(" #n ")" ::: "memory")
; #define G8_BAR __builtin_amdgcn_s_barrier()
; #define G8_SCHED __builtin_amdgcn_sched_barrier(0)
; __device__ __forceinline__ void gemm256(const bf* __restrict__ A, int lda, const bf* __restrict__ Bt, int ldb, int K,
;                                         int brow, int bcol, f32x4 (&acc)[2][2][4][2]) {
;     ...
;     G8_STAGE(G8_OSB(0, 1), b2 + hstepB, voffB);
;     G8_WAIT_V(6); G8_BAR; G8_MMA(1, 1, At, B1); G8_BAR;
;     G8_LDB(B0, 1, 0); G8_SCHED; G8_LDA(At, 1, 0); G8_STAGE(G8_OSA(0, 1), a2 + hstepA, voffA);
;     G8_WAIT_L(8); G8_BAR; G8_WAIT_L(0); G8_MMA(0, 0, At, B0); G8_BAR; G8_SCHED;
;     G8_LDB(B1, 1, 1); G8_STAGE(G8_OSB(1, 0), b3, voffB);
;     G8_BAR; G8_WAIT_L(0); G8_MMA(0, 1, At, B1); G8_BAR;
;     G8_LDA(At, 1, 1); G8_STAGE(G8_OSA(1, 0), a3, voffA);
	v_lshl_add_u64 v[244:245], v[142:143], 0, s[16:17]
	s_add_i32 s74, s75, s40
	v_lshl_add_u64 v[164:165], v[244:245], 0, s[70:71]
	s_mov_b32 m0, s74
	v_lshl_add_u64 v[246:247], v[154:155], 0, s[16:17]
	global_load_lds_dwordx4 v[164:165], off
	v_lshl_add_u64 v[164:165], v[246:247], 0, s[70:71]
	s_add_i32 m0, s74, 0x2000
	s_nop 0
	global_load_lds_dwordx4 v[164:165], off
	s_waitcnt vmcnt(6)
	s_barrier
	v_mfma_f32_16x16x32_bf16 v[28:31], v[226:229], v[180:183], v[28:31]
	v_mfma_f32_16x16x32_bf16 v[24:27], v[234:237], v[180:183], v[24:27]
	v_mfma_f32_16x16x32_bf16 v[20:23], v[226:229], v[188:191], v[20:23]
	v_mfma_f32_16x16x32_bf16 v[16:19], v[234:237], v[188:191], v[16:19]
	v_mfma_f32_16x16x32_bf16 v[12:15], v[226:229], v[210:213], v[12:15]
	v_mfma_f32_16x16x32_bf16 v[8:11], v[234:237], v[210:213], v[8:11]
	v_mfma_f32_16x16x32_bf16 v[4:7], v[226:229], v[218:221], v[4:7]
	v_mfma_f32_16x16x32_bf16 v[0:3], v[234:237], v[218:221], v[0:3]
	v_mfma_f32_16x16x32_bf16 v[28:31], v[230:233], v[184:187], v[28:31]
	v_mfma_f32_16x16x32_bf16 v[24:27], v[238:241], v[184:187], v[24:27]
	v_mfma_f32_16x16x32_bf16 v[20:23], v[230:233], v[192:195], v[20:23]
	v_mfma_f32_16x16x32_bf16 v[16:19], v[238:241], v[192:195], v[16:19]
	v_mfma_f32_16x16x32_bf16 v[12:15], v[230:233], v[214:217], v[12:15]
	v_mfma_f32_16x16x32_bf16 v[8:11], v[238:241], v[214:217], v[8:11]
	v_mfma_f32_16x16x32_bf16 v[4:7], v[230:233], v[222:225], v[4:7]
	v_mfma_f32_16x16x32_bf16 v[0:3], v[238:241], v[222:225], v[0:3]
	s_add_i32 s74, 0, 0x18000
	v_add_u32_e32 v163, s74, v157
	s_barrier
	ds_read_b128 v[164:167], v163
	ds_read_b128 v[168:171], v163 offset:1024
	ds_read_b128 v[172:175], v163 offset:2048
	ds_read_b128 v[176:179], v163 offset:3072
	s_mov_b32 m0, s44
	v_lshl_add_u64 v[158:159], v[158:159], 0, s[70:71]
	ds_read_b128 v[180:183], v156 offset:32768
	ds_read_b128 v[184:187], v156 offset:33792
	ds_read_b128 v[188:191], v156 offset:34816
	ds_read_b128 v[192:195], v156 offset:35840
	ds_read_b128 v[210:213], v156 offset:36864
	ds_read_b128 v[214:217], v156 offset:37888
	ds_read_b128 v[218:221], v156 offset:38912
	ds_read_b128 v[222:225], v156 offset:39936
	global_load_lds_dwordx4 v[158:159], off
	v_lshl_add_u64 v[158:159], v[196:197], 0, s[70:71]
	s_mov_b32 m0, s45
	s_nop 0
	global_load_lds_dwordx4 v[158:159], off
	s_waitcnt lgkmcnt(8)
	s_barrier
	s_waitcnt lgkmcnt(0)
	s_waitcnt lgkmcnt(0)
	v_mfma_f32_16x16x32_bf16 v[124:127], v[164:167], v[180:183], v[124:127]
	v_mfma_f32_16x16x32_bf16 v[120:123], v[172:175], v[180:183], v[120:123]
	v_mfma_f32_16x16x32_bf16 v[116:119], v[164:167], v[188:191], v[116:119]
	v_mfma_f32_16x16x32_bf16 v[112:115], v[172:175], v[188:191], v[112:115]
	v_mfma_f32_16x16x32_bf16 v[108:111], v[164:167], v[210:213], v[108:111]
	v_mfma_f32_16x16x32_bf16 v[104:107], v[172:175], v[210:213], v[104:107]
	v_mfma_f32_16x16x32_bf16 v[100:103], v[164:167], v[218:221], v[100:103]
	v_mfma_f32_16x16x32_bf16 v[96:99], v[172:175], v[218:221], v[96:99]
	v_mfma_f32_16x16x32_bf16 v[124:127], v[168:171], v[184:187], v[124:127]
	v_mfma_f32_16x16x32_bf16 v[120:123], v[176:179], v[184:187], v[120:123]
	v_mfma_f32_16x16x32_bf16 v[116:119], v[168:171], v[192:195], v[116:119]
	v_mfma_f32_16x16x32_bf16 v[112:115], v[176:179], v[192:195], v[112:115]
	v_mfma_f32_16x16x32_bf16 v[108:111], v[168:171], v[214:217], v[108:111]
	v_mfma_f32_16x16x32_bf16 v[104:107], v[176:179], v[214:217], v[104:107]
	v_mfma_f32_16x16x32_bf16 v[100:103], v[168:171], v[222:225], v[100:103]
	v_mfma_f32_16x16x32_bf16 v[96:99], v[176:179], v[222:225], v[96:99]
	s_barrier
	s_add_i32 s75, 0, 0x1c000
	v_add_u32_e32 v158, s75, v157
	s_add_i32 s74, s74, s40
	ds_read_b128 v[226:229], v158
	ds_read_b128 v[230:233], v158 offset:1024
	ds_read_b128 v[234:237], v158 offset:2048
	ds_read_b128 v[238:241], v158 offset:3072
	v_lshl_add_u64 v[158:159], v[198:199], 0, s[72:73]
	s_mov_b32 m0, s74
	s_nop 0
	global_load_lds_dwordx4 v[158:159], off
	v_lshl_add_u64 v[158:159], v[200:201], 0, s[72:73]
	s_add_i32 m0, s74, 0x2000
	s_nop 0
	global_load_lds_dwordx4 v[158:159], off
	s_barrier
	s_waitcnt lgkmcnt(0)
	s_waitcnt lgkmcnt(0)
	v_mfma_f32_16x16x32_bf16 v[92:95], v[226:229], v[180:183], v[92:95]
	v_mfma_f32_16x16x32_bf16 v[88:91], v[234:237], v[180:183], v[88:91]
	v_mfma_f32_16x16x32_bf16 v[84:87], v[226:229], v[188:191], v[84:87]
	v_mfma_f32_16x16x32_bf16 v[80:83], v[234:237], v[188:191], v[80:83]
	v_mfma_f32_16x16x32_bf16 v[76:79], v[226:229], v[210:213], v[76:79]
	v_mfma_f32_16x16x32_bf16 v[72:75], v[234:237], v[210:213], v[72:75]
	v_mfma_f32_16x16x32_bf16 v[68:71], v[226:229], v[218:221], v[68:71]
	v_mfma_f32_16x16x32_bf16 v[64:67], v[234:237], v[218:221], v[64:67]
	v_mfma_f32_16x16x32_bf16 v[92:95], v[230:233], v[184:187], v[92:95]
	v_mfma_f32_16x16x32_bf16 v[88:91], v[238:241], v[184:187], v[88:91]
	v_mfma_f32_16x16x32_bf16 v[84:87], v[230:233], v[192:195], v[84:87]
	v_mfma_f32_16x16x32_bf16 v[80:83], v[238:241], v[192:195], v[80:83]
	v_mfma_f32_16x16x32_bf16 v[76:79], v[230:233], v[214:217], v[76:79]
	v_mfma_f32_16x16x32_bf16 v[72:75], v[238:241], v[214:217], v[72:75]
	v_mfma_f32_16x16x32_bf16 v[68:71], v[230:233], v[222:225], v[68:71]
	v_mfma_f32_16x16x32_bf16 v[64:67], v[238:241], v[222:225], v[64:67]
	s_mov_b32 m0, s19
	v_lshl_add_u64 v[158:159], v[204:205], 0, s[72:73]
	s_barrier
	ds_read_b128 v[180:183], v156 offset:49152
	ds_read_b128 v[184:187], v156 offset:50176
	ds_read_b128 v[188:191], v156 offset:51200
	ds_read_b128 v[192:195], v156 offset:52224
	ds_read_b128 v[210:213], v156 offset:53248
	ds_read_b128 v[214:217], v156 offset:54272
	ds_read_b128 v[218:221], v156 offset:55296
	ds_read_b128 v[222:225], v156 offset:56320
	global_load_lds_dwordx4 v[158:159], off
	v_lshl_add_u64 v[158:159], v[242:243], 0, s[72:73]
	s_mov_b32 m0, s46
	s_nop 0
	global_load_lds_dwordx4 v[158:159], off
	s_barrier
; #define G8_STAGE(bufoff, gbase, voff) do { _Pragma("unroll") for (int _i = 0; _i < 2; ++_i) \
;     __builtin_amdgcn_global_load_lds((const unsigned*)((const char*)(gbase) + (voff)[_i]), (G8_LAS unsigned*)(lds + (bufoff) + ldsw + _i * 8192), 16, 0, 0); } while (0)
; #define G8_LDA(dst, b, h) do { _Pragma("unroll") for (int m = 0; m < 4; ++m) _Pragma("unroll") for (int k = 0; k < 2; ++k) dst[m][k] = *(const G8_LAS bf16x8*)(lds + G8_OSA(b, h) + aoff + m * 2048 + k * 1024); } while (0)
; #define G8_LDB(dst, b, h) do { _Pragma("unroll") for (int n = 0; n < 2; ++n) _Pragma("unroll") for (int k = 0; k < 2; ++k) dst[n][k] = *(const G8_LAS bf16x8*)(lds + G8_OSB(b, h) + boff + n * 2048 + k * 1024); } while (0)
; #define G8_WAIT_V(n) asm volatile("s_waitcnt vmcnt(" #n ")" ::: "memory")
; #define G8_WAIT_L(n) asm volatile("s_waitcnt lgkmcnt(" #n ")" ::: "memory")
; #define G8_BAR __builtin_amdgcn_s_barrier()
; #define G8_SCHED __builtin_amdgcn_sched_barrier(0)
; __device__ __forceinline__ void gemm256(const bf* __restrict__ A, int lda, const bf* __restrict__ Bt, int ldb, int K,
;                                         int brow, int bcol, f32x4 (&acc)[2][2][4][2]) {
;     ...
;     G8_BAR; G8_WAIT_L(0); G8_MMA(1, 0, At, B0); G8_BAR; G8_SCHED;
;     G8_STAGE(G8_OSB(1, 1), b3 + hstepB, voffB);
;     G8_WAIT_V(6); G8_BAR; G8_MMA(1, 1, At, B1); G8_BAR;
;   }
;   { const char* a1 = cA + (size_t)(nt - 1) * kstep;
;     G8_LDB(B0, 0, 0); G8_LDA(At, 0, 0); G8_STAGE(G8_OSA(1, 1), a1 + hstepA, voffA);
;     G8_BAR; G8_WAIT_L(0); G8_MMA(0, 0, At, B0); G8_BAR;
;     G8_LDB(B1, 0, 1); G8_BAR; G8_WAIT_L(0); G8_MMA(0, 1, At, B1); G8_BAR;
;     G8_LDA(At, 0, 1); G8_WAIT_V(4); G8_BAR; G8_WAIT_L(0); G8_MMA(1, 0, At, B0); G8_MMA(1, 1, At, B1); G8_BAR; }
	s_waitcnt lgkmcnt(0)
	s_waitcnt lgkmcnt(0)
	v_mfma_f32_16x16x32_bf16 v[60:63], v[164:167], v[180:183], v[60:63]
	v_mfma_f32_16x16x32_bf16 v[56:59], v[172:175], v[180:183], v[56:59]
	v_mfma_f32_16x16x32_bf16 v[52:55], v[164:167], v[188:191], v[52:55]
	v_mfma_f32_16x16x32_bf16 v[48:51], v[172:175], v[188:191], v[48:51]
	v_mfma_f32_16x16x32_bf16 v[44:47], v[164:167], v[210:213], v[44:47]
	v_mfma_f32_16x16x32_bf16 v[40:43], v[172:175], v[210:213], v[40:43]
	v_mfma_f32_16x16x32_bf16 v[36:39], v[164:167], v[218:221], v[36:39]
	v_mfma_f32_16x16x32_bf16 v[32:35], v[172:175], v[218:221], v[32:35]
	v_mfma_f32_16x16x32_bf16 v[60:63], v[168:171], v[184:187], v[60:63]
	v_mfma_f32_16x16x32_bf16 v[56:59], v[176:179], v[184:187], v[56:59]
	v_mfma_f32_16x16x32_bf16 v[52:55], v[168:171], v[192:195], v[52:55]
	v_mfma_f32_16x16x32_bf16 v[48:51], v[176:179], v[192:195], v[48:51]
	v_mfma_f32_16x16x32_bf16 v[44:47], v[168:171], v[214:217], v[44:47]
	v_mfma_f32_16x16x32_bf16 v[40:43], v[176:179], v[214:217], v[40:43]
	v_mfma_f32_16x16x32_bf16 v[36:39], v[168:171], v[222:225], v[36:39]
	v_mfma_f32_16x16x32_bf16 v[32:35], v[176:179], v[222:225], v[32:35]
	s_barrier
	s_add_i32 s74, s75, s40
	v_lshl_add_u64 v[158:159], v[244:245], 0, s[72:73]
	s_mov_b32 m0, s74
	s_nop 0
	global_load_lds_dwordx4 v[158:159], off
	v_lshl_add_u64 v[158:159], v[246:247], 0, s[72:73]
	s_add_i32 m0, s74, 0x2000
	s_nop 0
	global_load_lds_dwordx4 v[158:159], off
	s_waitcnt vmcnt(6)
	s_barrier
	v_mfma_f32_16x16x32_bf16 v[28:31], v[226:229], v[180:183], v[28:31]
	v_mfma_f32_16x16x32_bf16 v[24:27], v[234:237], v[180:183], v[24:27]
	v_mfma_f32_16x16x32_bf16 v[20:23], v[226:229], v[188:191], v[20:23]
	v_mfma_f32_16x16x32_bf16 v[16:19], v[234:237], v[188:191], v[16:19]
	v_mfma_f32_16x16x32_bf16 v[12:15], v[226:229], v[210:213], v[12:15]
	v_mfma_f32_16x16x32_bf16 v[8:11], v[234:237], v[210:213], v[8:11]
	v_mfma_f32_16x16x32_bf16 v[4:7], v[226:229], v[218:221], v[4:7]
	v_mfma_f32_16x16x32_bf16 v[0:3], v[234:237], v[218:221], v[0:3]
	v_mfma_f32_16x16x32_bf16 v[28:31], v[230:233], v[184:187], v[28:31]
	v_mfma_f32_16x16x32_bf16 v[24:27], v[238:241], v[184:187], v[24:27]
	v_mfma_f32_16x16x32_bf16 v[20:23], v[230:233], v[192:195], v[20:23]
	v_mfma_f32_16x16x32_bf16 v[16:19], v[238:241], v[192:195], v[16:19]
	v_mfma_f32_16x16x32_bf16 v[12:15], v[230:233], v[214:217], v[12:15]
	v_mfma_f32_16x16x32_bf16 v[8:11], v[238:241], v[214:217], v[8:11]
	v_mfma_f32_16x16x32_bf16 v[4:7], v[230:233], v[222:225], v[4:7]
	v_mfma_f32_16x16x32_bf16 v[0:3], v[238:241], v[222:225], v[0:3]
	s_add_u32 s16, s16, 0x100
	s_addc_u32 s17, s17, 0
	s_cmp_ge_u32 s48, s47
	s_barrier
	s_cbranch_scc0 .LBB0_2318
	s_mov_b32 m0, s68
	s_add_i32 s68, s18, -1
	s_lshl_b64 s[16:17], s[68:69], 7
	s_add_u32 s14, s14, s16
	s_addc_u32 s15, s15, s17
	v_add_u32_e32 v154, 0, v157
	s_add_u32 s14, s14, s42
	v_add_u32_e32 v142, 0x10000, v154
	s_addc_u32 s15, s15, 0
	ds_read_b128 v[130:133], v142
	ds_read_b128 v[134:137], v142 offset:1024
	ds_read_b128 v[138:141], v142 offset:2048
	ds_read_b128 v[164:167], v142 offset:3072
	ds_read_b128 v[168:171], v156
	ds_read_b128 v[172:175], v156 offset:1024
	ds_read_b128 v[176:179], v156 offset:2048
	ds_read_b128 v[180:183], v156 offset:3072
	ds_read_b128 v[184:187], v156 offset:4096
	ds_read_b128 v[188:191], v156 offset:5120
	ds_read_b128 v[192:195], v156 offset:6144
	ds_read_b128 v[210:213], v156 offset:7168
	v_lshl_add_u64 v[142:143], s[14:15], 0, v[144:145]
	global_load_lds_dwordx4 v[142:143], off
	v_lshl_add_u64 v[128:129], s[14:15], 0, v[128:129]
	s_mov_b32 m0, s49
	s_nop 0
	global_load_lds_dwordx4 v[128:129], off
	s_barrier
	s_waitcnt lgkmcnt(0)
	s_waitcnt lgkmcnt(0)
	v_mfma_f32_16x16x32_bf16 v[124:127], v[130:133], v[168:171], v[124:127]
	v_mfma_f32_16x16x32_bf16 v[120:123], v[138:141], v[168:171], v[120:123]
	v_mfma_f32_16x16x32_bf16 v[116:119], v[130:133], v[176:179], v[116:119]
	v_mfma_f32_16x16x32_bf16 v[112:115], v[138:141], v[176:179], v[112:115]
	v_mfma_f32_16x16x32_bf16 v[108:111], v[130:133], v[184:187], v[108:111]
	v_mfma_f32_16x16x32_bf16 v[104:107], v[138:141], v[184:187], v[104:107]
	v_mfma_f32_16x16x32_bf16 v[100:103], v[130:133], v[192:195], v[100:103]
	v_mfma_f32_16x16x32_bf16 v[96:99], v[138:141], v[192:195], v[96:99]
	v_mfma_f32_16x16x32_bf16 v[124:127], v[134:137], v[172:175], v[124:127]
	v_mfma_f32_16x16x32_bf16 v[120:123], v[164:167], v[172:175], v[120:123]
	v_mfma_f32_16x16x32_bf16 v[116:119], v[134:137], v[180:183], v[116:119]
	v_mfma_f32_16x16x32_bf16 v[112:115], v[164:167], v[180:183], v[112:115]
	v_mfma_f32_16x16x32_bf16 v[108:111], v[134:137], v[188:191], v[108:111]
	v_mfma_f32_16x16x32_bf16 v[104:107], v[164:167], v[188:191], v[104:107]
	v_mfma_f32_16x16x32_bf16 v[100:103], v[134:137], v[210:213], v[100:103]
	v_mfma_f32_16x16x32_bf16 v[96:99], v[164:167], v[210:213], v[96:99]
	v_add_u32_e32 v128, 0x14000, v154
	s_barrier
	ds_read_b128 v[214:217], v128
	ds_read_b128 v[218:221], v128 offset:1024
	ds_read_b128 v[222:225], v128 offset:2048
	ds_read_b128 v[226:229], v128 offset:3072
	s_barrier
	s_waitcnt lgkmcnt(0)
	s_waitcnt lgkmcnt(0)
	v_mfma_f32_16x16x32_bf16 v[92:95], v[214:217], v[168:171], v[92:95]
	v_mfma_f32_16x16x32_bf16 v[88:91], v[222:225], v[168:171], v[88:91]
	v_mfma_f32_16x16x32_bf16 v[84:87], v[214:217], v[176:179], v[84:87]
	v_mfma_f32_16x16x32_bf16 v[80:83], v[222:225], v[176:179], v[80:83]
	v_mfma_f32_16x16x32_bf16 v[76:79], v[214:217], v[184:187], v[76:79]
	v_mfma_f32_16x16x32_bf16 v[72:75], v[222:225], v[184:187], v[72:75]
	v_mfma_f32_16x16x32_bf16 v[68:71], v[214:217], v[192:195], v[68:71]
	v_mfma_f32_16x16x32_bf16 v[64:67], v[222:225], v[192:195], v[64:67]
	v_mfma_f32_16x16x32_bf16 v[92:95], v[218:221], v[172:175], v[92:95]
	v_mfma_f32_16x16x32_bf16 v[88:91], v[226:229], v[172:175], v[88:91]
	v_mfma_f32_16x16x32_bf16 v[84:87], v[218:221], v[180:183], v[84:87]
	v_mfma_f32_16x16x32_bf16 v[80:83], v[226:229], v[180:183], v[80:83]
	v_mfma_f32_16x16x32_bf16 v[76:79], v[218:221], v[188:191], v[76:79]
	v_mfma_f32_16x16x32_bf16 v[72:75], v[226:229], v[188:191], v[72:75]
	v_mfma_f32_16x16x32_bf16 v[68:71], v[218:221], v[210:213], v[68:71]
	v_mfma_f32_16x16x32_bf16 v[64:67], v[226:229], v[210:213], v[64:67]
	s_barrier
; #define G8_LDA(dst, b, h) do { _Pragma("unroll") for (int m = 0; m < 4; ++m) _Pragma("unroll") for (int k = 0; k < 2; ++k) dst[m][k] = *(const G8_LAS bf16x8*)(lds + G8_OSA(b, h) + aoff + m * 2048 + k * 1024); } while (0)
; #define G8_LDB(dst, b, h) do { _Pragma("unroll") for (int n = 0; n < 2; ++n) _Pragma("unroll") for (int k = 0; k < 2; ++k) dst[n][k] = *(const G8_LAS bf16x8*)(lds + G8_OSB(b, h) + boff + n * 2048 + k * 1024); } while (0)
; #define G8_WAIT_V(n) asm volatile("s_waitcnt vmcnt(" #n ")" ::: "memory")
; #define G8_WAIT_L(n) asm volatile("s_waitcnt lgkmcnt(" #n ")" ::: "memory")
; #define G8_BAR __builtin_amdgcn_s_barrier()
; __device__ __forceinline__ void gemm256(const bf* __restrict__ A, int lda, const bf* __restrict__ Bt, int ldb, int K,
;                                         int brow, int bcol, f32x4 (&acc)[2][2][4][2]) {
;     ...
;     G8_LDA(At, 0, 1); G8_WAIT_V(4); G8_BAR; G8_WAIT_L(0); G8_MMA(1, 0, At, B0); G8_MMA(1, 1, At, B1); G8_BAR; }
;   { G8_LDB(B0, 1, 0); G8_LDA(At, 1, 0); G8_WAIT_V(2); G8_BAR; G8_WAIT_L(0); G8_MMA(0, 0, At, B0); G8_BAR;
;     G8_LDB(B1, 1, 1); G8_WAIT_V(0); G8_BAR; G8_WAIT_L(0); G8_MMA(0, 1, At, B1); G8_BAR;
	ds_read_b128 v[168:171], v156 offset:16384
	ds_read_b128 v[172:175], v156 offset:17408
	ds_read_b128 v[176:179], v156 offset:18432
	ds_read_b128 v[180:183], v156 offset:19456
	ds_read_b128 v[184:187], v156 offset:20480
	ds_read_b128 v[188:191], v156 offset:21504
	ds_read_b128 v[192:195], v156 offset:22528
	ds_read_b128 v[210:213], v156 offset:23552
	s_waitcnt vmcnt(4)
	s_barrier
	s_waitcnt lgkmcnt(0)
	s_waitcnt lgkmcnt(0)
	v_mfma_f32_16x16x32_bf16 v[60:63], v[130:133], v[168:171], v[60:63]
	v_mfma_f32_16x16x32_bf16 v[56:59], v[138:141], v[168:171], v[56:59]
	v_mfma_f32_16x16x32_bf16 v[52:55], v[130:133], v[176:179], v[52:55]
	v_mfma_f32_16x16x32_bf16 v[48:51], v[138:141], v[176:179], v[48:51]
	v_mfma_f32_16x16x32_bf16 v[44:47], v[130:133], v[184:187], v[44:47]
	v_mfma_f32_16x16x32_bf16 v[40:43], v[138:141], v[184:187], v[40:43]
	v_mfma_f32_16x16x32_bf16 v[36:39], v[130:133], v[192:195], v[36:39]
	v_mfma_f32_16x16x32_bf16 v[32:35], v[138:141], v[192:195], v[32:35]
	v_mfma_f32_16x16x32_bf16 v[60:63], v[134:137], v[172:175], v[60:63]
	v_mfma_f32_16x16x32_bf16 v[56:59], v[164:167], v[172:175], v[56:59]
	v_mfma_f32_16x16x32_bf16 v[52:55], v[134:137], v[180:183], v[52:55]
	v_mfma_f32_16x16x32_bf16 v[48:51], v[164:167], v[180:183], v[48:51]
	v_mfma_f32_16x16x32_bf16 v[44:47], v[134:137], v[188:191], v[44:47]
	v_mfma_f32_16x16x32_bf16 v[40:43], v[164:167], v[188:191], v[40:43]
	v_mfma_f32_16x16x32_bf16 v[36:39], v[134:137], v[210:213], v[36:39]
	v_mfma_f32_16x16x32_bf16 v[32:35], v[164:167], v[210:213], v[32:35]
	v_mfma_f32_16x16x32_bf16 v[28:31], v[214:217], v[168:171], v[28:31]
	v_mfma_f32_16x16x32_bf16 v[24:27], v[222:225], v[168:171], v[24:27]
	v_mfma_f32_16x16x32_bf16 v[20:23], v[214:217], v[176:179], v[20:23]
	v_mfma_f32_16x16x32_bf16 v[16:19], v[222:225], v[176:179], v[16:19]
	v_mfma_f32_16x16x32_bf16 v[12:15], v[214:217], v[184:187], v[12:15]
	v_mfma_f32_16x16x32_bf16 v[8:11], v[222:225], v[184:187], v[8:11]
	v_mfma_f32_16x16x32_bf16 v[4:7], v[214:217], v[192:195], v[4:7]
	v_mfma_f32_16x16x32_bf16 v[0:3], v[222:225], v[192:195], v[0:3]
	v_mfma_f32_16x16x32_bf16 v[28:31], v[218:221], v[172:175], v[28:31]
	v_mfma_f32_16x16x32_bf16 v[24:27], v[226:229], v[172:175], v[24:27]
	v_mfma_f32_16x16x32_bf16 v[20:23], v[218:221], v[180:183], v[20:23]
	v_mfma_f32_16x16x32_bf16 v[16:19], v[226:229], v[180:183], v[16:19]
	v_mfma_f32_16x16x32_bf16 v[12:15], v[218:221], v[188:191], v[12:15]
	v_mfma_f32_16x16x32_bf16 v[8:11], v[226:229], v[188:191], v[8:11]
	v_mfma_f32_16x16x32_bf16 v[4:7], v[218:221], v[210:213], v[4:7]
	v_mfma_f32_16x16x32_bf16 v[0:3], v[226:229], v[210:213], v[0:3]
	v_add_u32_e32 v140, 0x18000, v154
	s_barrier
	ds_read_b128 v[128:131], v140
	ds_read_b128 v[132:135], v140 offset:1024
	ds_read_b128 v[136:139], v140 offset:2048
	ds_read_b128 v[140:143], v140 offset:3072
	ds_read_b128 v[164:167], v156 offset:32768
	ds_read_b128 v[168:171], v156 offset:33792
	ds_read_b128 v[172:175], v156 offset:34816
	ds_read_b128 v[176:179], v156 offset:35840
	ds_read_b128 v[180:183], v156 offset:36864
	ds_read_b128 v[184:187], v156 offset:37888
	ds_read_b128 v[188:191], v156 offset:38912
	ds_read_b128 v[192:195], v156 offset:39936
	s_waitcnt vmcnt(2)
	s_barrier
	s_waitcnt lgkmcnt(0)
	s_waitcnt lgkmcnt(0)
	v_mfma_f32_16x16x32_bf16 v[124:127], v[128:131], v[164:167], v[124:127]
	v_mfma_f32_16x16x32_bf16 v[120:123], v[136:139], v[164:167], v[120:123]
	v_mfma_f32_16x16x32_bf16 v[116:119], v[128:131], v[172:175], v[116:119]
	v_mfma_f32_16x16x32_bf16 v[112:115], v[136:139], v[172:175], v[112:115]
	v_mfma_f32_16x16x32_bf16 v[108:111], v[128:131], v[180:183], v[108:111]
	v_mfma_f32_16x16x32_bf16 v[104:107], v[136:139], v[180:183], v[104:107]
	v_mfma_f32_16x16x32_bf16 v[100:103], v[128:131], v[188:191], v[100:103]
	v_mfma_f32_16x16x32_bf16 v[96:99], v[136:139], v[188:191], v[96:99]
	v_mfma_f32_16x16x32_bf16 v[124:127], v[132:135], v[168:171], v[124:127]
	v_mfma_f32_16x16x32_bf16 v[120:123], v[140:143], v[168:171], v[120:123]
	v_mfma_f32_16x16x32_bf16 v[116:119], v[132:135], v[176:179], v[116:119]
	v_mfma_f32_16x16x32_bf16 v[112:115], v[140:143], v[176:179], v[112:115]
	v_mfma_f32_16x16x32_bf16 v[108:111], v[132:135], v[184:187], v[108:111]
	v_mfma_f32_16x16x32_bf16 v[104:107], v[140:143], v[184:187], v[104:107]
	v_mfma_f32_16x16x32_bf16 v[100:103], v[132:135], v[192:195], v[100:103]
	v_mfma_f32_16x16x32_bf16 v[96:99], v[140:143], v[192:195], v[96:99]
	v_add_u32_e32 v144, 0x1c000, v154
	s_barrier
; #define G8_LDA(dst, b, h) do { _Pragma("unroll") for (int m = 0; m < 4; ++m) _Pragma("unroll") for (int k = 0; k < 2; ++k) dst[m][k] = *(const G8_LAS bf16x8*)(lds + G8_OSA(b, h) + aoff + m * 2048 + k * 1024); } while (0)
; #define G8_LDB(dst, b, h) do { _Pragma("unroll") for (int n = 0; n < 2; ++n) _Pragma("unroll") for (int k = 0; k < 2; ++k) dst[n][k] = *(const G8_LAS bf16x8*)(lds + G8_OSB(b, h) + boff + n * 2048 + k * 1024); } while (0)
; #define G8_WAIT_V(n) asm volatile("s_waitcnt vmcnt(" #n ")" ::: "memory")
; #define G8_WAIT_L(n) asm volatile("s_waitcnt lgkmcnt(" #n ")" ::: "memory")
; #define G8_BAR __builtin_amdgcn_s_barrier()
; __device__ __forceinline__ void gemm256(const bf* __restrict__ A, int lda, const bf* __restrict__ Bt, int ldb, int K,
;                                         int brow, int bcol, f32x4 (&acc)[2][2][4][2]) {
;     ...
;   { G8_LDB(B0, 1, 0); G8_LDA(At, 1, 0); G8_WAIT_V(2); G8_BAR; G8_WAIT_L(0); G8_MMA(0, 0, At, B0); G8_BAR;
;     G8_LDB(B1, 1, 1); G8_WAIT_V(0); G8_BAR; G8_WAIT_L(0); G8_MMA(0, 1, At, B1); G8_BAR;
;     G8_LDA(At, 1, 1); G8_BAR; G8_WAIT_L(0); G8_MMA(1, 0, At, B0); G8_MMA(1, 1, At, B1); G8_BAR; }
;   if (wr == 0) G8_BAR;
	ds_read_b128 v[210:213], v144
	ds_read_b128 v[214:217], v144 offset:1024
	ds_read_b128 v[218:221], v144 offset:2048
	ds_read_b128 v[222:225], v144 offset:3072
	s_waitcnt vmcnt(0)
	s_barrier
	s_waitcnt lgkmcnt(0)
	s_waitcnt lgkmcnt(0)
	v_mfma_f32_16x16x32_bf16 v[92:95], v[210:213], v[164:167], v[92:95]
	v_mfma_f32_16x16x32_bf16 v[88:91], v[218:221], v[164:167], v[88:91]
	v_mfma_f32_16x16x32_bf16 v[84:87], v[210:213], v[172:175], v[84:87]
	v_mfma_f32_16x16x32_bf16 v[80:83], v[218:221], v[172:175], v[80:83]
	v_mfma_f32_16x16x32_bf16 v[76:79], v[210:213], v[180:183], v[76:79]
	v_mfma_f32_16x16x32_bf16 v[72:75], v[218:221], v[180:183], v[72:75]
	v_mfma_f32_16x16x32_bf16 v[68:71], v[210:213], v[188:191], v[68:71]
	v_mfma_f32_16x16x32_bf16 v[64:67], v[218:221], v[188:191], v[64:67]
	v_mfma_f32_16x16x32_bf16 v[92:95], v[214:217], v[168:171], v[92:95]
	v_mfma_f32_16x16x32_bf16 v[88:91], v[222:225], v[168:171], v[88:91]
	v_mfma_f32_16x16x32_bf16 v[84:87], v[214:217], v[176:179], v[84:87]
	v_mfma_f32_16x16x32_bf16 v[80:83], v[222:225], v[176:179], v[80:83]
	v_mfma_f32_16x16x32_bf16 v[76:79], v[214:217], v[184:187], v[76:79]
	v_mfma_f32_16x16x32_bf16 v[72:75], v[222:225], v[184:187], v[72:75]
	v_mfma_f32_16x16x32_bf16 v[68:71], v[214:217], v[192:195], v[68:71]
	v_mfma_f32_16x16x32_bf16 v[64:67], v[222:225], v[192:195], v[64:67]
	s_barrier
	ds_read_b128 v[164:167], v156 offset:49152
	ds_read_b128 v[168:171], v156 offset:50176
	ds_read_b128 v[172:175], v156 offset:51200
	ds_read_b128 v[176:179], v156 offset:52224
	ds_read_b128 v[180:183], v156 offset:53248
	ds_read_b128 v[184:187], v156 offset:54272
	ds_read_b128 v[188:191], v156 offset:55296
	ds_read_b128 v[154:157], v156 offset:56320
	s_barrier
	s_waitcnt lgkmcnt(0)
	s_waitcnt lgkmcnt(0)
	v_mfma_f32_16x16x32_bf16 v[60:63], v[128:131], v[164:167], v[60:63]
	v_mfma_f32_16x16x32_bf16 v[56:59], v[136:139], v[164:167], v[56:59]
	v_mfma_f32_16x16x32_bf16 v[52:55], v[128:131], v[172:175], v[52:55]
	v_mfma_f32_16x16x32_bf16 v[48:51], v[136:139], v[172:175], v[48:51]
	v_mfma_f32_16x16x32_bf16 v[44:47], v[128:131], v[180:183], v[44:47]
	v_mfma_f32_16x16x32_bf16 v[40:43], v[136:139], v[180:183], v[40:43]
	v_mfma_f32_16x16x32_bf16 v[36:39], v[128:131], v[188:191], v[36:39]
	v_mfma_f32_16x16x32_bf16 v[32:35], v[136:139], v[188:191], v[32:35]
	v_mfma_f32_16x16x32_bf16 v[60:63], v[132:135], v[168:171], v[60:63]
	v_mfma_f32_16x16x32_bf16 v[56:59], v[140:143], v[168:171], v[56:59]
	v_mfma_f32_16x16x32_bf16 v[52:55], v[132:135], v[176:179], v[52:55]
	v_mfma_f32_16x16x32_bf16 v[48:51], v[140:143], v[176:179], v[48:51]
	v_mfma_f32_16x16x32_bf16 v[44:47], v[132:135], v[184:187], v[44:47]
	v_mfma_f32_16x16x32_bf16 v[40:43], v[140:143], v[184:187], v[40:43]
	v_mfma_f32_16x16x32_bf16 v[36:39], v[132:135], v[154:157], v[36:39]
	v_mfma_f32_16x16x32_bf16 v[32:35], v[140:143], v[154:157], v[32:35]
	v_mfma_f32_16x16x32_bf16 v[28:31], v[210:213], v[164:167], v[28:31]
	v_mfma_f32_16x16x32_bf16 v[24:27], v[218:221], v[164:167], v[24:27]
	v_mfma_f32_16x16x32_bf16 v[20:23], v[210:213], v[172:175], v[20:23]
	v_mfma_f32_16x16x32_bf16 v[16:19], v[218:221], v[172:175], v[16:19]
	v_mfma_f32_16x16x32_bf16 v[12:15], v[210:213], v[180:183], v[12:15]
	v_mfma_f32_16x16x32_bf16 v[8:11], v[218:221], v[180:183], v[8:11]
	v_mfma_f32_16x16x32_bf16 v[4:7], v[210:213], v[188:191], v[4:7]
	v_mfma_f32_16x16x32_bf16 v[0:3], v[218:221], v[188:191], v[0:3]
	v_mfma_f32_16x16x32_bf16 v[28:31], v[214:217], v[168:171], v[28:31]
	v_mfma_f32_16x16x32_bf16 v[24:27], v[222:225], v[168:171], v[24:27]
	v_mfma_f32_16x16x32_bf16 v[20:23], v[214:217], v[176:179], v[20:23]
	v_mfma_f32_16x16x32_bf16 v[16:19], v[222:225], v[176:179], v[16:19]
	v_mfma_f32_16x16x32_bf16 v[12:15], v[214:217], v[184:187], v[12:15]
	v_mfma_f32_16x16x32_bf16 v[8:11], v[222:225], v[184:187], v[8:11]
	v_mfma_f32_16x16x32_bf16 v[4:7], v[214:217], v[154:157], v[4:7]
	v_mfma_f32_16x16x32_bf16 v[0:3], v[222:225], v[154:157], v[0:3]
	s_setprio 0
	s_cmpk_lt_u32 s39, 0x100
	s_barrier
	s_cbranch_scc0 .LBB0_2321
	s_barrier

; __device__ __forceinline__ int otid_full() { int t = threadIdx.x; asm volatile("" : "+v"(t)); return t; }
; #define G8_LAS __attribute__((address_space(3)))
; #define G8_STAGE(bufoff, gbase, voff) do { _Pragma("unroll") for (int _i = 0; _i < 2; ++_i) \
;     __builtin_amdgcn_global_load_lds((const unsigned*)((const char*)(gbase) + (voff)[_i]), (G8_LAS unsigned*)(lds + (bufoff) + ldsw + _i * 8192), 16, 0, 0); } while (0)
; #define G8_WAIT_V(n) asm volatile("s_waitcnt vmcnt(" #n ")" ::: "memory")
; __device__ __forceinline__ void gemm256(const bf* __restrict__ A, int lda, const bf* __restrict__ Bt, int ldb, int K,
;                                         int brow, int bcol, f32x4 (&acc)[2][2][4][2]) {
;   G8_LAS unsigned char* lds = (G8_LAS unsigned char*)dynsm;
;   const int tid = otid_full(), wid = __builtin_amdgcn_readfirstlane(tid >> 6), lane = tid & 63, wr = wid >> 2, wc = wid & 3, fr = lane & 15, fq = lane >> 4;
;   unsigned voffA[2], voffB[2];
; #pragma unroll
;   for (int i = 0; i < 2; ++i) { int R, C; g8_stage_rc(tid * 16 + i * 8192, R, C); voffA[i] = (unsigned)(R * lda + C) * 2u; voffB[i] = (unsigned)(R * ldb + C) * 2u; }
;   const size_t kstep = 128;
;   const size_t hstepA = (size_t)128 * lda * 2, hstepB = (size_t)128 * ldb * 2;
;   const unsigned ldsw = (unsigned)wid * 1024u;
;   const int aoff = g8_lds_byte(wr * 64 + fr, fq * 8), boff = g8_lds_byte(wc * 32 + fr, fq * 8);
;   const char* cA = (const char*)A + (size_t)brow * lda * 2; const char* cB = (const char*)Bt + (size_t)bcol * ldb * 2;
;   bf16x8 At[4][2], B0[2][2], B1[2][2];
;   const int nt = K / 64;
;   __syncthreads();
;   G8_STAGE(G8_OSB(0, 0), cB, voffB); G8_STAGE(G8_OSA(0, 0), cA, voffA); G8_STAGE(G8_OSB(0, 1), cB + hstepB, voffB); G8_STAGE(G8_OSA(0, 1), cA + hstepA, voffA);
;   if (wr == 1) G8_BAR;
;   G8_WAIT_V(4); G8_BAR;
;   G8_STAGE(G8_OSB(1, 0), cB + kstep, voffB); G8_STAGE(G8_OSA(1, 0), cA + kstep, voffA); G8_STAGE(G8_OSB(1, 1), cB + hstepB + kstep, voffB);
;   G8_WAIT_V(6); G8_BAR;
; __device__ __forceinline__ void phaseF(const Params& p, int layer) {
;     ...
;   for (int L = blockIdx.x; L < 1024; L += gridDim.x) {
;     int pm, pn; tile_order(L, 128, 8, pm, pn);
;     const int brow = pm * 256, bcol = pn * 256;
;     f32x4 acc[2][2][4][2]; ZERO_ACC8(acc);
;     gemm256(merged, 2048, p.WoutT + (size_t)layer * 2048 * 2048, 2048, 2048, brow, bcol, acc);
.LBB0_2436:
	v_and_b32_e32 v16, 15, v15
	v_and_b32_e32 v17, 48, v15
	v_lshlrev_b32_e32 v15, 2, v15
	v_lshlrev_b32_e32 v16, 6, v16
	v_and_b32_e32 v15, 32, v15
	s_lshl_b32 s22, s22, 12
	v_or_b32_e32 v18, v16, v17
	v_bitop3_b32 v16, v16, v15, v17 bitop3:0x36
	s_lshl_b32 s21, s21, 13
	s_and_b32 s22, s22, 0x3000
	s_add_i32 m0, s3, 0x18000
	v_lshl_add_u64 v[8:9], v[8:9], 0, s[50:51]
	v_or_b32_e32 v141, s22, v16
	v_bitop3_b32 v15, v18, s21, v15 bitop3:0xde
	s_waitcnt vmcnt(4)
	s_barrier
	global_load_lds_dwordx4 v[8:9], off
	v_lshl_add_u64 v[6:7], v[6:7], 0, s[50:51]
	s_add_i32 m0, s3, 0x1a000
	s_add_i32 s21, s3, 0x8000
	s_add_i32 s22, s3, 0xa000
	global_load_lds_dwordx4 v[6:7], off
	v_lshl_add_u64 v[4:5], v[4:5], 0, s[50:51]
	s_mov_b32 m0, s21
	s_add_u32 s10, s10, 0x80080
	global_load_lds_dwordx4 v[4:5], off
	v_lshl_add_u64 v[2:3], v[2:3], 0, s[50:51]
	s_mov_b32 m0, s22
	s_addc_u32 s11, s11, 0
	global_load_lds_dwordx4 v[2:3], off
	s_add_i32 m0, s3, 0x1c000
	v_lshl_add_u64 v[2:3], s[10:11], 0, v[144:145]
	global_load_lds_dwordx4 v[2:3], off
	v_lshl_add_u64 v[2:3], s[10:11], 0, v[128:129]
	s_add_i32 m0, s3, 0x1e000
	s_sub_i32 s11, s23, s25
	global_load_lds_dwordx4 v[2:3], off
	s_lshl_b32 s23, s24, 6
	s_sub_i32 s11, s11, s23
	s_sext_i32_i8 s11, s11
	s_lshl_b32 s10, s24, 11
	s_lshl_b32 s11, s11, 8
	s_add_i32 s10, s10, s11
	s_ashr_i32 s11, s10, 31
	v_readlane_b32 s52, v253, 3
	s_lshl_b64 s[10:11], s[10:11], 12
	v_lshlrev_b32_e32 v2, 15, v10
	v_readlane_b32 s62, v253, 13
	v_lshlrev_b32_e32 v4, 15, v1
	v_and_b32_e32 v2, 0xffff0000, v2
	v_readlane_b32 s63, v253, 14
	s_add_u32 s10, s62, s10
	v_and_b32_e32 v4, 0xffff0000, v4
	v_lshl_add_u32 v2, v13, 12, v2
	v_and_b32_e32 v3, 1, v10
	s_addc_u32 s11, s63, s11
	v_lshl_add_u32 v4, v11, 12, v4
	v_and_b32_e32 v1, 1, v1
	s_waitcnt vmcnt(6)
	v_lshl_or_b32 v2, v3, 6, v2
	v_lshl_or_b32 v1, v1, 6, v4
	s_add_u32 s8, s14, s8
	v_lshl_add_u32 v2, v14, 1, v2
	v_mov_b32_e32 v3, v145
	v_lshl_add_u32 v4, v12, 1, v1
	v_mov_b32_e32 v5, v145
	s_addc_u32 s9, s15, s9
	v_lshl_add_u64 v[130:131], s[10:11], 0, v[2:3]
	v_lshl_add_u64 v[132:133], s[10:11], 0, v[4:5]
	v_lshl_add_u64 v[134:135], s[8:9], 0, v[2:3]
	v_lshl_add_u64 v[136:137], s[8:9], 0, v[4:5]
	s_mov_b32 s10, -2
	s_mov_b64 s[8:9], 0
	v_add_u32_e32 v140, 0, v15
	v_mov_b32_e32 v1, v0
	v_mov_b32_e32 v2, v0
	v_mov_b32_e32 v3, v0
	v_mov_b32_e32 v4, v0
	v_mov_b32_e32 v5, v0
	v_mov_b32_e32 v6, v0
	v_mov_b32_e32 v7, v0
	v_mov_b32_e32 v8, v0
	v_mov_b32_e32 v9, v0
	v_mov_b32_e32 v10, v0
	v_mov_b32_e32 v11, v0
	v_mov_b32_e32 v12, v0
	v_mov_b32_e32 v13, v0
	v_mov_b32_e32 v14, v0
	v_mov_b32_e32 v15, v0
	v_mov_b32_e32 v16, v0
	v_mov_b32_e32 v17, v0
	v_mov_b32_e32 v18, v0
	v_mov_b32_e32 v19, v0
	v_mov_b32_e32 v20, v0
	v_mov_b32_e32 v21, v0
	v_mov_b32_e32 v22, v0
	v_mov_b32_e32 v23, v0
	v_mov_b32_e32 v24, v0
	v_mov_b32_e32 v25, v0
	v_mov_b32_e32 v26, v0
	v_mov_b32_e32 v27, v0
	v_mov_b32_e32 v28, v0
	v_mov_b32_e32 v29, v0
	v_mov_b32_e32 v30, v0
	v_mov_b32_e32 v31, v0
	v_mov_b32_e32 v32, v0
	v_mov_b32_e32 v33, v0
	v_mov_b32_e32 v34, v0
	v_mov_b32_e32 v35, v0
	v_mov_b32_e32 v36, v0
	v_mov_b32_e32 v37, v0
	v_mov_b32_e32 v38, v0
	v_mov_b32_e32 v39, v0
	v_mov_b32_e32 v40, v0
	v_mov_b32_e32 v41, v0
	v_mov_b32_e32 v42, v0
	v_mov_b32_e32 v43, v0
	v_mov_b32_e32 v44, v0
	v_mov_b32_e32 v45, v0
	v_mov_b32_e32 v46, v0
	v_mov_b32_e32 v47, v0
	v_mov_b32_e32 v48, v0
	v_mov_b32_e32 v49, v0
	v_mov_b32_e32 v50, v0
	v_mov_b32_e32 v51, v0
	v_mov_b32_e32 v52, v0
	v_mov_b32_e32 v53, v0
	v_mov_b32_e32 v54, v0
	v_mov_b32_e32 v55, v0
	v_mov_b32_e32 v56, v0
	v_mov_b32_e32 v57, v0
	v_mov_b32_e32 v58, v0
	v_mov_b32_e32 v59, v0
	v_mov_b32_e32 v60, v0
	v_mov_b32_e32 v61, v0
	v_mov_b32_e32 v62, v0
	v_mov_b32_e32 v63, v0
	v_mov_b32_e32 v64, v0
	v_mov_b32_e32 v65, v0
	v_mov_b32_e32 v66, v0
	v_mov_b32_e32 v67, v0
	v_mov_b32_e32 v68, v0
	v_mov_b32_e32 v69, v0
	v_mov_b32_e32 v70, v0
	v_mov_b32_e32 v71, v0
	v_mov_b32_e32 v72, v0
	v_mov_b32_e32 v73, v0
	v_mov_b32_e32 v74, v0
	v_mov_b32_e32 v75, v0
	v_mov_b32_e32 v76, v0
	v_mov_b32_e32 v77, v0
	v_mov_b32_e32 v78, v0
	v_mov_b32_e32 v79, v0
	v_mov_b32_e32 v80, v0
	v_mov_b32_e32 v81, v0
	v_mov_b32_e32 v82, v0
	v_mov_b32_e32 v83, v0
	v_mov_b32_e32 v84, v0
	v_mov_b32_e32 v85, v0
	v_mov_b32_e32 v86, v0
	v_mov_b32_e32 v87, v0
	v_mov_b32_e32 v88, v0
	v_mov_b32_e32 v89, v0
	v_mov_b32_e32 v90, v0
	v_mov_b32_e32 v91, v0
	v_mov_b32_e32 v92, v0
	v_mov_b32_e32 v93, v0
	v_mov_b32_e32 v94, v0
	v_mov_b32_e32 v95, v0
	v_mov_b32_e32 v96, v0
	v_mov_b32_e32 v97, v0
	v_mov_b32_e32 v98, v0
	v_mov_b32_e32 v99, v0
	v_mov_b32_e32 v100, v0
	v_mov_b32_e32 v101, v0
	v_mov_b32_e32 v102, v0
	v_mov_b32_e32 v103, v0
	v_mov_b32_e32 v104, v0
	v_mov_b32_e32 v105, v0
	v_mov_b32_e32 v106, v0
	v_mov_b32_e32 v107, v0
	v_mov_b32_e32 v108, v0
	v_mov_b32_e32 v109, v0
	v_mov_b32_e32 v110, v0
	v_mov_b32_e32 v111, v0
	v_mov_b32_e32 v112, v0
	v_mov_b32_e32 v113, v0
	v_mov_b32_e32 v114, v0
	v_mov_b32_e32 v115, v0
	v_mov_b32_e32 v116, v0
	v_mov_b32_e32 v117, v0
	v_mov_b32_e32 v118, v0
	v_mov_b32_e32 v119, v0
	v_mov_b32_e32 v120, v0
	v_mov_b32_e32 v121, v0
	v_mov_b32_e32 v122, v0
	v_mov_b32_e32 v123, v0
	v_mov_b32_e32 v124, v0
	v_mov_b32_e32 v125, v0
	v_mov_b32_e32 v126, v0
	v_mov_b32_e32 v127, v0
	s_barrier
	v_readlane_b32 s53, v253, 4
	v_readlane_b32 s54, v253, 5
	v_readlane_b32 s55, v253, 6
	v_readlane_b32 s56, v253, 7
	v_readlane_b32 s57, v253, 8
	v_readlane_b32 s58, v253, 9
	v_readlane_b32 s59, v253, 10
	v_readlane_b32 s60, v253, 11
	v_readlane_b32 s61, v253, 12
	v_readlane_b32 s64, v253, 15
	v_readlane_b32 s65, v253, 16
	v_readlane_b32 s66, v253, 17
	v_readlane_b32 s67, v253, 18
	s_setprio 0
	s_bitcmp1_b32 s17, 8
	s_cbranch_scc0 .Lprio_0
	s_setprio 1
; #define G8_STAGE(bufoff, gbase, voff) do { _Pragma("unroll") for (int _i = 0; _i < 2; ++_i) \
;     __builtin_amdgcn_global_load_lds((const unsigned*)((const char*)(gbase) + (voff)[_i]), (G8_LAS unsigned*)(lds + (bufoff) + ldsw + _i * 8192), 16, 0, 0); } while (0)
; #define G8_LDA(dst, b, h) do { _Pragma("unroll") for (int m = 0; m < 4; ++m) _Pragma("unroll") for (int k = 0; k < 2; ++k) dst[m][k] = *(const G8_LAS bf16x8*)(lds + G8_OSA(b, h) + aoff + m * 2048 + k * 1024); } while (0)
; #define G8_LDB(dst, b, h) do { _Pragma("unroll") for (int n = 0; n < 2; ++n) _Pragma("unroll") for (int k = 0; k < 2; ++k) dst[n][k] = *(const G8_LAS bf16x8*)(lds + G8_OSB(b, h) + boff + n * 2048 + k * 1024); } while (0)
; #define G8_WAIT_L(n) asm volatile("s_waitcnt lgkmcnt(" #n ")" ::: "memory")
; #define G8_BAR __builtin_amdgcn_s_barrier()
; #define G8_SCHED __builtin_amdgcn_sched_barrier(0)
; __device__ __forceinline__ void gemm256(const bf* __restrict__ A, int lda, const bf* __restrict__ Bt, int ldb, int K,
;                                         int brow, int bcol, f32x4 (&acc)[2][2][4][2]) {
;     ...
;     G8_LDB(B0, 0, 0); G8_SCHED; G8_LDA(At, 0, 0); G8_STAGE(G8_OSA(1, 1), a1 + hstepA, voffA);
;     G8_WAIT_L(8); G8_BAR; G8_WAIT_L(0); G8_MMA(0, 0, At, B0); G8_BAR; G8_SCHED;
;     G8_LDB(B1, 0, 1); G8_STAGE(G8_OSB(0, 0), b2, voffB);
;     G8_BAR; G8_WAIT_L(0); G8_MMA(0, 1, At, B1); G8_BAR;
;     G8_LDA(At, 0, 1); G8_STAGE(G8_OSA(0, 0), a2, voffA);
;     G8_BAR; G8_WAIT_L(0); G8_MMA(1, 0, At, B0); G8_BAR; G8_SCHED;
.Lprio_0:
.LBB0_2437:
	s_add_i32 s24, 0, 0x10000
	v_add_u32_e32 v142, s24, v141
	ds_read_b128 v[146:149], v142
	ds_read_b128 v[150:153], v142 offset:1024
	ds_read_b128 v[154:157], v142 offset:2048
	ds_read_b128 v[158:161], v142 offset:3072
	v_lshl_add_u64 v[142:143], v[130:131], 0, s[8:9]
	s_add_i32 s23, s3, 0xc000
	v_lshl_add_u64 v[194:195], v[142:143], 0, s[74:75]
	s_mov_b32 m0, s23
	v_lshl_add_u64 v[198:199], v[132:133], 0, s[8:9]
	s_add_i32 s11, s3, 0xe000
	ds_read_b128 v[162:165], v140
	ds_read_b128 v[166:169], v140 offset:1024
	ds_read_b128 v[170:173], v140 offset:2048
	ds_read_b128 v[174:177], v140 offset:3072
	ds_read_b128 v[178:181], v140 offset:4096
	ds_read_b128 v[182:185], v140 offset:5120
	ds_read_b128 v[186:189], v140 offset:6144
	ds_read_b128 v[190:193], v140 offset:7168
	global_load_lds_dwordx4 v[194:195], off
	v_lshl_add_u64 v[194:195], v[198:199], 0, s[74:75]
	s_mov_b32 m0, s11
	s_nop 0
	global_load_lds_dwordx4 v[194:195], off
	s_waitcnt lgkmcnt(8)
	s_barrier
	s_waitcnt lgkmcnt(0)
	s_waitcnt lgkmcnt(0)
	v_mfma_f32_16x16x32_bf16 v[124:127], v[146:149], v[162:165], v[124:127]
	v_mfma_f32_16x16x32_bf16 v[120:123], v[154:157], v[162:165], v[120:123]
	v_mfma_f32_16x16x32_bf16 v[116:119], v[146:149], v[170:173], v[116:119]
	v_mfma_f32_16x16x32_bf16 v[112:115], v[154:157], v[170:173], v[112:115]
	v_mfma_f32_16x16x32_bf16 v[108:111], v[146:149], v[178:181], v[108:111]
	v_mfma_f32_16x16x32_bf16 v[104:107], v[154:157], v[178:181], v[104:107]
	v_mfma_f32_16x16x32_bf16 v[100:103], v[146:149], v[186:189], v[100:103]
	v_mfma_f32_16x16x32_bf16 v[96:99], v[154:157], v[186:189], v[96:99]
	v_mfma_f32_16x16x32_bf16 v[124:127], v[150:153], v[166:169], v[124:127]
	v_mfma_f32_16x16x32_bf16 v[120:123], v[158:161], v[166:169], v[120:123]
	v_mfma_f32_16x16x32_bf16 v[116:119], v[150:153], v[174:177], v[116:119]
	v_mfma_f32_16x16x32_bf16 v[112:115], v[158:161], v[174:177], v[112:115]
	v_mfma_f32_16x16x32_bf16 v[108:111], v[150:153], v[182:185], v[108:111]
	v_mfma_f32_16x16x32_bf16 v[104:107], v[158:161], v[182:185], v[104:107]
	v_mfma_f32_16x16x32_bf16 v[100:103], v[150:153], v[190:193], v[100:103]
	v_mfma_f32_16x16x32_bf16 v[96:99], v[158:161], v[190:193], v[96:99]
	s_barrier
	s_add_i32 s25, 0, 0x14000
	v_add_u32_e32 v200, s25, v141
	ds_read_b128 v[194:197], v200
	ds_read_b128 v[210:213], v200 offset:1024
	ds_read_b128 v[214:217], v200 offset:2048
	ds_read_b128 v[218:221], v200 offset:3072
	v_lshl_add_u64 v[200:201], v[134:135], 0, s[8:9]
	s_add_i32 s24, s24, s18
	v_lshl_add_u64 v[204:205], v[200:201], 0, s[70:71]
	s_mov_b32 m0, s24
	s_nop 0
	global_load_lds_dwordx4 v[204:205], off
	v_lshl_add_u64 v[204:205], v[136:137], 0, s[8:9]
	v_lshl_add_u64 v[222:223], v[204:205], 0, s[70:71]
	s_add_i32 m0, s24, 0x2000
	s_nop 0
	global_load_lds_dwordx4 v[222:223], off
	s_barrier
	s_waitcnt lgkmcnt(0)
	s_waitcnt lgkmcnt(0)
	v_mfma_f32_16x16x32_bf16 v[92:95], v[194:197], v[162:165], v[92:95]
	v_mfma_f32_16x16x32_bf16 v[88:91], v[214:217], v[162:165], v[88:91]
	v_mfma_f32_16x16x32_bf16 v[84:87], v[194:197], v[170:173], v[84:87]
	v_mfma_f32_16x16x32_bf16 v[80:83], v[214:217], v[170:173], v[80:83]
	v_mfma_f32_16x16x32_bf16 v[76:79], v[194:197], v[178:181], v[76:79]
	v_mfma_f32_16x16x32_bf16 v[72:75], v[214:217], v[178:181], v[72:75]
	v_mfma_f32_16x16x32_bf16 v[68:71], v[194:197], v[186:189], v[68:71]
	v_mfma_f32_16x16x32_bf16 v[64:67], v[214:217], v[186:189], v[64:67]
	v_mfma_f32_16x16x32_bf16 v[92:95], v[210:213], v[166:169], v[92:95]
	v_mfma_f32_16x16x32_bf16 v[88:91], v[218:221], v[166:169], v[88:91]
	v_mfma_f32_16x16x32_bf16 v[84:87], v[210:213], v[174:177], v[84:87]
	v_mfma_f32_16x16x32_bf16 v[80:83], v[218:221], v[174:177], v[80:83]
	v_mfma_f32_16x16x32_bf16 v[76:79], v[210:213], v[182:185], v[76:79]
	v_mfma_f32_16x16x32_bf16 v[72:75], v[218:221], v[182:185], v[72:75]
	v_mfma_f32_16x16x32_bf16 v[68:71], v[210:213], v[190:193], v[68:71]
	v_mfma_f32_16x16x32_bf16 v[64:67], v[218:221], v[190:193], v[64:67]
	s_mov_b32 m0, s3
	v_lshl_add_u64 v[222:223], v[142:143], 0, s[70:71]
	s_barrier
	ds_read_b128 v[162:165], v140 offset:16384
	ds_read_b128 v[166:169], v140 offset:17408
	ds_read_b128 v[170:173], v140 offset:18432
	ds_read_b128 v[174:177], v140 offset:19456
	ds_read_b128 v[178:181], v140 offset:20480
	ds_read_b128 v[182:185], v140 offset:21504
	ds_read_b128 v[186:189], v140 offset:22528
	ds_read_b128 v[190:193], v140 offset:23552
	global_load_lds_dwordx4 v[222:223], off
	v_lshl_add_u64 v[222:223], v[198:199], 0, s[70:71]
	s_mov_b32 m0, s5
	s_nop 0
	global_load_lds_dwordx4 v[222:223], off
	s_barrier
	s_waitcnt lgkmcnt(0)
	s_waitcnt lgkmcnt(0)
	v_mfma_f32_16x16x32_bf16 v[60:63], v[146:149], v[162:165], v[60:63]
	v_mfma_f32_16x16x32_bf16 v[56:59], v[154:157], v[162:165], v[56:59]
	v_mfma_f32_16x16x32_bf16 v[52:55], v[146:149], v[170:173], v[52:55]
	v_mfma_f32_16x16x32_bf16 v[48:51], v[154:157], v[170:173], v[48:51]
	v_mfma_f32_16x16x32_bf16 v[44:47], v[146:149], v[178:181], v[44:47]
	v_mfma_f32_16x16x32_bf16 v[40:43], v[154:157], v[178:181], v[40:43]
	v_mfma_f32_16x16x32_bf16 v[36:39], v[146:149], v[186:189], v[36:39]
	v_mfma_f32_16x16x32_bf16 v[32:35], v[154:157], v[186:189], v[32:35]
	v_mfma_f32_16x16x32_bf16 v[60:63], v[150:153], v[166:169], v[60:63]
	v_mfma_f32_16x16x32_bf16 v[56:59], v[158:161], v[166:169], v[56:59]
	v_mfma_f32_16x16x32_bf16 v[52:55], v[150:153], v[174:177], v[52:55]
	v_mfma_f32_16x16x32_bf16 v[48:51], v[158:161], v[174:177], v[48:51]
	v_mfma_f32_16x16x32_bf16 v[44:47], v[150:153], v[182:185], v[44:47]
	v_mfma_f32_16x16x32_bf16 v[40:43], v[158:161], v[182:185], v[40:43]
	v_mfma_f32_16x16x32_bf16 v[36:39], v[150:153], v[190:193], v[36:39]
	v_mfma_f32_16x16x32_bf16 v[32:35], v[158:161], v[190:193], v[32:35]
	s_barrier
; #define G8_STAGE(bufoff, gbase, voff) do { _Pragma("unroll") for (int _i = 0; _i < 2; ++_i) \
;     __builtin_amdgcn_global_load_lds((const unsigned*)((const char*)(gbase) + (voff)[_i]), (G8_LAS unsigned*)(lds + (bufoff) + ldsw + _i * 8192), 16, 0, 0); } while (0)
; #define G8_LDA(dst, b, h) do { _Pragma("unroll") for (int m = 0; m < 4; ++m) _Pragma("unroll") for (int k = 0; k < 2; ++k) dst[m][k] = *(const G8_LAS bf16x8*)(lds + G8_OSA(b, h) + aoff + m * 2048 + k * 1024); } while (0)
; #define G8_LDB(dst, b, h) do { _Pragma("unroll") for (int n = 0; n < 2; ++n) _Pragma("unroll") for (int k = 0; k < 2; ++k) dst[n][k] = *(const G8_LAS bf16x8*)(lds + G8_OSB(b, h) + boff + n * 2048 + k * 1024); } while (0)
; #define G8_WAIT_V(n) asm volatile("s_waitcnt vmcnt(" #n ")" ::: "memory")
; #define G8_WAIT_L(n) asm volatile("s_waitcnt lgkmcnt(" #n ")" ::: "memory")
; #define G8_BAR __builtin_amdgcn_s_barrier()
; #define G8_SCHED __builtin_amdgcn_sched_barrier(0)
; __device__ __forceinline__ void gemm256(const bf* __restrict__ A, int lda, const bf* __restrict__ Bt, int ldb, int K,
;                                         int brow, int bcol, f32x4 (&acc)[2][2][4][2]) {
;     ...
;     G8_STAGE(G8_OSB(0, 1), b2 + hstepB, voffB);
;     G8_WAIT_V(6); G8_BAR; G8_MMA(1, 1, At, B1); G8_BAR;
;     G8_LDB(B0, 1, 0); G8_SCHED; G8_LDA(At, 1, 0); G8_STAGE(G8_OSA(0, 1), a2 + hstepA, voffA);
;     G8_WAIT_L(8); G8_BAR; G8_WAIT_L(0); G8_MMA(0, 0, At, B0); G8_BAR; G8_SCHED;
;     G8_LDB(B1, 1, 1); G8_STAGE(G8_OSB(1, 0), b3, voffB);
;     G8_BAR; G8_WAIT_L(0); G8_MMA(0, 1, At, B1); G8_BAR;
;     G8_LDA(At, 1, 1); G8_STAGE(G8_OSA(1, 0), a3, voffA);
	s_add_i32 s24, s25, s18
	v_lshl_add_u64 v[146:147], v[200:201], 0, s[76:77]
	s_mov_b32 m0, s24
	s_nop 0
	global_load_lds_dwordx4 v[146:147], off
	v_lshl_add_u64 v[146:147], v[204:205], 0, s[76:77]
	s_add_i32 m0, s24, 0x2000
	s_nop 0
	global_load_lds_dwordx4 v[146:147], off
	s_waitcnt vmcnt(6)
	s_barrier
	v_mfma_f32_16x16x32_bf16 v[28:31], v[194:197], v[162:165], v[28:31]
	v_mfma_f32_16x16x32_bf16 v[24:27], v[214:217], v[162:165], v[24:27]
	v_mfma_f32_16x16x32_bf16 v[20:23], v[194:197], v[170:173], v[20:23]
	v_mfma_f32_16x16x32_bf16 v[16:19], v[214:217], v[170:173], v[16:19]
	v_mfma_f32_16x16x32_bf16 v[12:15], v[194:197], v[178:181], v[12:15]
	v_mfma_f32_16x16x32_bf16 v[8:11], v[214:217], v[178:181], v[8:11]
	v_mfma_f32_16x16x32_bf16 v[4:7], v[194:197], v[186:189], v[4:7]
	v_mfma_f32_16x16x32_bf16 v[0:3], v[214:217], v[186:189], v[0:3]
	v_mfma_f32_16x16x32_bf16 v[28:31], v[210:213], v[166:169], v[28:31]
	v_mfma_f32_16x16x32_bf16 v[24:27], v[218:221], v[166:169], v[24:27]
	v_mfma_f32_16x16x32_bf16 v[20:23], v[210:213], v[174:177], v[20:23]
	v_mfma_f32_16x16x32_bf16 v[16:19], v[218:221], v[174:177], v[16:19]
	v_mfma_f32_16x16x32_bf16 v[12:15], v[210:213], v[182:185], v[12:15]
	v_mfma_f32_16x16x32_bf16 v[8:11], v[218:221], v[182:185], v[8:11]
	v_mfma_f32_16x16x32_bf16 v[4:7], v[210:213], v[190:193], v[4:7]
	v_mfma_f32_16x16x32_bf16 v[0:3], v[218:221], v[190:193], v[0:3]
	s_add_i32 s24, 0, 0x18000
	v_add_u32_e32 v158, s24, v141
	s_barrier
	ds_read_b128 v[146:149], v158
	ds_read_b128 v[150:153], v158 offset:1024
	ds_read_b128 v[154:157], v158 offset:2048
	ds_read_b128 v[158:161], v158 offset:3072
	s_mov_b32 m0, s19
	v_lshl_add_u64 v[194:195], v[142:143], 0, s[76:77]
	ds_read_b128 v[162:165], v140 offset:32768
	ds_read_b128 v[166:169], v140 offset:33792
	ds_read_b128 v[170:173], v140 offset:34816
	ds_read_b128 v[174:177], v140 offset:35840
	ds_read_b128 v[178:181], v140 offset:36864
	ds_read_b128 v[182:185], v140 offset:37888
	ds_read_b128 v[186:189], v140 offset:38912
	ds_read_b128 v[190:193], v140 offset:39936
	global_load_lds_dwordx4 v[194:195], off
	v_lshl_add_u64 v[194:195], v[198:199], 0, s[76:77]
	s_mov_b32 m0, s20
	s_nop 0
	global_load_lds_dwordx4 v[194:195], off
	s_waitcnt lgkmcnt(8)
	s_barrier
	s_waitcnt lgkmcnt(0)
	s_waitcnt lgkmcnt(0)
	v_mfma_f32_16x16x32_bf16 v[124:127], v[146:149], v[162:165], v[124:127]
	v_mfma_f32_16x16x32_bf16 v[120:123], v[154:157], v[162:165], v[120:123]
	v_mfma_f32_16x16x32_bf16 v[116:119], v[146:149], v[170:173], v[116:119]
	v_mfma_f32_16x16x32_bf16 v[112:115], v[154:157], v[170:173], v[112:115]
	v_mfma_f32_16x16x32_bf16 v[108:111], v[146:149], v[178:181], v[108:111]
	v_mfma_f32_16x16x32_bf16 v[104:107], v[154:157], v[178:181], v[104:107]
	v_mfma_f32_16x16x32_bf16 v[100:103], v[146:149], v[186:189], v[100:103]
	v_mfma_f32_16x16x32_bf16 v[96:99], v[154:157], v[186:189], v[96:99]
	v_mfma_f32_16x16x32_bf16 v[124:127], v[150:153], v[166:169], v[124:127]
	v_mfma_f32_16x16x32_bf16 v[120:123], v[158:161], v[166:169], v[120:123]
	v_mfma_f32_16x16x32_bf16 v[116:119], v[150:153], v[174:177], v[116:119]
	v_mfma_f32_16x16x32_bf16 v[112:115], v[158:161], v[174:177], v[112:115]
	v_mfma_f32_16x16x32_bf16 v[108:111], v[150:153], v[182:185], v[108:111]
	v_mfma_f32_16x16x32_bf16 v[104:107], v[158:161], v[182:185], v[104:107]
	v_mfma_f32_16x16x32_bf16 v[100:103], v[150:153], v[190:193], v[100:103]
	v_mfma_f32_16x16x32_bf16 v[96:99], v[158:161], v[190:193], v[96:99]
	s_barrier
	s_add_i32 s25, 0, 0x1c000
	s_add_i32 s24, s24, s18
	v_add_u32_e32 v218, s25, v141
	v_lshl_add_u64 v[222:223], v[200:201], 0, s[72:73]
	s_mov_b32 m0, s24
	ds_read_b128 v[194:197], v218
	ds_read_b128 v[210:213], v218 offset:1024
	ds_read_b128 v[214:217], v218 offset:2048
	ds_read_b128 v[218:221], v218 offset:3072
	global_load_lds_dwordx4 v[222:223], off
	v_lshl_add_u64 v[222:223], v[204:205], 0, s[72:73]
	s_add_i32 m0, s24, 0x2000
	s_nop 0
	global_load_lds_dwordx4 v[222:223], off
	s_barrier
	s_waitcnt lgkmcnt(0)
	s_waitcnt lgkmcnt(0)
	v_mfma_f32_16x16x32_bf16 v[92:95], v[194:197], v[162:165], v[92:95]
	v_mfma_f32_16x16x32_bf16 v[88:91], v[214:217], v[162:165], v[88:91]
	v_mfma_f32_16x16x32_bf16 v[84:87], v[194:197], v[170:173], v[84:87]
	v_mfma_f32_16x16x32_bf16 v[80:83], v[214:217], v[170:173], v[80:83]
	v_mfma_f32_16x16x32_bf16 v[76:79], v[194:197], v[178:181], v[76:79]
	v_mfma_f32_16x16x32_bf16 v[72:75], v[214:217], v[178:181], v[72:75]
	v_mfma_f32_16x16x32_bf16 v[68:71], v[194:197], v[186:189], v[68:71]
	v_mfma_f32_16x16x32_bf16 v[64:67], v[214:217], v[186:189], v[64:67]
	v_mfma_f32_16x16x32_bf16 v[92:95], v[210:213], v[166:169], v[92:95]
	v_mfma_f32_16x16x32_bf16 v[88:91], v[218:221], v[166:169], v[88:91]
	v_mfma_f32_16x16x32_bf16 v[84:87], v[210:213], v[174:177], v[84:87]
	v_mfma_f32_16x16x32_bf16 v[80:83], v[218:221], v[174:177], v[80:83]
	v_mfma_f32_16x16x32_bf16 v[76:79], v[210:213], v[182:185], v[76:79]
	v_mfma_f32_16x16x32_bf16 v[72:75], v[218:221], v[182:185], v[72:75]
	v_mfma_f32_16x16x32_bf16 v[68:71], v[210:213], v[190:193], v[68:71]
	v_mfma_f32_16x16x32_bf16 v[64:67], v[218:221], v[190:193], v[64:67]
	s_mov_b32 m0, s21
	v_lshl_add_u64 v[142:143], v[142:143], 0, s[72:73]
	s_barrier
	ds_read_b128 v[162:165], v140 offset:49152
	ds_read_b128 v[166:169], v140 offset:50176
	ds_read_b128 v[170:173], v140 offset:51200
	ds_read_b128 v[174:177], v140 offset:52224
	ds_read_b128 v[178:181], v140 offset:53248
	ds_read_b128 v[182:185], v140 offset:54272
	ds_read_b128 v[186:189], v140 offset:55296
	ds_read_b128 v[190:193], v140 offset:56320
	global_load_lds_dwordx4 v[142:143], off
	v_lshl_add_u64 v[142:143], v[198:199], 0, s[72:73]
	s_mov_b32 m0, s22
	s_nop 0
	global_load_lds_dwordx4 v[142:143], off
	s_barrier
; #define G8_STAGE(bufoff, gbase, voff) do { _Pragma("unroll") for (int _i = 0; _i < 2; ++_i) \
;     __builtin_amdgcn_global_load_lds((const unsigned*)((const char*)(gbase) + (voff)[_i]), (G8_LAS unsigned*)(lds + (bufoff) + ldsw + _i * 8192), 16, 0, 0); } while (0)
; #define G8_LDA(dst, b, h) do { _Pragma("unroll") for (int m = 0; m < 4; ++m) _Pragma("unroll") for (int k = 0; k < 2; ++k) dst[m][k] = *(const G8_LAS bf16x8*)(lds + G8_OSA(b, h) + aoff + m * 2048 + k * 1024); } while (0)
; #define G8_LDB(dst, b, h) do { _Pragma("unroll") for (int n = 0; n < 2; ++n) _Pragma("unroll") for (int k = 0; k < 2; ++k) dst[n][k] = *(const G8_LAS bf16x8*)(lds + G8_OSB(b, h) + boff + n * 2048 + k * 1024); } while (0)
; #define G8_WAIT_V(n) asm volatile("s_waitcnt vmcnt(" #n ")" ::: "memory")
; #define G8_WAIT_L(n) asm volatile("s_waitcnt lgkmcnt(" #n ")" ::: "memory")
; #define G8_BAR __builtin_amdgcn_s_barrier()
; #define G8_SCHED __builtin_amdgcn_sched_barrier(0)
; __device__ __forceinline__ void gemm256(const bf* __restrict__ A, int lda, const bf* __restrict__ Bt, int ldb, int K,
;                                         int brow, int bcol, f32x4 (&acc)[2][2][4][2]) {
;     ...
;     G8_BAR; G8_WAIT_L(0); G8_MMA(1, 0, At, B0); G8_BAR; G8_SCHED;
;     G8_STAGE(G8_OSB(1, 1), b3 + hstepB, voffB);
;     G8_WAIT_V(6); G8_BAR; G8_MMA(1, 1, At, B1); G8_BAR;
;   }
;   { const char* a1 = cA + (size_t)(nt - 1) * kstep;
;     G8_LDB(B0, 0, 0); G8_LDA(At, 0, 0); G8_STAGE(G8_OSA(1, 1), a1 + hstepA, voffA);
;     G8_BAR; G8_WAIT_L(0); G8_MMA(0, 0, At, B0); G8_BAR;
;     G8_LDB(B1, 0, 1); G8_BAR; G8_WAIT_L(0); G8_MMA(0, 1, At, B1); G8_BAR;
	s_waitcnt lgkmcnt(0)
	s_waitcnt lgkmcnt(0)
	v_mfma_f32_16x16x32_bf16 v[60:63], v[146:149], v[162:165], v[60:63]
	v_mfma_f32_16x16x32_bf16 v[56:59], v[154:157], v[162:165], v[56:59]
	v_mfma_f32_16x16x32_bf16 v[52:55], v[146:149], v[170:173], v[52:55]
	v_mfma_f32_16x16x32_bf16 v[48:51], v[154:157], v[170:173], v[48:51]
	v_mfma_f32_16x16x32_bf16 v[44:47], v[146:149], v[178:181], v[44:47]
	v_mfma_f32_16x16x32_bf16 v[40:43], v[154:157], v[178:181], v[40:43]
	v_mfma_f32_16x16x32_bf16 v[36:39], v[146:149], v[186:189], v[36:39]
	v_mfma_f32_16x16x32_bf16 v[32:35], v[154:157], v[186:189], v[32:35]
	v_mfma_f32_16x16x32_bf16 v[60:63], v[150:153], v[166:169], v[60:63]
	v_mfma_f32_16x16x32_bf16 v[56:59], v[158:161], v[166:169], v[56:59]
	v_mfma_f32_16x16x32_bf16 v[52:55], v[150:153], v[174:177], v[52:55]
	v_mfma_f32_16x16x32_bf16 v[48:51], v[158:161], v[174:177], v[48:51]
	v_mfma_f32_16x16x32_bf16 v[44:47], v[150:153], v[182:185], v[44:47]
	v_mfma_f32_16x16x32_bf16 v[40:43], v[158:161], v[182:185], v[40:43]
	v_mfma_f32_16x16x32_bf16 v[36:39], v[150:153], v[190:193], v[36:39]
	v_mfma_f32_16x16x32_bf16 v[32:35], v[158:161], v[190:193], v[32:35]
	s_barrier
	s_add_i32 s24, s25, s18
	v_lshl_add_u64 v[142:143], v[200:201], 0, s[84:85]
	s_mov_b32 m0, s24
	s_nop 0
	global_load_lds_dwordx4 v[142:143], off
	v_lshl_add_u64 v[142:143], v[204:205], 0, s[84:85]
	s_add_i32 m0, s24, 0x2000
	s_nop 0
	global_load_lds_dwordx4 v[142:143], off
	s_waitcnt vmcnt(6)
	s_barrier
	v_mfma_f32_16x16x32_bf16 v[28:31], v[194:197], v[162:165], v[28:31]
	v_mfma_f32_16x16x32_bf16 v[24:27], v[214:217], v[162:165], v[24:27]
	v_mfma_f32_16x16x32_bf16 v[20:23], v[194:197], v[170:173], v[20:23]
	v_mfma_f32_16x16x32_bf16 v[16:19], v[214:217], v[170:173], v[16:19]
	v_mfma_f32_16x16x32_bf16 v[12:15], v[194:197], v[178:181], v[12:15]
	v_mfma_f32_16x16x32_bf16 v[8:11], v[214:217], v[178:181], v[8:11]
	v_mfma_f32_16x16x32_bf16 v[4:7], v[194:197], v[186:189], v[4:7]
	v_mfma_f32_16x16x32_bf16 v[0:3], v[214:217], v[186:189], v[0:3]
	v_mfma_f32_16x16x32_bf16 v[28:31], v[210:213], v[166:169], v[28:31]
	v_mfma_f32_16x16x32_bf16 v[24:27], v[218:221], v[166:169], v[24:27]
	v_mfma_f32_16x16x32_bf16 v[20:23], v[210:213], v[174:177], v[20:23]
	v_mfma_f32_16x16x32_bf16 v[16:19], v[218:221], v[174:177], v[16:19]
	v_mfma_f32_16x16x32_bf16 v[12:15], v[210:213], v[182:185], v[12:15]
	v_mfma_f32_16x16x32_bf16 v[8:11], v[218:221], v[182:185], v[8:11]
	v_mfma_f32_16x16x32_bf16 v[4:7], v[210:213], v[190:193], v[4:7]
	v_mfma_f32_16x16x32_bf16 v[0:3], v[218:221], v[190:193], v[0:3]
	s_add_i32 s10, s10, 2
	s_add_u32 s8, s8, 0x100
	s_addc_u32 s9, s9, 0
	s_cmp_gt_u32 s10, 27
	s_barrier
	s_cbranch_scc0 .LBB0_2437
	v_add_u32_e32 v141, 0, v141
	s_add_u32 s6, s6, 0x80f80
	v_add_u32_e32 v142, 0x10000, v141
	s_addc_u32 s7, s7, 0
	s_mov_b32 m0, s23
	ds_read_b128 v[130:133], v142
	ds_read_b128 v[134:137], v142 offset:1024
	ds_read_b128 v[146:149], v142 offset:2048
	ds_read_b128 v[150:153], v142 offset:3072
	ds_read_b128 v[154:157], v140
	ds_read_b128 v[158:161], v140 offset:1024
	ds_read_b128 v[162:165], v140 offset:2048
	ds_read_b128 v[166:169], v140 offset:3072
	ds_read_b128 v[170:173], v140 offset:4096
	ds_read_b128 v[174:177], v140 offset:5120
	ds_read_b128 v[178:181], v140 offset:6144
	ds_read_b128 v[182:185], v140 offset:7168
	v_lshl_add_u64 v[142:143], s[6:7], 0, v[144:145]
	global_load_lds_dwordx4 v[142:143], off
	v_lshl_add_u64 v[128:129], s[6:7], 0, v[128:129]
	s_mov_b32 m0, s11
	s_nop 0
	global_load_lds_dwordx4 v[128:129], off
	s_barrier
	s_waitcnt lgkmcnt(0)
	s_waitcnt lgkmcnt(0)
	v_mfma_f32_16x16x32_bf16 v[124:127], v[130:133], v[154:157], v[124:127]
	v_mfma_f32_16x16x32_bf16 v[112:115], v[146:149], v[162:165], v[112:115]
	v_mfma_f32_16x16x32_bf16 v[108:111], v[130:133], v[170:173], v[108:111]
	v_mfma_f32_16x16x32_bf16 v[96:99], v[146:149], v[178:181], v[96:99]
	v_mfma_f32_16x16x32_bf16 v[124:127], v[134:137], v[158:161], v[124:127]
	v_mfma_f32_16x16x32_bf16 v[120:123], v[146:149], v[154:157], v[120:123]
	v_mfma_f32_16x16x32_bf16 v[116:119], v[130:133], v[162:165], v[116:119]
	v_mfma_f32_16x16x32_bf16 v[112:115], v[150:153], v[166:169], v[112:115]
	v_mfma_f32_16x16x32_bf16 v[108:111], v[134:137], v[174:177], v[108:111]
	v_mfma_f32_16x16x32_bf16 v[104:107], v[146:149], v[170:173], v[104:107]
	v_mfma_f32_16x16x32_bf16 v[100:103], v[130:133], v[178:181], v[100:103]
	v_mfma_f32_16x16x32_bf16 v[96:99], v[150:153], v[182:185], v[96:99]
	v_mfma_f32_16x16x32_bf16 v[186:189], v[150:153], v[158:161], v[120:123]
	v_mfma_f32_16x16x32_bf16 v[190:193], v[134:137], v[166:169], v[116:119]
	v_mfma_f32_16x16x32_bf16 v[194:197], v[150:153], v[174:177], v[104:107]
	v_mfma_f32_16x16x32_bf16 v[210:213], v[134:137], v[182:185], v[100:103]
	v_add_u32_e32 v120, 0x14000, v141
	s_barrier
	ds_read_b128 v[100:103], v120
	ds_read_b128 v[104:107], v120 offset:1024
	ds_read_b128 v[116:119], v120 offset:2048
	ds_read_b128 v[120:123], v120 offset:3072
	s_barrier
	s_waitcnt lgkmcnt(0)
	s_waitcnt lgkmcnt(0)
	v_mfma_f32_16x16x32_bf16 v[92:95], v[100:103], v[154:157], v[92:95]
	v_mfma_f32_16x16x32_bf16 v[80:83], v[116:119], v[162:165], v[80:83]
	v_mfma_f32_16x16x32_bf16 v[76:79], v[100:103], v[170:173], v[76:79]
	v_mfma_f32_16x16x32_bf16 v[64:67], v[116:119], v[178:181], v[64:67]
	v_mfma_f32_16x16x32_bf16 v[92:95], v[104:107], v[158:161], v[92:95]
	v_mfma_f32_16x16x32_bf16 v[88:91], v[116:119], v[154:157], v[88:91]
	v_mfma_f32_16x16x32_bf16 v[84:87], v[100:103], v[162:165], v[84:87]
	v_mfma_f32_16x16x32_bf16 v[80:83], v[120:123], v[166:169], v[80:83]
	v_mfma_f32_16x16x32_bf16 v[76:79], v[104:107], v[174:177], v[76:79]
	v_mfma_f32_16x16x32_bf16 v[72:75], v[116:119], v[170:173], v[72:75]
	v_mfma_f32_16x16x32_bf16 v[68:71], v[100:103], v[178:181], v[68:71]
	v_mfma_f32_16x16x32_bf16 v[64:67], v[120:123], v[182:185], v[64:67]
	v_mfma_f32_16x16x32_bf16 v[154:157], v[120:123], v[158:161], v[88:91]
	v_mfma_f32_16x16x32_bf16 v[158:161], v[104:107], v[166:169], v[84:87]
	v_mfma_f32_16x16x32_bf16 v[162:165], v[120:123], v[174:177], v[72:75]
	v_mfma_f32_16x16x32_bf16 v[166:169], v[104:107], v[182:185], v[68:71]
	s_barrier
; #define G8_LDA(dst, b, h) do { _Pragma("unroll") for (int m = 0; m < 4; ++m) _Pragma("unroll") for (int k = 0; k < 2; ++k) dst[m][k] = *(const G8_LAS bf16x8*)(lds + G8_OSA(b, h) + aoff + m * 2048 + k * 1024); } while (0)
; #define G8_LDB(dst, b, h) do { _Pragma("unroll") for (int n = 0; n < 2; ++n) _Pragma("unroll") for (int k = 0; k < 2; ++k) dst[n][k] = *(const G8_LAS bf16x8*)(lds + G8_OSB(b, h) + boff + n * 2048 + k * 1024); } while (0)
; #define G8_WAIT_V(n) asm volatile("s_waitcnt vmcnt(" #n ")" ::: "memory")
; #define G8_WAIT_L(n) asm volatile("s_waitcnt lgkmcnt(" #n ")" ::: "memory")
; #define G8_BAR __builtin_amdgcn_s_barrier()
; __device__ __forceinline__ void gemm256(const bf* __restrict__ A, int lda, const bf* __restrict__ Bt, int ldb, int K,
;                                         int brow, int bcol, f32x4 (&acc)[2][2][4][2]) {
;     ...
;     G8_LDA(At, 0, 1); G8_WAIT_V(4); G8_BAR; G8_WAIT_L(0); G8_MMA(1, 0, At, B0); G8_MMA(1, 1, At, B1); G8_BAR; }
;   { G8_LDB(B0, 1, 0); G8_LDA(At, 1, 0); G8_WAIT_V(2); G8_BAR; G8_WAIT_L(0); G8_MMA(0, 0, At, B0); G8_BAR;
	s_nop 0
	ds_read_b128 v[68:71], v140 offset:16384
	ds_read_b128 v[72:75], v140 offset:17408
	ds_read_b128 v[84:87], v140 offset:18432
	ds_read_b128 v[88:91], v140 offset:19456
	ds_read_b128 v[170:173], v140 offset:20480
	ds_read_b128 v[174:177], v140 offset:21504
	ds_read_b128 v[178:181], v140 offset:22528
	ds_read_b128 v[182:185], v140 offset:23552
	s_waitcnt vmcnt(4)
	s_barrier
	s_waitcnt lgkmcnt(0)
	s_waitcnt lgkmcnt(0)
	v_mfma_f32_16x16x32_bf16 v[56:59], v[146:149], v[68:71], v[56:59]
	v_mfma_f32_16x16x32_bf16 v[48:51], v[146:149], v[84:87], v[48:51]
	v_mfma_f32_16x16x32_bf16 v[40:43], v[146:149], v[170:173], v[40:43]
	v_mfma_f32_16x16x32_bf16 v[32:35], v[146:149], v[178:181], v[32:35]
	v_mfma_f32_16x16x32_bf16 v[60:63], v[130:133], v[68:71], v[60:63]
	v_mfma_f32_16x16x32_bf16 v[56:59], v[150:153], v[72:75], v[56:59]
	v_mfma_f32_16x16x32_bf16 v[52:55], v[130:133], v[84:87], v[52:55]
	v_mfma_f32_16x16x32_bf16 v[48:51], v[150:153], v[88:91], v[48:51]
	v_mfma_f32_16x16x32_bf16 v[44:47], v[130:133], v[170:173], v[44:47]
	v_mfma_f32_16x16x32_bf16 v[40:43], v[150:153], v[174:177], v[40:43]
	v_mfma_f32_16x16x32_bf16 v[36:39], v[130:133], v[178:181], v[36:39]
	v_mfma_f32_16x16x32_bf16 v[32:35], v[150:153], v[182:185], v[32:35]
	v_mfma_f32_16x16x32_bf16 v[214:217], v[134:137], v[72:75], v[60:63]
	v_mfma_f32_16x16x32_bf16 v[218:221], v[134:137], v[88:91], v[52:55]
	v_mfma_f32_16x16x32_bf16 v[222:225], v[134:137], v[174:177], v[44:47]
	v_mfma_f32_16x16x32_bf16 v[128:131], v[134:137], v[182:185], v[36:39]
	v_mfma_f32_16x16x32_bf16 v[24:27], v[116:119], v[68:71], v[24:27]
	v_mfma_f32_16x16x32_bf16 v[16:19], v[116:119], v[84:87], v[16:19]
	v_mfma_f32_16x16x32_bf16 v[8:11], v[116:119], v[170:173], v[8:11]
	v_mfma_f32_16x16x32_bf16 v[0:3], v[116:119], v[178:181], v[0:3]
	v_mfma_f32_16x16x32_bf16 v[28:31], v[100:103], v[68:71], v[28:31]
	v_mfma_f32_16x16x32_bf16 v[24:27], v[120:123], v[72:75], v[24:27]
	v_mfma_f32_16x16x32_bf16 v[20:23], v[100:103], v[84:87], v[20:23]
	v_mfma_f32_16x16x32_bf16 v[16:19], v[120:123], v[88:91], v[16:19]
	v_mfma_f32_16x16x32_bf16 v[12:15], v[100:103], v[170:173], v[12:15]
	v_mfma_f32_16x16x32_bf16 v[8:11], v[120:123], v[174:177], v[8:11]
	v_mfma_f32_16x16x32_bf16 v[4:7], v[100:103], v[178:181], v[4:7]
	v_mfma_f32_16x16x32_bf16 v[0:3], v[120:123], v[182:185], v[0:3]
	v_mfma_f32_16x16x32_bf16 v[132:135], v[104:107], v[72:75], v[28:31]
	v_mfma_f32_16x16x32_bf16 v[146:149], v[104:107], v[88:91], v[20:23]
	v_mfma_f32_16x16x32_bf16 v[150:153], v[104:107], v[174:177], v[12:15]
	v_mfma_f32_16x16x32_bf16 v[170:173], v[104:107], v[182:185], v[4:7]
	v_add_u32_e32 v20, 0x18000, v141
	s_barrier
	ds_read_b128 v[4:7], v20
	ds_read_b128 v[12:15], v20 offset:1024
	ds_read_b128 v[174:177], v20 offset:2048
	ds_read_b128 v[178:181], v20 offset:3072
	ds_read_b128 v[20:23], v140 offset:32768
	ds_read_b128 v[28:31], v140 offset:33792
	ds_read_b128 v[36:39], v140 offset:34816
	ds_read_b128 v[44:47], v140 offset:35840
	ds_read_b128 v[52:55], v140 offset:36864
	ds_read_b128 v[60:63], v140 offset:37888
	ds_read_b128 v[182:185], v140 offset:38912
	ds_read_b128 v[226:229], v140 offset:39936
	s_waitcnt vmcnt(2)
	s_barrier
	s_waitcnt lgkmcnt(0)
	s_waitcnt lgkmcnt(0)
	v_mfma_f32_16x16x32_bf16 v[68:71], v[4:7], v[20:23], v[124:127]
	v_mfma_f32_16x16x32_bf16 v[120:123], v[12:15], v[28:31], v[68:71]
	v_mfma_f32_16x16x32_bf16 v[68:71], v[174:177], v[20:23], v[186:189]
	v_mfma_f32_16x16x32_bf16 v[116:119], v[178:181], v[28:31], v[68:71]
	v_mfma_f32_16x16x32_bf16 v[68:71], v[4:7], v[36:39], v[190:193]
	v_mfma_f32_16x16x32_bf16 v[104:107], v[12:15], v[44:47], v[68:71]
	v_mfma_f32_16x16x32_bf16 v[68:71], v[174:177], v[36:39], v[112:115]
	v_mfma_f32_16x16x32_bf16 v[100:103], v[178:181], v[44:47], v[68:71]
	v_mfma_f32_16x16x32_bf16 v[68:71], v[4:7], v[52:55], v[108:111]
	v_mfma_f32_16x16x32_bf16 v[88:91], v[12:15], v[60:63], v[68:71]
	v_mfma_f32_16x16x32_bf16 v[68:71], v[174:177], v[52:55], v[194:197]
	v_mfma_f32_16x16x32_bf16 v[84:87], v[178:181], v[60:63], v[68:71]
	v_mfma_f32_16x16x32_bf16 v[68:71], v[4:7], v[182:185], v[210:213]
	v_mfma_f32_16x16x32_bf16 v[72:75], v[12:15], v[226:229], v[68:71]
	v_mfma_f32_16x16x32_bf16 v[68:71], v[174:177], v[182:185], v[96:99]
	v_mfma_f32_16x16x32_bf16 v[68:71], v[178:181], v[226:229], v[68:71]
	s_nop 0
	v_add_u32_e32 v96, 0x1c000, v141
	s_barrier
; #define G8_LDA(dst, b, h) do { _Pragma("unroll") for (int m = 0; m < 4; ++m) _Pragma("unroll") for (int k = 0; k < 2; ++k) dst[m][k] = *(const G8_LAS bf16x8*)(lds + G8_OSA(b, h) + aoff + m * 2048 + k * 1024); } while (0)
; #define G8_LDB(dst, b, h) do { _Pragma("unroll") for (int n = 0; n < 2; ++n) _Pragma("unroll") for (int k = 0; k < 2; ++k) dst[n][k] = *(const G8_LAS bf16x8*)(lds + G8_OSB(b, h) + boff + n * 2048 + k * 1024); } while (0)
; #define G8_WAIT_V(n) asm volatile("s_waitcnt vmcnt(" #n ")" ::: "memory")
; #define G8_WAIT_L(n) asm volatile("s_waitcnt lgkmcnt(" #n ")" ::: "memory")
; #define G8_BAR __builtin_amdgcn_s_barrier()
; __device__ __forceinline__ void gemm256(const bf* __restrict__ A, int lda, const bf* __restrict__ Bt, int ldb, int K,
;                                         int brow, int bcol, f32x4 (&acc)[2][2][4][2]) {
;     ...
;     G8_LDB(B1, 1, 1); G8_WAIT_V(0); G8_BAR; G8_WAIT_L(0); G8_MMA(0, 1, At, B1); G8_BAR;
;     G8_LDA(At, 1, 1); G8_BAR; G8_WAIT_L(0); G8_MMA(1, 0, At, B0); G8_MMA(1, 1, At, B1); G8_BAR; }
;   if (wr == 0) G8_BAR;
	ds_read_b128 v[186:189], v96
	ds_read_b128 v[190:193], v96 offset:1024
	ds_read_b128 v[194:197], v96 offset:2048
	ds_read_b128 v[210:213], v96 offset:3072
	s_waitcnt vmcnt(0)
	s_barrier
	s_waitcnt lgkmcnt(0)
	s_waitcnt lgkmcnt(0)
	v_mfma_f32_16x16x32_bf16 v[92:95], v[186:189], v[20:23], v[92:95]
	v_mfma_f32_16x16x32_bf16 v[20:23], v[194:197], v[20:23], v[154:157]
	v_mfma_f32_16x16x32_bf16 v[112:115], v[210:213], v[28:31], v[20:23]
	v_mfma_f32_16x16x32_bf16 v[20:23], v[186:189], v[36:39], v[158:161]
	v_mfma_f32_16x16x32_bf16 v[108:111], v[190:193], v[44:47], v[20:23]
	v_mfma_f32_16x16x32_bf16 v[20:23], v[194:197], v[36:39], v[80:83]
	v_mfma_f32_16x16x32_bf16 v[96:99], v[210:213], v[44:47], v[20:23]
	v_mfma_f32_16x16x32_bf16 v[20:23], v[186:189], v[52:55], v[76:79]
	v_mfma_f32_16x16x32_bf16 v[124:127], v[190:193], v[28:31], v[92:95]
	v_mfma_f32_16x16x32_bf16 v[92:95], v[190:193], v[60:63], v[20:23]
	v_mfma_f32_16x16x32_bf16 v[20:23], v[194:197], v[52:55], v[162:165]
	v_mfma_f32_16x16x32_bf16 v[80:83], v[210:213], v[60:63], v[20:23]
	v_mfma_f32_16x16x32_bf16 v[20:23], v[186:189], v[182:185], v[166:169]
	v_mfma_f32_16x16x32_bf16 v[76:79], v[190:193], v[226:229], v[20:23]
	v_mfma_f32_16x16x32_bf16 v[20:23], v[194:197], v[182:185], v[64:67]
	v_mfma_f32_16x16x32_bf16 v[60:63], v[210:213], v[226:229], v[20:23]
	s_barrier
	ds_read_b128 v[154:157], v140 offset:49152
	ds_read_b128 v[158:161], v140 offset:50176
	ds_read_b128 v[162:165], v140 offset:51200
	ds_read_b128 v[166:169], v140 offset:52224
	ds_read_b128 v[182:185], v140 offset:53248
	ds_read_b128 v[226:229], v140 offset:54272
	ds_read_b128 v[230:233], v140 offset:55296
	ds_read_b128 v[140:143], v140 offset:56320
	s_barrier
	s_waitcnt lgkmcnt(0)
	s_waitcnt lgkmcnt(0)
	v_mfma_f32_16x16x32_bf16 v[20:23], v[4:7], v[154:157], v[214:217]
	v_mfma_f32_16x16x32_bf16 v[64:67], v[12:15], v[158:161], v[20:23]
	v_mfma_f32_16x16x32_bf16 v[20:23], v[174:177], v[154:157], v[56:59]
	v_mfma_f32_16x16x32_bf16 v[52:55], v[178:181], v[158:161], v[20:23]
	v_mfma_f32_16x16x32_bf16 v[20:23], v[4:7], v[162:165], v[218:221]
	v_mfma_f32_16x16x32_bf16 v[44:47], v[12:15], v[166:169], v[20:23]
	v_mfma_f32_16x16x32_bf16 v[20:23], v[174:177], v[162:165], v[48:51]
	v_mfma_f32_16x16x32_bf16 v[36:39], v[178:181], v[166:169], v[20:23]
	v_mfma_f32_16x16x32_bf16 v[20:23], v[4:7], v[182:185], v[222:225]
	v_mfma_f32_16x16x32_bf16 v[4:7], v[4:7], v[230:233], v[128:131]
	v_mfma_f32_16x16x32_bf16 v[28:31], v[12:15], v[226:229], v[20:23]
	v_mfma_f32_16x16x32_bf16 v[20:23], v[174:177], v[182:185], v[40:43]
	v_mfma_f32_16x16x32_bf16 v[12:15], v[12:15], v[140:143], v[4:7]
	v_mfma_f32_16x16x32_bf16 v[4:7], v[174:177], v[230:233], v[32:35]
	v_mfma_f32_16x16x32_bf16 v[20:23], v[178:181], v[226:229], v[20:23]
	v_mfma_f32_16x16x32_bf16 v[4:7], v[178:181], v[140:143], v[4:7]
	v_mfma_f32_16x16x32_bf16 v[32:35], v[186:189], v[154:157], v[132:135]
	v_mfma_f32_16x16x32_bf16 v[24:27], v[194:197], v[154:157], v[24:27]
	v_mfma_f32_16x16x32_bf16 v[16:19], v[194:197], v[162:165], v[16:19]
	v_mfma_f32_16x16x32_bf16 v[56:59], v[190:193], v[158:161], v[32:35]
	v_mfma_f32_16x16x32_bf16 v[48:51], v[210:213], v[158:161], v[24:27]
	v_mfma_f32_16x16x32_bf16 v[24:27], v[186:189], v[162:165], v[146:149]
	v_mfma_f32_16x16x32_bf16 v[32:35], v[210:213], v[166:169], v[16:19]
	v_mfma_f32_16x16x32_bf16 v[16:19], v[186:189], v[182:185], v[150:153]
	v_mfma_f32_16x16x32_bf16 v[8:11], v[194:197], v[182:185], v[8:11]
	v_mfma_f32_16x16x32_bf16 v[40:43], v[190:193], v[166:169], v[24:27]
	v_mfma_f32_16x16x32_bf16 v[24:27], v[190:193], v[226:229], v[16:19]
	v_mfma_f32_16x16x32_bf16 v[16:19], v[210:213], v[226:229], v[8:11]
	v_mfma_f32_16x16x32_bf16 v[8:11], v[186:189], v[230:233], v[170:173]
	v_mfma_f32_16x16x32_bf16 v[0:3], v[194:197], v[230:233], v[0:3]
	v_mfma_f32_16x16x32_bf16 v[8:11], v[190:193], v[140:143], v[8:11]
	v_mfma_f32_16x16x32_bf16 v[0:3], v[210:213], v[140:143], v[0:3]
	s_setprio 0
	s_cmpk_lt_u32 s17, 0x100
	s_barrier
	s_cbranch_scc0 .LBB0_2433
	s_barrier
	s_branch .LBB0_2433
